# GEMM K-loop load segments: M0-hazard s_nops removed by putting the M0 write ahead of the address add; B-fragment LDS reads issued first from dedicated base VGPRs, scalar loop bookkeeping after them
# speedup vs baseline: 1.0200x; 1.0006x over previous
; #define PG8_STAGE(bufoff, gbase, voff) do { _Pragma("unroll") for (int _i = 0; _i < 2; ++_i) \
;         __builtin_amdgcn_global_load_lds((const unsigned*)((const char*)(gbase) + (voff)[_i]), (LAS unsigned*)(lds + (bufoff) + ldsw + _i * 8192), 16, 0, 0); } while (0)
; #define PG8_LDA(dst, b, h) do { _Pragma("unroll") for (int m = 0; m < 4; ++m) _Pragma("unroll") for (int k = 0; k < 2; ++k) dst[m][k] = *(const LAS bf16x8*)(lds + PG8_SA(b, h) + aoff + m * 2048 + k * 1024); } while (0)
; #define PG8_LDB(dst, b, h) do { _Pragma("unroll") for (int n = 0; n < 2; ++n) _Pragma("unroll") for (int k = 0; k < 2; ++k) dst[n][k] = *(const LAS bf16x8*)(lds + PG8_SB(b, h) + boff + n * 2048 + k * 1024); } while (0)
; #define PG8_MMA(ai, bj, At, Bt) do { __builtin_amdgcn_s_setprio(1); _Pragma("unroll") for (int m = 0; m < 4; ++m) _Pragma("unroll") for (int n = 0; n < 2; ++n) _Pragma("unroll") for (int k = 0; k < 2; ++k) \
;         acc[ai][bj][m][n] = __builtin_amdgcn_mfma_f32_16x16x32_bf16(Bt[n][k], At[m][k], acc[ai][bj][m][n], 0, 0, 0); __builtin_amdgcn_s_setprio(0); } while (0)
; #define PG8_WAIT_V(n) asm volatile("s_waitcnt vmcnt(" #n ")" ::: "memory")
; #define PG8_WAIT_L(n) asm volatile("s_waitcnt lgkmcnt(" #n ")" ::: "memory")
; #define PG8_BAR __builtin_amdgcn_s_barrier()
; #define PG8_SCHED __builtin_amdgcn_sched_barrier(0)
; template <class Epi, class Sched>
; __device__ __forceinline__ void gemm_phase(LAS unsigned char* lds, const Gemm g, const Sched& S, const Epi& E) {
;     ...
; #pragma unroll
;     for (int a = 0; a < 2; ++a)
; #pragma unroll
;         for (int b = 0; b < 2; ++b)
; #pragma unroll
;             for (int m = 0; m < 4; ++m)
; #pragma unroll
;                 for (int n = 0; n < 2; ++n) acc[a][b][m][n] = (f32x4){0.f, 0.f, 0.f, 0.f};
;     ...
;         for (int t = 0; t < nt; t += 2) {
;             const bool last = (t == nt - 2);
;             const char* a1 = cA + (size_t)(t + 1) * kstep;
;             const char* a2 = last ? nA : cA + (size_t)(t + 2) * kstep; const char* b2 = last ? nB : cB + (size_t)(t + 2) * kstep;
;             const char* a3 = a2 + kstep; const char* b3 = b2 + kstep;
;             PG8_LDB(B0, 0, 0); PG8_LDB(B1, 0, 1); PG8_SCHED; PG8_LDA(At, 0, 0); PG8_STAGE(PG8_SA(1, 1), a1 + hstep, voffA);
;             PG8_WAIT_V(8); PG8_WAIT_L(0); PG8_BAR; PG8_MMA(0, 0, At, B0); PG8_MMA(0, 1, At, B1); PG8_BAR; PG8_SCHED;
.Lunit0_k:
	s_add_u32 s15, s0, 0x100
	s_addc_u32 s16, s1, 0
	s_add_u32 s0, s64, 0x80
	v_mov_b64_e32 v[2:3], 0
	v_mov_b64_e32 v[4:5], 0
	v_mov_b64_e32 v[6:7], 0
	v_mov_b64_e32 v[8:9], 0
	v_mov_b64_e32 v[10:11], 0
	v_mov_b64_e32 v[12:13], 0
	v_mov_b64_e32 v[14:15], 0
	v_mov_b64_e32 v[16:17], 0
	v_mov_b64_e32 v[18:19], 0
	v_mov_b64_e32 v[20:21], 0
	v_mov_b64_e32 v[22:23], 0
	v_mov_b64_e32 v[24:25], 0
	v_mov_b64_e32 v[26:27], 0
	v_mov_b64_e32 v[28:29], 0
	v_mov_b64_e32 v[30:31], 0
	v_mov_b64_e32 v[32:33], 0
	v_mov_b64_e32 v[34:35], 0
	v_mov_b64_e32 v[36:37], 0
	v_mov_b64_e32 v[38:39], 0
	v_mov_b64_e32 v[40:41], 0
	v_mov_b64_e32 v[42:43], 0
	v_mov_b64_e32 v[44:45], 0
	v_mov_b64_e32 v[46:47], 0
	v_mov_b64_e32 v[48:49], 0
	v_mov_b64_e32 v[50:51], 0
	v_mov_b64_e32 v[52:53], 0
	v_mov_b64_e32 v[54:55], 0
	v_mov_b64_e32 v[56:57], 0
	v_mov_b64_e32 v[58:59], 0
	v_mov_b64_e32 v[60:61], 0
	v_mov_b64_e32 v[62:63], 0
	v_mov_b64_e32 v[64:65], 0
	v_mov_b64_e32 v[66:67], 0
	v_mov_b64_e32 v[68:69], 0
	v_mov_b64_e32 v[70:71], 0
	v_mov_b64_e32 v[72:73], 0
	v_mov_b64_e32 v[74:75], 0
	v_mov_b64_e32 v[76:77], 0
	v_mov_b64_e32 v[78:79], 0
	v_mov_b64_e32 v[80:81], 0
	v_mov_b64_e32 v[82:83], 0
	v_mov_b64_e32 v[84:85], 0
	v_mov_b64_e32 v[86:87], 0
	v_mov_b64_e32 v[88:89], 0
	v_mov_b64_e32 v[90:91], 0
	v_mov_b64_e32 v[92:93], 0
	v_mov_b64_e32 v[94:95], 0
	v_mov_b64_e32 v[96:97], 0
	v_mov_b64_e32 v[98:99], 0
	v_mov_b64_e32 v[100:101], 0
	v_mov_b64_e32 v[102:103], 0
	v_mov_b64_e32 v[104:105], 0
	v_mov_b64_e32 v[106:107], 0
	v_mov_b64_e32 v[108:109], 0
	v_mov_b64_e32 v[110:111], 0
	v_mov_b64_e32 v[112:113], 0
	v_mov_b64_e32 v[114:115], 0
	v_mov_b64_e32 v[116:117], 0
	v_mov_b64_e32 v[118:119], 0
	v_mov_b64_e32 v[120:121], 0
	v_mov_b64_e32 v[122:123], 0
	v_mov_b64_e32 v[124:125], 0
	v_mov_b64_e32 v[126:127], 0
	v_mov_b64_e32 v[128:129], 0
	s_addc_u32 s1, s65, 0
	s_mov_b32 s28, 0
	v_add_u32_e32 v235, 0x10000, v185
	v_add_u32_e32 v238, 0x14000, v185
	v_add_u32_e32 v239, 0x18000, v185
	v_add_u32_e32 v250, 0x1c000, v185
.LBB0_178:
	ds_read_b128 v[130:133], v235
	ds_read_b128 v[134:137], v235 offset:1024
	ds_read_b128 v[138:141], v235 offset:2048
	ds_read_b128 v[142:145], v235 offset:3072
	ds_read_b128 v[146:149], v238
	ds_read_b128 v[150:153], v238 offset:1024
	ds_read_b128 v[166:169], v238 offset:2048
	ds_read_b128 v[170:173], v238 offset:3072
	ds_read_b128 v[174:177], v187
	ds_read_b128 v[178:181], v187 offset:1024
	ds_read_b128 v[188:191], v187 offset:2048
	ds_read_b128 v[206:209], v187 offset:3072
	ds_read_b128 v[210:213], v187 offset:4096
	ds_read_b128 v[214:217], v187 offset:5120
	ds_read_b128 v[218:221], v187 offset:6144
	ds_read_b128 v[222:225], v187 offset:7168
	s_add_i32 s40, s28, 2
	s_add_u32 s26, s0, 0x80
	s_addc_u32 s29, s1, 0
	s_add_i32 s41, 0, 0x10000
	s_cmp_eq_u32 s80, s28
	s_cselect_b32 s29, s61, s29
	s_cselect_b32 s28, s60, s26
	s_cselect_b32 s65, s63, s16
	s_cselect_b32 s64, s62, s15
	s_add_i32 s26, 0, 0x14000
	s_add_i32 m0, s13, 0xc000
	v_lshl_add_u64 v[182:183], s[0:1], 0, v[164:165]
	global_load_lds_dwordx4 v[182:183], off
	s_add_i32 m0, s13, 0xe000
	v_lshl_add_u64 v[182:183], s[0:1], 0, v[162:163]
	global_load_lds_dwordx4 v[182:183], off
	s_waitcnt vmcnt(8)
	s_waitcnt lgkmcnt(0)
	s_barrier
	s_setprio 1
	s_waitcnt lgkmcnt(0)
	v_mfma_f32_16x16x32_bf16 v[122:125], v[130:133], v[174:177], v[122:125]
	v_mfma_f32_16x16x32_bf16 v[114:117], v[138:141], v[174:177], v[114:117]
	v_mfma_f32_16x16x32_bf16 v[106:109], v[130:133], v[188:191], v[106:109]
	v_mfma_f32_16x16x32_bf16 v[98:101], v[138:141], v[188:191], v[98:101]
	v_mfma_f32_16x16x32_bf16 v[90:93], v[130:133], v[210:213], v[90:93]
	v_mfma_f32_16x16x32_bf16 v[82:85], v[138:141], v[210:213], v[82:85]
	v_mfma_f32_16x16x32_bf16 v[74:77], v[130:133], v[218:221], v[74:77]
	v_mfma_f32_16x16x32_bf16 v[66:69], v[138:141], v[218:221], v[66:69]
	v_mfma_f32_16x16x32_bf16 v[122:125], v[134:137], v[178:181], v[122:125]
	v_mfma_f32_16x16x32_bf16 v[114:117], v[142:145], v[178:181], v[114:117]
	v_mfma_f32_16x16x32_bf16 v[106:109], v[134:137], v[206:209], v[106:109]
	v_mfma_f32_16x16x32_bf16 v[98:101], v[142:145], v[206:209], v[98:101]
	v_mfma_f32_16x16x32_bf16 v[90:93], v[134:137], v[214:217], v[90:93]
	v_mfma_f32_16x16x32_bf16 v[82:85], v[142:145], v[214:217], v[82:85]
	v_mfma_f32_16x16x32_bf16 v[74:77], v[134:137], v[222:225], v[74:77]
	v_mfma_f32_16x16x32_bf16 v[66:69], v[142:145], v[222:225], v[66:69]
	s_setprio 0
	s_setprio 1
	v_mfma_f32_16x16x32_bf16 v[126:129], v[146:149], v[174:177], v[126:129]
	v_mfma_f32_16x16x32_bf16 v[118:121], v[166:169], v[174:177], v[118:121]
	v_mfma_f32_16x16x32_bf16 v[110:113], v[146:149], v[188:191], v[110:113]
	v_mfma_f32_16x16x32_bf16 v[102:105], v[166:169], v[188:191], v[102:105]
	v_mfma_f32_16x16x32_bf16 v[94:97], v[146:149], v[210:213], v[94:97]
	v_mfma_f32_16x16x32_bf16 v[86:89], v[166:169], v[210:213], v[86:89]
	v_mfma_f32_16x16x32_bf16 v[78:81], v[146:149], v[218:221], v[78:81]
	v_mfma_f32_16x16x32_bf16 v[70:73], v[166:169], v[218:221], v[70:73]
	v_mfma_f32_16x16x32_bf16 v[126:129], v[150:153], v[178:181], v[126:129]
	v_mfma_f32_16x16x32_bf16 v[118:121], v[170:173], v[178:181], v[118:121]
	v_mfma_f32_16x16x32_bf16 v[110:113], v[150:153], v[206:209], v[110:113]
	v_mfma_f32_16x16x32_bf16 v[102:105], v[170:173], v[206:209], v[102:105]
	v_mfma_f32_16x16x32_bf16 v[94:97], v[150:153], v[214:217], v[94:97]
	v_mfma_f32_16x16x32_bf16 v[86:89], v[170:173], v[214:217], v[86:89]
	v_mfma_f32_16x16x32_bf16 v[78:81], v[150:153], v[222:225], v[78:81]
	v_mfma_f32_16x16x32_bf16 v[70:73], v[170:173], v[222:225], v[70:73]
	s_setprio 0
	s_barrier
; #define PG8_STAGE(bufoff, gbase, voff) do { _Pragma("unroll") for (int _i = 0; _i < 2; ++_i) \
;         __builtin_amdgcn_global_load_lds((const unsigned*)((const char*)(gbase) + (voff)[_i]), (LAS unsigned*)(lds + (bufoff) + ldsw + _i * 8192), 16, 0, 0); } while (0)
; #define PG8_LDA(dst, b, h) do { _Pragma("unroll") for (int m = 0; m < 4; ++m) _Pragma("unroll") for (int k = 0; k < 2; ++k) dst[m][k] = *(const LAS bf16x8*)(lds + PG8_SA(b, h) + aoff + m * 2048 + k * 1024); } while (0)
; #define PG8_LDB(dst, b, h) do { _Pragma("unroll") for (int n = 0; n < 2; ++n) _Pragma("unroll") for (int k = 0; k < 2; ++k) dst[n][k] = *(const LAS bf16x8*)(lds + PG8_SB(b, h) + boff + n * 2048 + k * 1024); } while (0)
; #define PG8_MMA(ai, bj, At, Bt) do { __builtin_amdgcn_s_setprio(1); _Pragma("unroll") for (int m = 0; m < 4; ++m) _Pragma("unroll") for (int n = 0; n < 2; ++n) _Pragma("unroll") for (int k = 0; k < 2; ++k) \
;         acc[ai][bj][m][n] = __builtin_amdgcn_mfma_f32_16x16x32_bf16(Bt[n][k], At[m][k], acc[ai][bj][m][n], 0, 0, 0); __builtin_amdgcn_s_setprio(0); } while (0)
; #define PG8_WAIT_V(n) asm volatile("s_waitcnt vmcnt(" #n ")" ::: "memory")
; #define PG8_WAIT_L(n) asm volatile("s_waitcnt lgkmcnt(" #n ")" ::: "memory")
; #define PG8_BAR __builtin_amdgcn_s_barrier()
; #define PG8_SCHED __builtin_amdgcn_sched_barrier(0)
; template <class Epi, class Sched>
; __device__ __forceinline__ void gemm_phase(LAS unsigned char* lds, const Gemm g, const Sched& S, const Epi& E) {
;     ...
;             PG8_LDA(At, 0, 1); PG8_STAGE(PG8_SB(0, 0), b2, voffB); PG8_STAGE(PG8_SB(0, 1), b2 + hstep, voffB); PG8_STAGE(PG8_SA(0, 0), a2, voffA);
;             PG8_WAIT_V(8); PG8_WAIT_L(0); PG8_BAR; PG8_MMA(1, 0, At, B0); PG8_MMA(1, 1, At, B1); PG8_BAR; PG8_SCHED;
;             PG8_LDB(B0, 1, 0); PG8_LDB(B1, 1, 1); PG8_SCHED; PG8_LDA(At, 1, 0); PG8_STAGE(PG8_SA(0, 1), a2 + hstep, voffA);
;             PG8_WAIT_V(8); PG8_WAIT_L(0); PG8_BAR; PG8_MMA(0, 0, At, B0); PG8_MMA(0, 1, At, B1); PG8_BAR; PG8_SCHED;
	s_add_i32 s41, s41, s12
	v_lshl_add_u64 v[182:183], s[64:65], 0, v[0:1]
	s_mov_b32 m0, s41
	ds_read_b128 v[174:177], v187 offset:16384
	ds_read_b128 v[178:181], v187 offset:17408
	ds_read_b128 v[188:191], v187 offset:18432
	ds_read_b128 v[206:209], v187 offset:19456
	ds_read_b128 v[210:213], v187 offset:20480
	ds_read_b128 v[214:217], v187 offset:21504
	ds_read_b128 v[218:221], v187 offset:22528
	ds_read_b128 v[222:225], v187 offset:23552
	global_load_lds_dwordx4 v[182:183], off
	s_add_i32 m0, s41, 0x2000
	v_lshl_add_u64 v[192:193], s[64:65], 0, v[154:155]
	s_add_u32 s64, s64, s46
	s_addc_u32 s65, s65, s47
	s_add_i32 s26, s26, s12
	global_load_lds_dwordx4 v[192:193], off
	v_lshl_add_u64 v[226:227], s[64:65], 0, v[0:1]
	s_mov_b32 m0, s26
	v_lshl_add_u64 v[228:229], s[64:65], 0, v[154:155]
	global_load_lds_dwordx4 v[226:227], off
	s_add_i32 m0, s26, 0x2000
	v_lshl_add_u64 v[230:231], s[28:29], 0, v[158:159]
	global_load_lds_dwordx4 v[228:229], off
	s_mov_b32 m0, s13
	v_lshl_add_u64 v[232:233], s[28:29], 0, v[156:157]
	global_load_lds_dwordx4 v[230:231], off
	s_mov_b32 m0, s27
	s_nop 0
	global_load_lds_dwordx4 v[232:233], off
	s_waitcnt vmcnt(8)
	s_waitcnt lgkmcnt(0)
	s_barrier
	s_setprio 1
	s_waitcnt lgkmcnt(0)
	v_mfma_f32_16x16x32_bf16 v[58:61], v[130:133], v[174:177], v[58:61]
	v_mfma_f32_16x16x32_bf16 v[50:53], v[138:141], v[174:177], v[50:53]
	v_mfma_f32_16x16x32_bf16 v[42:45], v[130:133], v[188:191], v[42:45]
	v_mfma_f32_16x16x32_bf16 v[34:37], v[138:141], v[188:191], v[34:37]
	v_mfma_f32_16x16x32_bf16 v[26:29], v[130:133], v[210:213], v[26:29]
	v_mfma_f32_16x16x32_bf16 v[18:21], v[138:141], v[210:213], v[18:21]
	v_mfma_f32_16x16x32_bf16 v[10:13], v[130:133], v[218:221], v[10:13]
	v_mfma_f32_16x16x32_bf16 v[2:5], v[138:141], v[218:221], v[2:5]
	v_mfma_f32_16x16x32_bf16 v[58:61], v[134:137], v[178:181], v[58:61]
	v_mfma_f32_16x16x32_bf16 v[50:53], v[142:145], v[178:181], v[50:53]
	v_mfma_f32_16x16x32_bf16 v[42:45], v[134:137], v[206:209], v[42:45]
	v_mfma_f32_16x16x32_bf16 v[34:37], v[142:145], v[206:209], v[34:37]
	v_mfma_f32_16x16x32_bf16 v[26:29], v[134:137], v[214:217], v[26:29]
	v_mfma_f32_16x16x32_bf16 v[18:21], v[142:145], v[214:217], v[18:21]
	v_mfma_f32_16x16x32_bf16 v[10:13], v[134:137], v[222:225], v[10:13]
	v_mfma_f32_16x16x32_bf16 v[2:5], v[142:145], v[222:225], v[2:5]
	s_setprio 0
	s_setprio 1
	v_mfma_f32_16x16x32_bf16 v[62:65], v[146:149], v[174:177], v[62:65]
	v_mfma_f32_16x16x32_bf16 v[54:57], v[166:169], v[174:177], v[54:57]
	v_mfma_f32_16x16x32_bf16 v[46:49], v[146:149], v[188:191], v[46:49]
	v_mfma_f32_16x16x32_bf16 v[38:41], v[166:169], v[188:191], v[38:41]
	v_mfma_f32_16x16x32_bf16 v[30:33], v[146:149], v[210:213], v[30:33]
	v_mfma_f32_16x16x32_bf16 v[22:25], v[166:169], v[210:213], v[22:25]
	v_mfma_f32_16x16x32_bf16 v[14:17], v[146:149], v[218:221], v[14:17]
	v_mfma_f32_16x16x32_bf16 v[6:9], v[166:169], v[218:221], v[6:9]
	v_mfma_f32_16x16x32_bf16 v[62:65], v[150:153], v[178:181], v[62:65]
	v_mfma_f32_16x16x32_bf16 v[54:57], v[170:173], v[178:181], v[54:57]
	v_mfma_f32_16x16x32_bf16 v[46:49], v[150:153], v[206:209], v[46:49]
	v_mfma_f32_16x16x32_bf16 v[38:41], v[170:173], v[206:209], v[38:41]
	v_mfma_f32_16x16x32_bf16 v[30:33], v[150:153], v[214:217], v[30:33]
	v_mfma_f32_16x16x32_bf16 v[22:25], v[170:173], v[214:217], v[22:25]
	v_mfma_f32_16x16x32_bf16 v[14:17], v[150:153], v[222:225], v[14:17]
	v_mfma_f32_16x16x32_bf16 v[6:9], v[170:173], v[222:225], v[6:9]
	s_setprio 0
	s_barrier
	ds_read_b128 v[130:133], v239
	ds_read_b128 v[134:137], v239 offset:1024
	ds_read_b128 v[138:141], v239 offset:2048
	ds_read_b128 v[142:145], v239 offset:3072
	ds_read_b128 v[146:149], v250
	ds_read_b128 v[150:153], v250 offset:1024
	ds_read_b128 v[166:169], v250 offset:2048
	ds_read_b128 v[170:173], v250 offset:3072
	s_add_i32 s26, 0, 0x18000
	s_add_i32 s41, 0, 0x1c000
	s_add_u32 s28, s28, s46
	s_addc_u32 s29, s29, s47
	s_mov_b32 m0, s30
	v_lshl_add_u64 v[244:245], s[28:29], 0, v[158:159]
	ds_read_b128 v[174:177], v187 offset:32768
	ds_read_b128 v[178:181], v187 offset:33792
	ds_read_b128 v[188:191], v187 offset:34816
	ds_read_b128 v[206:209], v187 offset:35840
	ds_read_b128 v[210:213], v187 offset:36864
	ds_read_b128 v[214:217], v187 offset:37888
	ds_read_b128 v[218:221], v187 offset:38912
	ds_read_b128 v[222:225], v187 offset:39936
	global_load_lds_dwordx4 v[244:245], off
	s_mov_b32 m0, s31
	v_lshl_add_u64 v[244:245], s[28:29], 0, v[156:157]
	global_load_lds_dwordx4 v[244:245], off
	s_waitcnt vmcnt(8)
	s_waitcnt lgkmcnt(0)
	s_barrier
; #define PG8_STAGE(bufoff, gbase, voff) do { _Pragma("unroll") for (int _i = 0; _i < 2; ++_i) \
;         __builtin_amdgcn_global_load_lds((const unsigned*)((const char*)(gbase) + (voff)[_i]), (LAS unsigned*)(lds + (bufoff) + ldsw + _i * 8192), 16, 0, 0); } while (0)
; #define PG8_LDA(dst, b, h) do { _Pragma("unroll") for (int m = 0; m < 4; ++m) _Pragma("unroll") for (int k = 0; k < 2; ++k) dst[m][k] = *(const LAS bf16x8*)(lds + PG8_SA(b, h) + aoff + m * 2048 + k * 1024); } while (0)
; #define PG8_MMA(ai, bj, At, Bt) do { __builtin_amdgcn_s_setprio(1); _Pragma("unroll") for (int m = 0; m < 4; ++m) _Pragma("unroll") for (int n = 0; n < 2; ++n) _Pragma("unroll") for (int k = 0; k < 2; ++k) \
;         acc[ai][bj][m][n] = __builtin_amdgcn_mfma_f32_16x16x32_bf16(Bt[n][k], At[m][k], acc[ai][bj][m][n], 0, 0, 0); __builtin_amdgcn_s_setprio(0); } while (0)
; #define PG8_WAIT_V(n) asm volatile("s_waitcnt vmcnt(" #n ")" ::: "memory")
; #define PG8_WAIT_L(n) asm volatile("s_waitcnt lgkmcnt(" #n ")" ::: "memory")
; #define PG8_BAR __builtin_amdgcn_s_barrier()
; #define PG8_SCHED __builtin_amdgcn_sched_barrier(0)
; template <class Epi, class Sched>
; __device__ __forceinline__ void gemm_phase(LAS unsigned char* lds, const Gemm g, const Sched& S, const Epi& E) {
;     ...
;             PG8_WAIT_V(8); PG8_WAIT_L(0); PG8_BAR; PG8_MMA(0, 0, At, B0); PG8_MMA(0, 1, At, B1); PG8_BAR; PG8_SCHED;
;             PG8_LDA(At, 1, 1); PG8_STAGE(PG8_SB(1, 0), b3, voffB); PG8_STAGE(PG8_SB(1, 1), b3 + hstep, voffB); PG8_STAGE(PG8_SA(1, 0), a3, voffA);
;             PG8_WAIT_V(8); PG8_WAIT_L(0); PG8_BAR; PG8_MMA(1, 0, At, B0); PG8_MMA(1, 1, At, B1); PG8_BAR; PG8_SCHED;
;         }
	s_setprio 1
	s_waitcnt lgkmcnt(0)
	v_mfma_f32_16x16x32_bf16 v[122:125], v[130:133], v[174:177], v[122:125]
	v_mfma_f32_16x16x32_bf16 v[114:117], v[138:141], v[174:177], v[114:117]
	v_mfma_f32_16x16x32_bf16 v[106:109], v[130:133], v[188:191], v[106:109]
	v_mfma_f32_16x16x32_bf16 v[98:101], v[138:141], v[188:191], v[98:101]
	v_mfma_f32_16x16x32_bf16 v[90:93], v[130:133], v[210:213], v[90:93]
	v_mfma_f32_16x16x32_bf16 v[82:85], v[138:141], v[210:213], v[82:85]
	v_mfma_f32_16x16x32_bf16 v[74:77], v[130:133], v[218:221], v[74:77]
	v_mfma_f32_16x16x32_bf16 v[66:69], v[138:141], v[218:221], v[66:69]
	v_mfma_f32_16x16x32_bf16 v[122:125], v[134:137], v[178:181], v[122:125]
	v_mfma_f32_16x16x32_bf16 v[114:117], v[142:145], v[178:181], v[114:117]
	v_mfma_f32_16x16x32_bf16 v[106:109], v[134:137], v[206:209], v[106:109]
	v_mfma_f32_16x16x32_bf16 v[98:101], v[142:145], v[206:209], v[98:101]
	v_mfma_f32_16x16x32_bf16 v[90:93], v[134:137], v[214:217], v[90:93]
	v_mfma_f32_16x16x32_bf16 v[82:85], v[142:145], v[214:217], v[82:85]
	v_mfma_f32_16x16x32_bf16 v[74:77], v[134:137], v[222:225], v[74:77]
	v_mfma_f32_16x16x32_bf16 v[66:69], v[142:145], v[222:225], v[66:69]
	s_setprio 0
	s_setprio 1
	v_mfma_f32_16x16x32_bf16 v[126:129], v[146:149], v[174:177], v[126:129]
	v_mfma_f32_16x16x32_bf16 v[118:121], v[166:169], v[174:177], v[118:121]
	v_mfma_f32_16x16x32_bf16 v[110:113], v[146:149], v[188:191], v[110:113]
	v_mfma_f32_16x16x32_bf16 v[102:105], v[166:169], v[188:191], v[102:105]
	v_mfma_f32_16x16x32_bf16 v[94:97], v[146:149], v[210:213], v[94:97]
	v_mfma_f32_16x16x32_bf16 v[86:89], v[166:169], v[210:213], v[86:89]
	v_mfma_f32_16x16x32_bf16 v[78:81], v[146:149], v[218:221], v[78:81]
	v_mfma_f32_16x16x32_bf16 v[70:73], v[166:169], v[218:221], v[70:73]
	v_mfma_f32_16x16x32_bf16 v[126:129], v[150:153], v[178:181], v[126:129]
	v_mfma_f32_16x16x32_bf16 v[118:121], v[170:173], v[178:181], v[118:121]
	v_mfma_f32_16x16x32_bf16 v[110:113], v[150:153], v[206:209], v[110:113]
	v_mfma_f32_16x16x32_bf16 v[102:105], v[170:173], v[206:209], v[102:105]
	v_mfma_f32_16x16x32_bf16 v[94:97], v[150:153], v[214:217], v[94:97]
	v_mfma_f32_16x16x32_bf16 v[86:89], v[170:173], v[214:217], v[86:89]
	v_mfma_f32_16x16x32_bf16 v[78:81], v[150:153], v[222:225], v[78:81]
	v_mfma_f32_16x16x32_bf16 v[70:73], v[170:173], v[222:225], v[70:73]
	s_setprio 0
	s_barrier
	s_add_i32 s26, s26, s12
	v_lshl_add_u64 v[182:183], v[182:183], 0, s[18:19]
	s_mov_b32 m0, s26
	ds_read_b128 v[174:177], v187 offset:49152
	ds_read_b128 v[178:181], v187 offset:50176
	ds_read_b128 v[188:191], v187 offset:51200
	ds_read_b128 v[206:209], v187 offset:52224
	ds_read_b128 v[210:213], v187 offset:53248
	ds_read_b128 v[214:217], v187 offset:54272
	ds_read_b128 v[218:221], v187 offset:55296
	ds_read_b128 v[222:225], v187 offset:56320
	global_load_lds_dwordx4 v[182:183], off
	v_lshl_add_u64 v[182:183], v[192:193], 0, s[18:19]
	s_add_i32 m0, s26, 0x2000
	s_add_i32 s26, s41, s12
	global_load_lds_dwordx4 v[182:183], off
	s_mov_b32 m0, s26
	v_lshl_add_u64 v[182:183], v[226:227], 0, s[18:19]
	global_load_lds_dwordx4 v[182:183], off
	s_add_i32 m0, s26, 0x2000
	v_lshl_add_u64 v[182:183], v[228:229], 0, s[18:19]
	global_load_lds_dwordx4 v[182:183], off
	s_mov_b32 m0, s34
	v_lshl_add_u64 v[182:183], v[230:231], 0, s[18:19]
	global_load_lds_dwordx4 v[182:183], off
	s_mov_b32 m0, s35
	v_lshl_add_u64 v[182:183], v[232:233], 0, s[18:19]
	global_load_lds_dwordx4 v[182:183], off
	s_waitcnt vmcnt(8)
	s_waitcnt lgkmcnt(0)
	s_barrier
	s_setprio 1
	s_waitcnt lgkmcnt(0)
	v_mfma_f32_16x16x32_bf16 v[58:61], v[130:133], v[174:177], v[58:61]
	v_mfma_f32_16x16x32_bf16 v[50:53], v[138:141], v[174:177], v[50:53]
	v_mfma_f32_16x16x32_bf16 v[42:45], v[130:133], v[188:191], v[42:45]
	v_mfma_f32_16x16x32_bf16 v[34:37], v[138:141], v[188:191], v[34:37]
	v_mfma_f32_16x16x32_bf16 v[26:29], v[130:133], v[210:213], v[26:29]
	v_mfma_f32_16x16x32_bf16 v[18:21], v[138:141], v[210:213], v[18:21]
	v_mfma_f32_16x16x32_bf16 v[10:13], v[130:133], v[218:221], v[10:13]
	v_mfma_f32_16x16x32_bf16 v[2:5], v[138:141], v[218:221], v[2:5]
	v_mfma_f32_16x16x32_bf16 v[58:61], v[134:137], v[178:181], v[58:61]
	v_mfma_f32_16x16x32_bf16 v[50:53], v[142:145], v[178:181], v[50:53]
	v_mfma_f32_16x16x32_bf16 v[42:45], v[134:137], v[206:209], v[42:45]
	v_mfma_f32_16x16x32_bf16 v[34:37], v[142:145], v[206:209], v[34:37]
	v_mfma_f32_16x16x32_bf16 v[26:29], v[134:137], v[214:217], v[26:29]
	v_mfma_f32_16x16x32_bf16 v[18:21], v[142:145], v[214:217], v[18:21]
	v_mfma_f32_16x16x32_bf16 v[10:13], v[134:137], v[222:225], v[10:13]
	v_mfma_f32_16x16x32_bf16 v[2:5], v[142:145], v[222:225], v[2:5]
	s_setprio 0
	s_setprio 1
	v_mfma_f32_16x16x32_bf16 v[62:65], v[146:149], v[174:177], v[62:65]
	v_mfma_f32_16x16x32_bf16 v[54:57], v[166:169], v[174:177], v[54:57]
	v_mfma_f32_16x16x32_bf16 v[46:49], v[146:149], v[188:191], v[46:49]
	v_mfma_f32_16x16x32_bf16 v[38:41], v[166:169], v[188:191], v[38:41]
	v_mfma_f32_16x16x32_bf16 v[30:33], v[146:149], v[210:213], v[30:33]
	v_mfma_f32_16x16x32_bf16 v[22:25], v[166:169], v[210:213], v[22:25]
	v_mfma_f32_16x16x32_bf16 v[14:17], v[146:149], v[218:221], v[14:17]
	v_mfma_f32_16x16x32_bf16 v[6:9], v[166:169], v[218:221], v[6:9]
	v_mfma_f32_16x16x32_bf16 v[62:65], v[150:153], v[178:181], v[62:65]
	v_mfma_f32_16x16x32_bf16 v[54:57], v[170:173], v[178:181], v[54:57]
	v_mfma_f32_16x16x32_bf16 v[46:49], v[150:153], v[206:209], v[46:49]
	v_mfma_f32_16x16x32_bf16 v[38:41], v[170:173], v[206:209], v[38:41]
	v_mfma_f32_16x16x32_bf16 v[30:33], v[150:153], v[214:217], v[30:33]
	v_mfma_f32_16x16x32_bf16 v[22:25], v[170:173], v[214:217], v[22:25]
	v_mfma_f32_16x16x32_bf16 v[14:17], v[150:153], v[222:225], v[14:17]
	v_mfma_f32_16x16x32_bf16 v[6:9], v[170:173], v[222:225], v[6:9]
	s_setprio 0
	s_barrier
	s_add_u32 s15, s15, 0x100
	s_addc_u32 s16, s16, 0
	s_add_u32 s0, s0, 0x100
	s_addc_u32 s1, s1, 0
	s_cmp_ge_i32 s40, s67
	s_mov_b32 s28, s40
	s_cbranch_scc0 .LBB0_178

; #define PG8_STAGE(bufoff, gbase, voff) do { _Pragma("unroll") for (int _i = 0; _i < 2; ++_i) \
;         __builtin_amdgcn_global_load_lds((const unsigned*)((const char*)(gbase) + (voff)[_i]), (LAS unsigned*)(lds + (bufoff) + ldsw + _i * 8192), 16, 0, 0); } while (0)
; #define PG8_LDA(dst, b, h) do { _Pragma("unroll") for (int m = 0; m < 4; ++m) _Pragma("unroll") for (int k = 0; k < 2; ++k) dst[m][k] = *(const LAS bf16x8*)(lds + PG8_SA(b, h) + aoff + m * 2048 + k * 1024); } while (0)
; #define PG8_LDB(dst, b, h) do { _Pragma("unroll") for (int n = 0; n < 2; ++n) _Pragma("unroll") for (int k = 0; k < 2; ++k) dst[n][k] = *(const LAS bf16x8*)(lds + PG8_SB(b, h) + boff + n * 2048 + k * 1024); } while (0)
; #define PG8_MMA(ai, bj, At, Bt) do { __builtin_amdgcn_s_setprio(1); _Pragma("unroll") for (int m = 0; m < 4; ++m) _Pragma("unroll") for (int n = 0; n < 2; ++n) _Pragma("unroll") for (int k = 0; k < 2; ++k) \
;         acc[ai][bj][m][n] = __builtin_amdgcn_mfma_f32_16x16x32_bf16(Bt[n][k], At[m][k], acc[ai][bj][m][n], 0, 0, 0); __builtin_amdgcn_s_setprio(0); } while (0)
; #define PG8_WAIT_V(n) asm volatile("s_waitcnt vmcnt(" #n ")" ::: "memory")
; #define PG8_WAIT_L(n) asm volatile("s_waitcnt lgkmcnt(" #n ")" ::: "memory")
; #define PG8_BAR __builtin_amdgcn_s_barrier()
; #define PG8_SCHED __builtin_amdgcn_sched_barrier(0)
; template <class Epi, class Sched>
; __device__ __forceinline__ void gemm_phase(LAS unsigned char* lds, const Gemm g, const Sched& S, const Epi& E) {
;     ...
; #pragma unroll
;     for (int a = 0; a < 2; ++a)
; #pragma unroll
;         for (int b = 0; b < 2; ++b)
; #pragma unroll
;             for (int m = 0; m < 4; ++m)
; #pragma unroll
;                 for (int n = 0; n < 2; ++n) acc[a][b][m][n] = (f32x4){0.f, 0.f, 0.f, 0.f};
;     ...
;         for (int t = 0; t < nt; t += 2) {
;             const bool last = (t == nt - 2);
;             const char* a1 = cA + (size_t)(t + 1) * kstep;
;             const char* a2 = last ? nA : cA + (size_t)(t + 2) * kstep; const char* b2 = last ? nB : cB + (size_t)(t + 2) * kstep;
;             const char* a3 = a2 + kstep; const char* b3 = b2 + kstep;
;             PG8_LDB(B0, 0, 0); PG8_LDB(B1, 0, 1); PG8_SCHED; PG8_LDA(At, 0, 0); PG8_STAGE(PG8_SA(1, 1), a1 + hstep, voffA);
;             PG8_WAIT_V(8); PG8_WAIT_L(0); PG8_BAR; PG8_MMA(0, 0, At, B0); PG8_MMA(0, 1, At, B1); PG8_BAR; PG8_SCHED;
.Lunit1_k:
	s_add_u32 s15, s0, 0x100
	s_addc_u32 s16, s1, 0
	s_add_u32 s0, s38, 0x80
	v_mov_b64_e32 v[2:3], 0
	v_mov_b64_e32 v[4:5], 0
	v_mov_b64_e32 v[6:7], 0
	v_mov_b64_e32 v[8:9], 0
	v_mov_b64_e32 v[10:11], 0
	v_mov_b64_e32 v[12:13], 0
	v_mov_b64_e32 v[14:15], 0
	v_mov_b64_e32 v[16:17], 0
	v_mov_b64_e32 v[18:19], 0
	v_mov_b64_e32 v[20:21], 0
	v_mov_b64_e32 v[22:23], 0
	v_mov_b64_e32 v[24:25], 0
	v_mov_b64_e32 v[26:27], 0
	v_mov_b64_e32 v[28:29], 0
	v_mov_b64_e32 v[30:31], 0
	v_mov_b64_e32 v[32:33], 0
	v_mov_b64_e32 v[34:35], 0
	v_mov_b64_e32 v[36:37], 0
	v_mov_b64_e32 v[38:39], 0
	v_mov_b64_e32 v[40:41], 0
	v_mov_b64_e32 v[42:43], 0
	v_mov_b64_e32 v[44:45], 0
	v_mov_b64_e32 v[46:47], 0
	v_mov_b64_e32 v[48:49], 0
	v_mov_b64_e32 v[50:51], 0
	v_mov_b64_e32 v[52:53], 0
	v_mov_b64_e32 v[54:55], 0
	v_mov_b64_e32 v[56:57], 0
	v_mov_b64_e32 v[58:59], 0
	v_mov_b64_e32 v[60:61], 0
	v_mov_b64_e32 v[62:63], 0
	v_mov_b64_e32 v[64:65], 0
	v_mov_b64_e32 v[66:67], 0
	v_mov_b64_e32 v[68:69], 0
	v_mov_b64_e32 v[70:71], 0
	v_mov_b64_e32 v[72:73], 0
	v_mov_b64_e32 v[74:75], 0
	v_mov_b64_e32 v[76:77], 0
	v_mov_b64_e32 v[78:79], 0
	v_mov_b64_e32 v[80:81], 0
	v_mov_b64_e32 v[82:83], 0
	v_mov_b64_e32 v[84:85], 0
	v_mov_b64_e32 v[86:87], 0
	v_mov_b64_e32 v[88:89], 0
	v_mov_b64_e32 v[90:91], 0
	v_mov_b64_e32 v[92:93], 0
	v_mov_b64_e32 v[94:95], 0
	v_mov_b64_e32 v[96:97], 0
	v_mov_b64_e32 v[98:99], 0
	v_mov_b64_e32 v[100:101], 0
	v_mov_b64_e32 v[102:103], 0
	v_mov_b64_e32 v[104:105], 0
	v_mov_b64_e32 v[106:107], 0
	v_mov_b64_e32 v[108:109], 0
	v_mov_b64_e32 v[110:111], 0
	v_mov_b64_e32 v[112:113], 0
	v_mov_b64_e32 v[114:115], 0
	v_mov_b64_e32 v[116:117], 0
	v_mov_b64_e32 v[118:119], 0
	v_mov_b64_e32 v[120:121], 0
	v_mov_b64_e32 v[122:123], 0
	v_mov_b64_e32 v[124:125], 0
	v_mov_b64_e32 v[126:127], 0
	v_mov_b64_e32 v[128:129], 0
	s_addc_u32 s1, s39, 0
	s_mov_b32 s28, 0
	v_add_u32_e32 v235, 0x10000, v217
	v_add_u32_e32 v238, 0x14000, v217
	v_add_u32_e32 v239, 0x18000, v217
	v_add_u32_e32 v250, 0x1c000, v217
.LBB0_296:
	ds_read_b128 v[140:143], v235
	ds_read_b128 v[144:147], v235 offset:1024
	ds_read_b128 v[148:151], v235 offset:2048
	ds_read_b128 v[152:155], v235 offset:3072
	ds_read_b128 v[156:159], v238
	ds_read_b128 v[160:163], v238 offset:1024
	ds_read_b128 v[164:167], v238 offset:2048
	ds_read_b128 v[168:171], v238 offset:3072
	ds_read_b128 v[172:175], v219
	ds_read_b128 v[176:179], v219 offset:1024
	ds_read_b128 v[180:183], v219 offset:2048
	ds_read_b128 v[184:187], v219 offset:3072
	ds_read_b128 v[188:191], v219 offset:4096
	ds_read_b128 v[206:209], v219 offset:5120
	ds_read_b128 v[210:213], v219 offset:6144
	ds_read_b128 v[220:223], v219 offset:7168
	s_add_i32 s38, s28, 2
	s_add_u32 s26, s0, 0x80
	s_addc_u32 s29, s1, 0
	s_add_i32 s39, 0, 0x10000
	s_cmp_eq_u32 s88, s28
	s_cselect_b32 s29, s47, s29
	s_cselect_b32 s28, s46, s26
	s_cselect_b32 s93, s67, s16
	s_cselect_b32 s92, s66, s15
	s_add_i32 s26, 0, 0x14000
	s_add_i32 m0, s13, 0xc000
	v_lshl_add_u64 v[192:193], s[0:1], 0, v[138:139]
	global_load_lds_dwordx4 v[192:193], off
	s_add_i32 m0, s13, 0xe000
	v_lshl_add_u64 v[192:193], s[0:1], 0, v[136:137]
	global_load_lds_dwordx4 v[192:193], off
	s_waitcnt vmcnt(8)
	s_waitcnt lgkmcnt(0)
	s_barrier
	s_setprio 1
	s_waitcnt lgkmcnt(0)
	v_mfma_f32_16x16x32_bf16 v[126:129], v[140:143], v[172:175], v[126:129]
	v_mfma_f32_16x16x32_bf16 v[122:125], v[148:151], v[172:175], v[122:125]
	v_mfma_f32_16x16x32_bf16 v[118:121], v[140:143], v[180:183], v[118:121]
	v_mfma_f32_16x16x32_bf16 v[114:117], v[148:151], v[180:183], v[114:117]
	v_mfma_f32_16x16x32_bf16 v[106:109], v[140:143], v[188:191], v[106:109]
	v_mfma_f32_16x16x32_bf16 v[98:101], v[148:151], v[188:191], v[98:101]
	v_mfma_f32_16x16x32_bf16 v[90:93], v[140:143], v[210:213], v[90:93]
	v_mfma_f32_16x16x32_bf16 v[82:85], v[148:151], v[210:213], v[82:85]
	v_mfma_f32_16x16x32_bf16 v[126:129], v[144:147], v[176:179], v[126:129]
	v_mfma_f32_16x16x32_bf16 v[122:125], v[152:155], v[176:179], v[122:125]
	v_mfma_f32_16x16x32_bf16 v[118:121], v[144:147], v[184:187], v[118:121]
	v_mfma_f32_16x16x32_bf16 v[114:117], v[152:155], v[184:187], v[114:117]
	v_mfma_f32_16x16x32_bf16 v[106:109], v[144:147], v[206:209], v[106:109]
	v_mfma_f32_16x16x32_bf16 v[98:101], v[152:155], v[206:209], v[98:101]
	v_mfma_f32_16x16x32_bf16 v[90:93], v[144:147], v[220:223], v[90:93]
	v_mfma_f32_16x16x32_bf16 v[82:85], v[152:155], v[220:223], v[82:85]
	s_setprio 0
	s_setprio 1
	v_mfma_f32_16x16x32_bf16 v[110:113], v[156:159], v[172:175], v[110:113]
	v_mfma_f32_16x16x32_bf16 v[102:105], v[164:167], v[172:175], v[102:105]
	v_mfma_f32_16x16x32_bf16 v[94:97], v[156:159], v[180:183], v[94:97]
	v_mfma_f32_16x16x32_bf16 v[86:89], v[164:167], v[180:183], v[86:89]
	v_mfma_f32_16x16x32_bf16 v[78:81], v[156:159], v[188:191], v[78:81]
	v_mfma_f32_16x16x32_bf16 v[74:77], v[164:167], v[188:191], v[74:77]
	v_mfma_f32_16x16x32_bf16 v[70:73], v[156:159], v[210:213], v[70:73]
	v_mfma_f32_16x16x32_bf16 v[66:69], v[164:167], v[210:213], v[66:69]
	v_mfma_f32_16x16x32_bf16 v[110:113], v[160:163], v[176:179], v[110:113]
	v_mfma_f32_16x16x32_bf16 v[102:105], v[168:171], v[176:179], v[102:105]
	v_mfma_f32_16x16x32_bf16 v[94:97], v[160:163], v[184:187], v[94:97]
	v_mfma_f32_16x16x32_bf16 v[86:89], v[168:171], v[184:187], v[86:89]
	v_mfma_f32_16x16x32_bf16 v[78:81], v[160:163], v[206:209], v[78:81]
	v_mfma_f32_16x16x32_bf16 v[74:77], v[168:171], v[206:209], v[74:77]
	v_mfma_f32_16x16x32_bf16 v[70:73], v[160:163], v[220:223], v[70:73]
	v_mfma_f32_16x16x32_bf16 v[66:69], v[168:171], v[220:223], v[66:69]
	s_setprio 0
	s_barrier
; #define PG8_STAGE(bufoff, gbase, voff) do { _Pragma("unroll") for (int _i = 0; _i < 2; ++_i) \
;         __builtin_amdgcn_global_load_lds((const unsigned*)((const char*)(gbase) + (voff)[_i]), (LAS unsigned*)(lds + (bufoff) + ldsw + _i * 8192), 16, 0, 0); } while (0)
; #define PG8_LDA(dst, b, h) do { _Pragma("unroll") for (int m = 0; m < 4; ++m) _Pragma("unroll") for (int k = 0; k < 2; ++k) dst[m][k] = *(const LAS bf16x8*)(lds + PG8_SA(b, h) + aoff + m * 2048 + k * 1024); } while (0)
; #define PG8_LDB(dst, b, h) do { _Pragma("unroll") for (int n = 0; n < 2; ++n) _Pragma("unroll") for (int k = 0; k < 2; ++k) dst[n][k] = *(const LAS bf16x8*)(lds + PG8_SB(b, h) + boff + n * 2048 + k * 1024); } while (0)
; #define PG8_MMA(ai, bj, At, Bt) do { __builtin_amdgcn_s_setprio(1); _Pragma("unroll") for (int m = 0; m < 4; ++m) _Pragma("unroll") for (int n = 0; n < 2; ++n) _Pragma("unroll") for (int k = 0; k < 2; ++k) \
;         acc[ai][bj][m][n] = __builtin_amdgcn_mfma_f32_16x16x32_bf16(Bt[n][k], At[m][k], acc[ai][bj][m][n], 0, 0, 0); __builtin_amdgcn_s_setprio(0); } while (0)
; #define PG8_WAIT_V(n) asm volatile("s_waitcnt vmcnt(" #n ")" ::: "memory")
; #define PG8_WAIT_L(n) asm volatile("s_waitcnt lgkmcnt(" #n ")" ::: "memory")
; #define PG8_BAR __builtin_amdgcn_s_barrier()
; #define PG8_SCHED __builtin_amdgcn_sched_barrier(0)
; template <class Epi, class Sched>
; __device__ __forceinline__ void gemm_phase(LAS unsigned char* lds, const Gemm g, const Sched& S, const Epi& E) {
;     ...
;             PG8_LDA(At, 0, 1); PG8_STAGE(PG8_SB(0, 0), b2, voffB); PG8_STAGE(PG8_SB(0, 1), b2 + hstep, voffB); PG8_STAGE(PG8_SA(0, 0), a2, voffA);
;             PG8_WAIT_V(8); PG8_WAIT_L(0); PG8_BAR; PG8_MMA(1, 0, At, B0); PG8_MMA(1, 1, At, B1); PG8_BAR; PG8_SCHED;
;             PG8_LDB(B0, 1, 0); PG8_LDB(B1, 1, 1); PG8_SCHED; PG8_LDA(At, 1, 0); PG8_STAGE(PG8_SA(0, 1), a2 + hstep, voffA);
;             PG8_WAIT_V(8); PG8_WAIT_L(0); PG8_BAR; PG8_MMA(0, 0, At, B0); PG8_MMA(0, 1, At, B1); PG8_BAR; PG8_SCHED;
	s_add_i32 s39, s39, s12
	v_lshl_add_u64 v[192:193], s[92:93], 0, v[0:1]
	s_mov_b32 m0, s39
	ds_read_b128 v[172:175], v219 offset:16384
	ds_read_b128 v[176:179], v219 offset:17408
	ds_read_b128 v[180:183], v219 offset:18432
	ds_read_b128 v[184:187], v219 offset:19456
	ds_read_b128 v[188:191], v219 offset:20480
	ds_read_b128 v[206:209], v219 offset:21504
	ds_read_b128 v[210:213], v219 offset:22528
	ds_read_b128 v[220:223], v219 offset:23552
	global_load_lds_dwordx4 v[192:193], off
	s_add_i32 m0, s39, 0x2000
	v_lshl_add_u64 v[214:215], s[92:93], 0, v[130:131]
	s_add_u32 s92, s92, s56
	s_addc_u32 s93, s93, s57
	s_add_i32 s26, s26, s12
	global_load_lds_dwordx4 v[214:215], off
	v_lshl_add_u64 v[224:225], s[92:93], 0, v[0:1]
	s_mov_b32 m0, s26
	v_lshl_add_u64 v[226:227], s[92:93], 0, v[130:131]
	global_load_lds_dwordx4 v[224:225], off
	s_add_i32 m0, s26, 0x2000
	v_lshl_add_u64 v[228:229], s[28:29], 0, v[134:135]
	global_load_lds_dwordx4 v[226:227], off
	s_mov_b32 m0, s13
	v_lshl_add_u64 v[230:231], s[28:29], 0, v[132:133]
	global_load_lds_dwordx4 v[228:229], off
	s_mov_b32 m0, s27
	s_nop 0
	global_load_lds_dwordx4 v[230:231], off
	s_waitcnt vmcnt(8)
	s_waitcnt lgkmcnt(0)
	s_barrier
	s_setprio 1
	s_waitcnt lgkmcnt(0)
	v_mfma_f32_16x16x32_bf16 v[62:65], v[140:143], v[172:175], v[62:65]
	v_mfma_f32_16x16x32_bf16 v[58:61], v[148:151], v[172:175], v[58:61]
	v_mfma_f32_16x16x32_bf16 v[54:57], v[140:143], v[180:183], v[54:57]
	v_mfma_f32_16x16x32_bf16 v[50:53], v[148:151], v[180:183], v[50:53]
	v_mfma_f32_16x16x32_bf16 v[42:45], v[140:143], v[188:191], v[42:45]
	v_mfma_f32_16x16x32_bf16 v[34:37], v[148:151], v[188:191], v[34:37]
	v_mfma_f32_16x16x32_bf16 v[26:29], v[140:143], v[210:213], v[26:29]
	v_mfma_f32_16x16x32_bf16 v[18:21], v[148:151], v[210:213], v[18:21]
	v_mfma_f32_16x16x32_bf16 v[62:65], v[144:147], v[176:179], v[62:65]
	v_mfma_f32_16x16x32_bf16 v[58:61], v[152:155], v[176:179], v[58:61]
	v_mfma_f32_16x16x32_bf16 v[54:57], v[144:147], v[184:187], v[54:57]
	v_mfma_f32_16x16x32_bf16 v[50:53], v[152:155], v[184:187], v[50:53]
	v_mfma_f32_16x16x32_bf16 v[42:45], v[144:147], v[206:209], v[42:45]
	v_mfma_f32_16x16x32_bf16 v[34:37], v[152:155], v[206:209], v[34:37]
	v_mfma_f32_16x16x32_bf16 v[26:29], v[144:147], v[220:223], v[26:29]
	v_mfma_f32_16x16x32_bf16 v[18:21], v[152:155], v[220:223], v[18:21]
	s_setprio 0
	s_setprio 1
	v_mfma_f32_16x16x32_bf16 v[46:49], v[156:159], v[172:175], v[46:49]
	v_mfma_f32_16x16x32_bf16 v[38:41], v[164:167], v[172:175], v[38:41]
	v_mfma_f32_16x16x32_bf16 v[30:33], v[156:159], v[180:183], v[30:33]
	v_mfma_f32_16x16x32_bf16 v[22:25], v[164:167], v[180:183], v[22:25]
	v_mfma_f32_16x16x32_bf16 v[14:17], v[156:159], v[188:191], v[14:17]
	v_mfma_f32_16x16x32_bf16 v[10:13], v[164:167], v[188:191], v[10:13]
	v_mfma_f32_16x16x32_bf16 v[6:9], v[156:159], v[210:213], v[6:9]
	v_mfma_f32_16x16x32_bf16 v[2:5], v[164:167], v[210:213], v[2:5]
	v_mfma_f32_16x16x32_bf16 v[46:49], v[160:163], v[176:179], v[46:49]
	v_mfma_f32_16x16x32_bf16 v[38:41], v[168:171], v[176:179], v[38:41]
	v_mfma_f32_16x16x32_bf16 v[30:33], v[160:163], v[184:187], v[30:33]
	v_mfma_f32_16x16x32_bf16 v[22:25], v[168:171], v[184:187], v[22:25]
	v_mfma_f32_16x16x32_bf16 v[14:17], v[160:163], v[206:209], v[14:17]
	v_mfma_f32_16x16x32_bf16 v[10:13], v[168:171], v[206:209], v[10:13]
	v_mfma_f32_16x16x32_bf16 v[6:9], v[160:163], v[220:223], v[6:9]
	v_mfma_f32_16x16x32_bf16 v[2:5], v[168:171], v[220:223], v[2:5]
	s_setprio 0
	s_barrier
	ds_read_b128 v[140:143], v239
	ds_read_b128 v[144:147], v239 offset:1024
	ds_read_b128 v[148:151], v239 offset:2048
	ds_read_b128 v[152:155], v239 offset:3072
	ds_read_b128 v[156:159], v250
	ds_read_b128 v[160:163], v250 offset:1024
	ds_read_b128 v[164:167], v250 offset:2048
	ds_read_b128 v[168:171], v250 offset:3072
	s_add_i32 s26, 0, 0x18000
	s_add_i32 s39, 0, 0x1c000
	s_add_u32 s28, s28, s56
	s_addc_u32 s29, s29, s57
	s_mov_b32 m0, s34
	v_lshl_add_u64 v[232:233], s[28:29], 0, v[134:135]
	ds_read_b128 v[172:175], v219 offset:32768
	ds_read_b128 v[176:179], v219 offset:33792
	ds_read_b128 v[180:183], v219 offset:34816
	ds_read_b128 v[184:187], v219 offset:35840
	ds_read_b128 v[188:191], v219 offset:36864
	ds_read_b128 v[206:209], v219 offset:37888
	ds_read_b128 v[210:213], v219 offset:38912
	ds_read_b128 v[220:223], v219 offset:39936
	global_load_lds_dwordx4 v[232:233], off
	s_mov_b32 m0, s35
	v_lshl_add_u64 v[232:233], s[28:29], 0, v[132:133]
	global_load_lds_dwordx4 v[232:233], off
	s_waitcnt vmcnt(8)
	s_waitcnt lgkmcnt(0)
	s_barrier
; #define PG8_STAGE(bufoff, gbase, voff) do { _Pragma("unroll") for (int _i = 0; _i < 2; ++_i) \
;         __builtin_amdgcn_global_load_lds((const unsigned*)((const char*)(gbase) + (voff)[_i]), (LAS unsigned*)(lds + (bufoff) + ldsw + _i * 8192), 16, 0, 0); } while (0)
; #define PG8_LDA(dst, b, h) do { _Pragma("unroll") for (int m = 0; m < 4; ++m) _Pragma("unroll") for (int k = 0; k < 2; ++k) dst[m][k] = *(const LAS bf16x8*)(lds + PG8_SA(b, h) + aoff + m * 2048 + k * 1024); } while (0)
; #define PG8_MMA(ai, bj, At, Bt) do { __builtin_amdgcn_s_setprio(1); _Pragma("unroll") for (int m = 0; m < 4; ++m) _Pragma("unroll") for (int n = 0; n < 2; ++n) _Pragma("unroll") for (int k = 0; k < 2; ++k) \
;         acc[ai][bj][m][n] = __builtin_amdgcn_mfma_f32_16x16x32_bf16(Bt[n][k], At[m][k], acc[ai][bj][m][n], 0, 0, 0); __builtin_amdgcn_s_setprio(0); } while (0)
; #define PG8_WAIT_V(n) asm volatile("s_waitcnt vmcnt(" #n ")" ::: "memory")
; #define PG8_WAIT_L(n) asm volatile("s_waitcnt lgkmcnt(" #n ")" ::: "memory")
; #define PG8_BAR __builtin_amdgcn_s_barrier()
; #define PG8_SCHED __builtin_amdgcn_sched_barrier(0)
; template <class Epi, class Sched>
; __device__ __forceinline__ void gemm_phase(LAS unsigned char* lds, const Gemm g, const Sched& S, const Epi& E) {
;     ...
;             PG8_WAIT_V(8); PG8_WAIT_L(0); PG8_BAR; PG8_MMA(0, 0, At, B0); PG8_MMA(0, 1, At, B1); PG8_BAR; PG8_SCHED;
;             PG8_LDA(At, 1, 1); PG8_STAGE(PG8_SB(1, 0), b3, voffB); PG8_STAGE(PG8_SB(1, 1), b3 + hstep, voffB); PG8_STAGE(PG8_SA(1, 0), a3, voffA);
;             PG8_WAIT_V(8); PG8_WAIT_L(0); PG8_BAR; PG8_MMA(1, 0, At, B0); PG8_MMA(1, 1, At, B1); PG8_BAR; PG8_SCHED;
;         }
	s_setprio 1
	s_waitcnt lgkmcnt(0)
	v_mfma_f32_16x16x32_bf16 v[126:129], v[140:143], v[172:175], v[126:129]
	v_mfma_f32_16x16x32_bf16 v[122:125], v[148:151], v[172:175], v[122:125]
	v_mfma_f32_16x16x32_bf16 v[118:121], v[140:143], v[180:183], v[118:121]
	v_mfma_f32_16x16x32_bf16 v[114:117], v[148:151], v[180:183], v[114:117]
	v_mfma_f32_16x16x32_bf16 v[106:109], v[140:143], v[188:191], v[106:109]
	v_mfma_f32_16x16x32_bf16 v[98:101], v[148:151], v[188:191], v[98:101]
	v_mfma_f32_16x16x32_bf16 v[90:93], v[140:143], v[210:213], v[90:93]
	v_mfma_f32_16x16x32_bf16 v[82:85], v[148:151], v[210:213], v[82:85]
	v_mfma_f32_16x16x32_bf16 v[126:129], v[144:147], v[176:179], v[126:129]
	v_mfma_f32_16x16x32_bf16 v[122:125], v[152:155], v[176:179], v[122:125]
	v_mfma_f32_16x16x32_bf16 v[118:121], v[144:147], v[184:187], v[118:121]
	v_mfma_f32_16x16x32_bf16 v[114:117], v[152:155], v[184:187], v[114:117]
	v_mfma_f32_16x16x32_bf16 v[106:109], v[144:147], v[206:209], v[106:109]
	v_mfma_f32_16x16x32_bf16 v[98:101], v[152:155], v[206:209], v[98:101]
	v_mfma_f32_16x16x32_bf16 v[90:93], v[144:147], v[220:223], v[90:93]
	v_mfma_f32_16x16x32_bf16 v[82:85], v[152:155], v[220:223], v[82:85]
	s_setprio 0
	s_setprio 1
	v_mfma_f32_16x16x32_bf16 v[110:113], v[156:159], v[172:175], v[110:113]
	v_mfma_f32_16x16x32_bf16 v[102:105], v[164:167], v[172:175], v[102:105]
	v_mfma_f32_16x16x32_bf16 v[94:97], v[156:159], v[180:183], v[94:97]
	v_mfma_f32_16x16x32_bf16 v[86:89], v[164:167], v[180:183], v[86:89]
	v_mfma_f32_16x16x32_bf16 v[78:81], v[156:159], v[188:191], v[78:81]
	v_mfma_f32_16x16x32_bf16 v[74:77], v[164:167], v[188:191], v[74:77]
	v_mfma_f32_16x16x32_bf16 v[70:73], v[156:159], v[210:213], v[70:73]
	v_mfma_f32_16x16x32_bf16 v[66:69], v[164:167], v[210:213], v[66:69]
	v_mfma_f32_16x16x32_bf16 v[110:113], v[160:163], v[176:179], v[110:113]
	v_mfma_f32_16x16x32_bf16 v[102:105], v[168:171], v[176:179], v[102:105]
	v_mfma_f32_16x16x32_bf16 v[94:97], v[160:163], v[184:187], v[94:97]
	v_mfma_f32_16x16x32_bf16 v[86:89], v[168:171], v[184:187], v[86:89]
	v_mfma_f32_16x16x32_bf16 v[78:81], v[160:163], v[206:209], v[78:81]
	v_mfma_f32_16x16x32_bf16 v[74:77], v[168:171], v[206:209], v[74:77]
	v_mfma_f32_16x16x32_bf16 v[70:73], v[160:163], v[220:223], v[70:73]
	v_mfma_f32_16x16x32_bf16 v[66:69], v[168:171], v[220:223], v[66:69]
	s_setprio 0
	s_barrier
	s_add_i32 s26, s26, s12
	v_lshl_add_u64 v[192:193], v[192:193], 0, s[18:19]
	s_mov_b32 m0, s26
	ds_read_b128 v[172:175], v219 offset:49152
	ds_read_b128 v[176:179], v219 offset:50176
	ds_read_b128 v[180:183], v219 offset:51200
	ds_read_b128 v[184:187], v219 offset:52224
	ds_read_b128 v[188:191], v219 offset:53248
	ds_read_b128 v[206:209], v219 offset:54272
	ds_read_b128 v[210:213], v219 offset:55296
	ds_read_b128 v[220:223], v219 offset:56320
	global_load_lds_dwordx4 v[192:193], off
	v_lshl_add_u64 v[192:193], v[214:215], 0, s[18:19]
	s_add_i32 m0, s26, 0x2000
	s_add_i32 s26, s39, s12
	global_load_lds_dwordx4 v[192:193], off
	s_mov_b32 m0, s26
	v_lshl_add_u64 v[192:193], v[224:225], 0, s[18:19]
	global_load_lds_dwordx4 v[192:193], off
	s_add_i32 m0, s26, 0x2000
	v_lshl_add_u64 v[192:193], v[226:227], 0, s[18:19]
	global_load_lds_dwordx4 v[192:193], off
	s_mov_b32 m0, s84
	v_lshl_add_u64 v[192:193], v[228:229], 0, s[18:19]
	global_load_lds_dwordx4 v[192:193], off
	s_mov_b32 m0, s85
	v_lshl_add_u64 v[192:193], v[230:231], 0, s[18:19]
	global_load_lds_dwordx4 v[192:193], off
	s_waitcnt vmcnt(8)
	s_waitcnt lgkmcnt(0)
	s_barrier
	s_setprio 1
	s_waitcnt lgkmcnt(0)
	v_mfma_f32_16x16x32_bf16 v[62:65], v[140:143], v[172:175], v[62:65]
	v_mfma_f32_16x16x32_bf16 v[58:61], v[148:151], v[172:175], v[58:61]
	v_mfma_f32_16x16x32_bf16 v[54:57], v[140:143], v[180:183], v[54:57]
	v_mfma_f32_16x16x32_bf16 v[50:53], v[148:151], v[180:183], v[50:53]
	v_mfma_f32_16x16x32_bf16 v[42:45], v[140:143], v[188:191], v[42:45]
	v_mfma_f32_16x16x32_bf16 v[34:37], v[148:151], v[188:191], v[34:37]
	v_mfma_f32_16x16x32_bf16 v[26:29], v[140:143], v[210:213], v[26:29]
	v_mfma_f32_16x16x32_bf16 v[18:21], v[148:151], v[210:213], v[18:21]
	v_mfma_f32_16x16x32_bf16 v[62:65], v[144:147], v[176:179], v[62:65]
	v_mfma_f32_16x16x32_bf16 v[58:61], v[152:155], v[176:179], v[58:61]
	v_mfma_f32_16x16x32_bf16 v[54:57], v[144:147], v[184:187], v[54:57]
	v_mfma_f32_16x16x32_bf16 v[50:53], v[152:155], v[184:187], v[50:53]
	v_mfma_f32_16x16x32_bf16 v[42:45], v[144:147], v[206:209], v[42:45]
	v_mfma_f32_16x16x32_bf16 v[34:37], v[152:155], v[206:209], v[34:37]
	v_mfma_f32_16x16x32_bf16 v[26:29], v[144:147], v[220:223], v[26:29]
	v_mfma_f32_16x16x32_bf16 v[18:21], v[152:155], v[220:223], v[18:21]
	s_setprio 0
	s_setprio 1
	v_mfma_f32_16x16x32_bf16 v[46:49], v[156:159], v[172:175], v[46:49]
	v_mfma_f32_16x16x32_bf16 v[38:41], v[164:167], v[172:175], v[38:41]
	v_mfma_f32_16x16x32_bf16 v[30:33], v[156:159], v[180:183], v[30:33]
	v_mfma_f32_16x16x32_bf16 v[22:25], v[164:167], v[180:183], v[22:25]
	v_mfma_f32_16x16x32_bf16 v[14:17], v[156:159], v[188:191], v[14:17]
	v_mfma_f32_16x16x32_bf16 v[10:13], v[164:167], v[188:191], v[10:13]
	v_mfma_f32_16x16x32_bf16 v[6:9], v[156:159], v[210:213], v[6:9]
	v_mfma_f32_16x16x32_bf16 v[2:5], v[164:167], v[210:213], v[2:5]
	v_mfma_f32_16x16x32_bf16 v[46:49], v[160:163], v[176:179], v[46:49]
	v_mfma_f32_16x16x32_bf16 v[38:41], v[168:171], v[176:179], v[38:41]
	v_mfma_f32_16x16x32_bf16 v[30:33], v[160:163], v[184:187], v[30:33]
	v_mfma_f32_16x16x32_bf16 v[22:25], v[168:171], v[184:187], v[22:25]
	v_mfma_f32_16x16x32_bf16 v[14:17], v[160:163], v[206:209], v[14:17]
	v_mfma_f32_16x16x32_bf16 v[10:13], v[168:171], v[206:209], v[10:13]
	v_mfma_f32_16x16x32_bf16 v[6:9], v[160:163], v[220:223], v[6:9]
	v_mfma_f32_16x16x32_bf16 v[2:5], v[168:171], v[220:223], v[2:5]
	s_setprio 0
	s_barrier
; #define PG8_MMA(ai, bj, At, Bt) do { __builtin_amdgcn_s_setprio(1); _Pragma("unroll") for (int m = 0; m < 4; ++m) _Pragma("unroll") for (int n = 0; n < 2; ++n) _Pragma("unroll") for (int k = 0; k < 2; ++k) \
;         acc[ai][bj][m][n] = __builtin_amdgcn_mfma_f32_16x16x32_bf16(Bt[n][k], At[m][k], acc[ai][bj][m][n], 0, 0, 0); __builtin_amdgcn_s_setprio(0); } while (0)
; #define PG8_WAIT_V(n) asm volatile("s_waitcnt vmcnt(" #n ")" ::: "memory")
; #define PG8_WAIT_L(n) asm volatile("s_waitcnt lgkmcnt(" #n ")" ::: "memory")
; #define PG8_BAR __builtin_amdgcn_s_barrier()
; #define PG8_SCHED __builtin_amdgcn_sched_barrier(0)
; template <class Epi, class Sched>
; __device__ __forceinline__ void gemm_phase(LAS unsigned char* lds, const Gemm g, const Sched& S, const Epi& E) {
;     ...
;             PG8_WAIT_V(8); PG8_WAIT_L(0); PG8_BAR; PG8_MMA(1, 0, At, B0); PG8_MMA(1, 1, At, B1); PG8_BAR; PG8_SCHED;
;         }
;     __device__ __forceinline__ void operator()(const AccT& acc, const Unit& u, int wr, int wc, int fr, int fq) const {
;     ...
;                     v0 = v0 + acc[ai][bj][m][0] * c; v1 = v1 + acc[ai][bj][m][1] * c;
	s_add_u32 s15, s15, 0x100
	s_addc_u32 s16, s16, 0
	s_add_u32 s0, s0, 0x100
	s_addc_u32 s1, s1, 0
	s_cmp_ge_i32 s38, s31
	s_mov_b32 s28, s38
	s_cbranch_scc0 .LBB0_296
	v_readlane_b32 s92, v255, 40
	v_pk_mul_f32 v[208:209], v[128:129], 0.5 op_sel_hi:[1,0]
	v_pk_mul_f32 v[210:211], v[126:127], 0.5 op_sel_hi:[1,0]
	v_pk_mul_f32 v[212:213], v[124:125], 0.5 op_sel_hi:[1,0]
	v_pk_mul_f32 v[214:215], v[122:123], 0.5 op_sel_hi:[1,0]
	v_pk_mul_f32 v[192:193], v[112:113], 0.5 op_sel_hi:[1,0]
	v_pk_mul_f32 v[190:191], v[110:111], 0.5 op_sel_hi:[1,0]
	v_pk_mul_f32 v[188:189], v[104:105], 0.5 op_sel_hi:[1,0]
	v_pk_mul_f32 v[186:187], v[102:103], 0.5 op_sel_hi:[1,0]
	v_pk_mul_f32 v[184:185], v[120:121], 0.5 op_sel_hi:[1,0]
	v_pk_mul_f32 v[182:183], v[118:119], 0.5 op_sel_hi:[1,0]
	v_pk_mul_f32 v[180:181], v[116:117], 0.5 op_sel_hi:[1,0]
	v_pk_mul_f32 v[178:179], v[114:115], 0.5 op_sel_hi:[1,0]
	v_pk_mul_f32 v[176:177], v[96:97], 0.5 op_sel_hi:[1,0]
	v_pk_mul_f32 v[174:175], v[94:95], 0.5 op_sel_hi:[1,0]
	v_pk_mul_f32 v[172:173], v[88:89], 0.5 op_sel_hi:[1,0]
	v_pk_mul_f32 v[170:171], v[86:87], 0.5 op_sel_hi:[1,0]
	v_pk_mul_f32 v[168:169], v[108:109], 0.5 op_sel_hi:[1,0]
	v_pk_mul_f32 v[166:167], v[106:107], 0.5 op_sel_hi:[1,0]
	v_pk_mul_f32 v[164:165], v[100:101], 0.5 op_sel_hi:[1,0]
	v_pk_mul_f32 v[162:163], v[98:99], 0.5 op_sel_hi:[1,0]
	v_pk_mul_f32 v[160:161], v[80:81], 0.5 op_sel_hi:[1,0]
	v_pk_mul_f32 v[158:159], v[78:79], 0.5 op_sel_hi:[1,0]
	v_pk_mul_f32 v[156:157], v[76:77], 0.5 op_sel_hi:[1,0]
	v_pk_mul_f32 v[154:155], v[74:75], 0.5 op_sel_hi:[1,0]
	v_pk_mul_f32 v[150:151], v[92:93], 0.5 op_sel_hi:[1,0]
	v_pk_mul_f32 v[148:149], v[90:91], 0.5 op_sel_hi:[1,0]
	v_pk_mul_f32 v[146:147], v[84:85], 0.5 op_sel_hi:[1,0]
	v_pk_mul_f32 v[144:145], v[82:83], 0.5 op_sel_hi:[1,0]
	v_pk_mul_f32 v[142:143], v[72:73], 0.5 op_sel_hi:[1,0]
	v_pk_mul_f32 v[140:141], v[70:71], 0.5 op_sel_hi:[1,0]
	v_pk_mul_f32 v[128:129], v[68:69], 0.5 op_sel_hi:[1,0]
	v_pk_mul_f32 v[126:127], v[66:67], 0.5 op_sel_hi:[1,0]
	v_pk_mul_f32 v[124:125], v[64:65], 0.5 op_sel_hi:[1,0]
	v_pk_mul_f32 v[122:123], v[62:63], 0.5 op_sel_hi:[1,0]
	v_pk_mul_f32 v[120:121], v[60:61], 0.5 op_sel_hi:[1,0]
	v_pk_mul_f32 v[118:119], v[58:59], 0.5 op_sel_hi:[1,0]
	v_pk_mul_f32 v[116:117], v[48:49], 0.5 op_sel_hi:[1,0]
	v_pk_mul_f32 v[114:115], v[46:47], 0.5 op_sel_hi:[1,0]
	v_pk_mul_f32 v[112:113], v[40:41], 0.5 op_sel_hi:[1,0]
	v_pk_mul_f32 v[110:111], v[38:39], 0.5 op_sel_hi:[1,0]
	v_pk_mul_f32 v[108:109], v[56:57], 0.5 op_sel_hi:[1,0]
	v_pk_mul_f32 v[106:107], v[54:55], 0.5 op_sel_hi:[1,0]
	v_pk_mul_f32 v[104:105], v[52:53], 0.5 op_sel_hi:[1,0]
	v_pk_mul_f32 v[102:103], v[50:51], 0.5 op_sel_hi:[1,0]
	v_pk_mul_f32 v[100:101], v[32:33], 0.5 op_sel_hi:[1,0]
	v_pk_mul_f32 v[98:99], v[30:31], 0.5 op_sel_hi:[1,0]
	v_pk_mul_f32 v[96:97], v[24:25], 0.5 op_sel_hi:[1,0]
	v_pk_mul_f32 v[94:95], v[22:23], 0.5 op_sel_hi:[1,0]
	v_pk_mul_f32 v[92:93], v[44:45], 0.5 op_sel_hi:[1,0]
	v_pk_mul_f32 v[90:91], v[42:43], 0.5 op_sel_hi:[1,0]
	v_pk_mul_f32 v[88:89], v[36:37], 0.5 op_sel_hi:[1,0]
	v_pk_mul_f32 v[86:87], v[34:35], 0.5 op_sel_hi:[1,0]
	v_pk_mul_f32 v[84:85], v[16:17], 0.5 op_sel_hi:[1,0]
	v_pk_mul_f32 v[82:83], v[14:15], 0.5 op_sel_hi:[1,0]
	v_pk_mul_f32 v[80:81], v[12:13], 0.5 op_sel_hi:[1,0]
	v_pk_mul_f32 v[78:79], v[10:11], 0.5 op_sel_hi:[1,0]
	v_pk_mul_f32 v[76:77], v[28:29], 0.5 op_sel_hi:[1,0]
	v_pk_mul_f32 v[74:75], v[26:27], 0.5 op_sel_hi:[1,0]
	v_pk_mul_f32 v[72:73], v[20:21], 0.5 op_sel_hi:[1,0]
	v_pk_mul_f32 v[70:71], v[18:19], 0.5 op_sel_hi:[1,0]
	v_pk_mul_f32 v[68:69], v[8:9], 0.5 op_sel_hi:[1,0]
	v_pk_mul_f32 v[66:67], v[6:7], 0.5 op_sel_hi:[1,0]
	v_pk_mul_f32 v[64:65], v[4:5], 0.5 op_sel_hi:[1,0]
	v_pk_mul_f32 v[62:63], v[2:3], 0.5 op_sel_hi:[1,0]
	v_readlane_b32 s93, v255, 41

; #define PG8_STAGE(bufoff, gbase, voff) do { _Pragma("unroll") for (int _i = 0; _i < 2; ++_i) \
;         __builtin_amdgcn_global_load_lds((const unsigned*)((const char*)(gbase) + (voff)[_i]), (LAS unsigned*)(lds + (bufoff) + ldsw + _i * 8192), 16, 0, 0); } while (0)
; #define PG8_LDA(dst, b, h) do { _Pragma("unroll") for (int m = 0; m < 4; ++m) _Pragma("unroll") for (int k = 0; k < 2; ++k) dst[m][k] = *(const LAS bf16x8*)(lds + PG8_SA(b, h) + aoff + m * 2048 + k * 1024); } while (0)
; #define PG8_LDB(dst, b, h) do { _Pragma("unroll") for (int n = 0; n < 2; ++n) _Pragma("unroll") for (int k = 0; k < 2; ++k) dst[n][k] = *(const LAS bf16x8*)(lds + PG8_SB(b, h) + boff + n * 2048 + k * 1024); } while (0)
; #define PG8_MMA(ai, bj, At, Bt) do { __builtin_amdgcn_s_setprio(1); _Pragma("unroll") for (int m = 0; m < 4; ++m) _Pragma("unroll") for (int n = 0; n < 2; ++n) _Pragma("unroll") for (int k = 0; k < 2; ++k) \
;         acc[ai][bj][m][n] = __builtin_amdgcn_mfma_f32_16x16x32_bf16(Bt[n][k], At[m][k], acc[ai][bj][m][n], 0, 0, 0); __builtin_amdgcn_s_setprio(0); } while (0)
; #define PG8_WAIT_V(n) asm volatile("s_waitcnt vmcnt(" #n ")" ::: "memory")
; #define PG8_WAIT_L(n) asm volatile("s_waitcnt lgkmcnt(" #n ")" ::: "memory")
; #define PG8_BAR __builtin_amdgcn_s_barrier()
; #define PG8_SCHED __builtin_amdgcn_sched_barrier(0)
; template <class Epi, class Sched>
; __device__ __forceinline__ void gemm_phase(LAS unsigned char* lds, const Gemm g, const Sched& S, const Epi& E) {
;     ...
; #pragma unroll
;     for (int a = 0; a < 2; ++a)
; #pragma unroll
;         for (int b = 0; b < 2; ++b)
; #pragma unroll
;             for (int m = 0; m < 4; ++m)
; #pragma unroll
;                 for (int n = 0; n < 2; ++n) acc[a][b][m][n] = (f32x4){0.f, 0.f, 0.f, 0.f};
;     ...
;         for (int t = 0; t < nt; t += 2) {
;             const bool last = (t == nt - 2);
;             const char* a1 = cA + (size_t)(t + 1) * kstep;
;             const char* a2 = last ? nA : cA + (size_t)(t + 2) * kstep; const char* b2 = last ? nB : cB + (size_t)(t + 2) * kstep;
;             const char* a3 = a2 + kstep; const char* b3 = b2 + kstep;
;             PG8_LDB(B0, 0, 0); PG8_LDB(B1, 0, 1); PG8_SCHED; PG8_LDA(At, 0, 0); PG8_STAGE(PG8_SA(1, 1), a1 + hstep, voffA);
;             PG8_WAIT_V(8); PG8_WAIT_L(0); PG8_BAR; PG8_MMA(0, 0, At, B0); PG8_MMA(0, 1, At, B1); PG8_BAR; PG8_SCHED;
.Lunit2_k:
	s_add_u32 s15, s0, 0x100
	s_addc_u32 s16, s1, 0
	s_add_u32 s0, s38, 0x80
	v_mov_b64_e32 v[2:3], 0
	v_mov_b64_e32 v[4:5], 0
	v_mov_b64_e32 v[6:7], 0
	v_mov_b64_e32 v[8:9], 0
	v_mov_b64_e32 v[10:11], 0
	v_mov_b64_e32 v[12:13], 0
	v_mov_b64_e32 v[14:15], 0
	v_mov_b64_e32 v[16:17], 0
	v_mov_b64_e32 v[18:19], 0
	v_mov_b64_e32 v[20:21], 0
	v_mov_b64_e32 v[22:23], 0
	v_mov_b64_e32 v[24:25], 0
	v_mov_b64_e32 v[26:27], 0
	v_mov_b64_e32 v[28:29], 0
	v_mov_b64_e32 v[30:31], 0
	v_mov_b64_e32 v[32:33], 0
	v_mov_b64_e32 v[34:35], 0
	v_mov_b64_e32 v[36:37], 0
	v_mov_b64_e32 v[38:39], 0
	v_mov_b64_e32 v[40:41], 0
	v_mov_b64_e32 v[42:43], 0
	v_mov_b64_e32 v[44:45], 0
	v_mov_b64_e32 v[46:47], 0
	v_mov_b64_e32 v[48:49], 0
	v_mov_b64_e32 v[50:51], 0
	v_mov_b64_e32 v[52:53], 0
	v_mov_b64_e32 v[54:55], 0
	v_mov_b64_e32 v[56:57], 0
	v_mov_b64_e32 v[58:59], 0
	v_mov_b64_e32 v[60:61], 0
	v_mov_b64_e32 v[62:63], 0
	v_mov_b64_e32 v[64:65], 0
	v_mov_b64_e32 v[66:67], 0
	v_mov_b64_e32 v[68:69], 0
	v_mov_b64_e32 v[70:71], 0
	v_mov_b64_e32 v[72:73], 0
	v_mov_b64_e32 v[74:75], 0
	v_mov_b64_e32 v[76:77], 0
	v_mov_b64_e32 v[78:79], 0
	v_mov_b64_e32 v[80:81], 0
	v_mov_b64_e32 v[82:83], 0
	v_mov_b64_e32 v[84:85], 0
	v_mov_b64_e32 v[86:87], 0
	v_mov_b64_e32 v[88:89], 0
	v_mov_b64_e32 v[90:91], 0
	v_mov_b64_e32 v[92:93], 0
	v_mov_b64_e32 v[94:95], 0
	v_mov_b64_e32 v[96:97], 0
	v_mov_b64_e32 v[98:99], 0
	v_mov_b64_e32 v[100:101], 0
	v_mov_b64_e32 v[102:103], 0
	v_mov_b64_e32 v[104:105], 0
	v_mov_b64_e32 v[106:107], 0
	v_mov_b64_e32 v[108:109], 0
	v_mov_b64_e32 v[110:111], 0
	v_mov_b64_e32 v[112:113], 0
	v_mov_b64_e32 v[114:115], 0
	v_mov_b64_e32 v[116:117], 0
	v_mov_b64_e32 v[118:119], 0
	v_mov_b64_e32 v[120:121], 0
	v_mov_b64_e32 v[122:123], 0
	v_mov_b64_e32 v[124:125], 0
	v_mov_b64_e32 v[126:127], 0
	v_mov_b64_e32 v[128:129], 0
	s_addc_u32 s1, s39, 0
	s_mov_b32 s28, 0
	v_add_u32_e32 v235, 0x10000, v185
	v_add_u32_e32 v238, 0x14000, v185
	v_add_u32_e32 v239, 0x18000, v185
	v_add_u32_e32 v250, 0x1c000, v185
.LBB0_428:
	ds_read_b128 v[130:133], v235
	ds_read_b128 v[134:137], v235 offset:1024
	ds_read_b128 v[138:141], v235 offset:2048
	ds_read_b128 v[142:145], v235 offset:3072
	ds_read_b128 v[146:149], v238
	ds_read_b128 v[150:153], v238 offset:1024
	ds_read_b128 v[166:169], v238 offset:2048
	ds_read_b128 v[170:173], v238 offset:3072
	ds_read_b128 v[174:177], v189
	ds_read_b128 v[178:181], v189 offset:1024
	ds_read_b128 v[190:193], v189 offset:2048
	ds_read_b128 v[206:209], v189 offset:3072
	ds_read_b128 v[210:213], v189 offset:4096
	ds_read_b128 v[214:217], v189 offset:5120
	ds_read_b128 v[218:221], v189 offset:6144
	ds_read_b128 v[222:225], v189 offset:7168
	s_add_i32 s38, s28, 2
	s_add_u32 s26, s0, 0x80
	s_addc_u32 s29, s1, 0
	s_add_i32 s39, 0, 0x10000
	s_cmp_eq_u32 s84, s28
	s_cselect_b32 s29, s65, s29
	s_cselect_b32 s28, s64, s26
	s_cselect_b32 s47, s67, s16
	s_cselect_b32 s46, s66, s15
	s_add_i32 s26, 0, 0x14000
	s_add_i32 m0, s13, 0xc000
	v_lshl_add_u64 v[186:187], s[0:1], 0, v[164:165]
	global_load_lds_dwordx4 v[186:187], off
	s_add_i32 m0, s13, 0xe000
	v_lshl_add_u64 v[186:187], s[0:1], 0, v[162:163]
	global_load_lds_dwordx4 v[186:187], off
	s_waitcnt vmcnt(8)
	s_waitcnt lgkmcnt(0)
	s_barrier
	s_setprio 1
	s_waitcnt lgkmcnt(0)
	v_mfma_f32_16x16x32_bf16 v[126:129], v[130:133], v[174:177], v[126:129]
	v_mfma_f32_16x16x32_bf16 v[122:125], v[138:141], v[174:177], v[122:125]
	v_mfma_f32_16x16x32_bf16 v[110:113], v[130:133], v[190:193], v[110:113]
	v_mfma_f32_16x16x32_bf16 v[106:109], v[138:141], v[190:193], v[106:109]
	v_mfma_f32_16x16x32_bf16 v[94:97], v[130:133], v[210:213], v[94:97]
	v_mfma_f32_16x16x32_bf16 v[90:93], v[138:141], v[210:213], v[90:93]
	v_mfma_f32_16x16x32_bf16 v[78:81], v[130:133], v[218:221], v[78:81]
	v_mfma_f32_16x16x32_bf16 v[74:77], v[138:141], v[218:221], v[74:77]
	v_mfma_f32_16x16x32_bf16 v[126:129], v[134:137], v[178:181], v[126:129]
	v_mfma_f32_16x16x32_bf16 v[122:125], v[142:145], v[178:181], v[122:125]
	v_mfma_f32_16x16x32_bf16 v[110:113], v[134:137], v[206:209], v[110:113]
	v_mfma_f32_16x16x32_bf16 v[106:109], v[142:145], v[206:209], v[106:109]
	v_mfma_f32_16x16x32_bf16 v[94:97], v[134:137], v[214:217], v[94:97]
	v_mfma_f32_16x16x32_bf16 v[90:93], v[142:145], v[214:217], v[90:93]
	v_mfma_f32_16x16x32_bf16 v[78:81], v[134:137], v[222:225], v[78:81]
	v_mfma_f32_16x16x32_bf16 v[74:77], v[142:145], v[222:225], v[74:77]
	s_setprio 0
	s_setprio 1
	v_mfma_f32_16x16x32_bf16 v[118:121], v[146:149], v[174:177], v[118:121]
	v_mfma_f32_16x16x32_bf16 v[114:117], v[166:169], v[174:177], v[114:117]
	v_mfma_f32_16x16x32_bf16 v[102:105], v[146:149], v[190:193], v[102:105]
	v_mfma_f32_16x16x32_bf16 v[98:101], v[166:169], v[190:193], v[98:101]
	v_mfma_f32_16x16x32_bf16 v[86:89], v[146:149], v[210:213], v[86:89]
	v_mfma_f32_16x16x32_bf16 v[82:85], v[166:169], v[210:213], v[82:85]
	v_mfma_f32_16x16x32_bf16 v[70:73], v[146:149], v[218:221], v[70:73]
	v_mfma_f32_16x16x32_bf16 v[66:69], v[166:169], v[218:221], v[66:69]
	v_mfma_f32_16x16x32_bf16 v[118:121], v[150:153], v[178:181], v[118:121]
	v_mfma_f32_16x16x32_bf16 v[114:117], v[170:173], v[178:181], v[114:117]
	v_mfma_f32_16x16x32_bf16 v[102:105], v[150:153], v[206:209], v[102:105]
	v_mfma_f32_16x16x32_bf16 v[98:101], v[170:173], v[206:209], v[98:101]
	v_mfma_f32_16x16x32_bf16 v[86:89], v[150:153], v[214:217], v[86:89]
	v_mfma_f32_16x16x32_bf16 v[82:85], v[170:173], v[214:217], v[82:85]
	v_mfma_f32_16x16x32_bf16 v[70:73], v[150:153], v[222:225], v[70:73]
	v_mfma_f32_16x16x32_bf16 v[66:69], v[170:173], v[222:225], v[66:69]
	s_setprio 0
	s_barrier
; #define PG8_STAGE(bufoff, gbase, voff) do { _Pragma("unroll") for (int _i = 0; _i < 2; ++_i) \
;         __builtin_amdgcn_global_load_lds((const unsigned*)((const char*)(gbase) + (voff)[_i]), (LAS unsigned*)(lds + (bufoff) + ldsw + _i * 8192), 16, 0, 0); } while (0)
; #define PG8_LDA(dst, b, h) do { _Pragma("unroll") for (int m = 0; m < 4; ++m) _Pragma("unroll") for (int k = 0; k < 2; ++k) dst[m][k] = *(const LAS bf16x8*)(lds + PG8_SA(b, h) + aoff + m * 2048 + k * 1024); } while (0)
; #define PG8_LDB(dst, b, h) do { _Pragma("unroll") for (int n = 0; n < 2; ++n) _Pragma("unroll") for (int k = 0; k < 2; ++k) dst[n][k] = *(const LAS bf16x8*)(lds + PG8_SB(b, h) + boff + n * 2048 + k * 1024); } while (0)
; #define PG8_MMA(ai, bj, At, Bt) do { __builtin_amdgcn_s_setprio(1); _Pragma("unroll") for (int m = 0; m < 4; ++m) _Pragma("unroll") for (int n = 0; n < 2; ++n) _Pragma("unroll") for (int k = 0; k < 2; ++k) \
;         acc[ai][bj][m][n] = __builtin_amdgcn_mfma_f32_16x16x32_bf16(Bt[n][k], At[m][k], acc[ai][bj][m][n], 0, 0, 0); __builtin_amdgcn_s_setprio(0); } while (0)
; #define PG8_WAIT_V(n) asm volatile("s_waitcnt vmcnt(" #n ")" ::: "memory")
; #define PG8_WAIT_L(n) asm volatile("s_waitcnt lgkmcnt(" #n ")" ::: "memory")
; #define PG8_BAR __builtin_amdgcn_s_barrier()
; #define PG8_SCHED __builtin_amdgcn_sched_barrier(0)
; template <class Epi, class Sched>
; __device__ __forceinline__ void gemm_phase(LAS unsigned char* lds, const Gemm g, const Sched& S, const Epi& E) {
;     ...
;             PG8_LDA(At, 0, 1); PG8_STAGE(PG8_SB(0, 0), b2, voffB); PG8_STAGE(PG8_SB(0, 1), b2 + hstep, voffB); PG8_STAGE(PG8_SA(0, 0), a2, voffA);
;             PG8_WAIT_V(8); PG8_WAIT_L(0); PG8_BAR; PG8_MMA(1, 0, At, B0); PG8_MMA(1, 1, At, B1); PG8_BAR; PG8_SCHED;
;             PG8_LDB(B0, 1, 0); PG8_LDB(B1, 1, 1); PG8_SCHED; PG8_LDA(At, 1, 0); PG8_STAGE(PG8_SA(0, 1), a2 + hstep, voffA);
;             PG8_WAIT_V(8); PG8_WAIT_L(0); PG8_BAR; PG8_MMA(0, 0, At, B0); PG8_MMA(0, 1, At, B1); PG8_BAR; PG8_SCHED;
	s_add_i32 s39, s39, s12
	v_lshl_add_u64 v[186:187], s[46:47], 0, v[0:1]
	s_mov_b32 m0, s39
	ds_read_b128 v[174:177], v189 offset:16384
	ds_read_b128 v[178:181], v189 offset:17408
	ds_read_b128 v[190:193], v189 offset:18432
	ds_read_b128 v[206:209], v189 offset:19456
	ds_read_b128 v[210:213], v189 offset:20480
	ds_read_b128 v[214:217], v189 offset:21504
	ds_read_b128 v[218:221], v189 offset:22528
	ds_read_b128 v[222:225], v189 offset:23552
	global_load_lds_dwordx4 v[186:187], off
	s_add_i32 m0, s39, 0x2000
	v_lshl_add_u64 v[226:227], s[46:47], 0, v[154:155]
	s_add_u32 s46, s46, s48
	s_addc_u32 s47, s47, s49
	s_add_i32 s26, s26, s12
	global_load_lds_dwordx4 v[226:227], off
	v_lshl_add_u64 v[228:229], s[46:47], 0, v[0:1]
	s_mov_b32 m0, s26
	v_lshl_add_u64 v[230:231], s[46:47], 0, v[154:155]
	global_load_lds_dwordx4 v[228:229], off
	s_add_i32 m0, s26, 0x2000
	v_lshl_add_u64 v[232:233], s[28:29], 0, v[158:159]
	global_load_lds_dwordx4 v[230:231], off
	s_mov_b32 m0, s13
	v_lshl_add_u64 v[244:245], s[28:29], 0, v[156:157]
	global_load_lds_dwordx4 v[232:233], off
	s_mov_b32 m0, s27
	s_nop 0
	global_load_lds_dwordx4 v[244:245], off
	s_waitcnt vmcnt(8)
	s_waitcnt lgkmcnt(0)
	s_barrier
	s_setprio 1
	s_waitcnt lgkmcnt(0)
	v_mfma_f32_16x16x32_bf16 v[62:65], v[130:133], v[174:177], v[62:65]
	v_mfma_f32_16x16x32_bf16 v[58:61], v[138:141], v[174:177], v[58:61]
	v_mfma_f32_16x16x32_bf16 v[46:49], v[130:133], v[190:193], v[46:49]
	v_mfma_f32_16x16x32_bf16 v[42:45], v[138:141], v[190:193], v[42:45]
	v_mfma_f32_16x16x32_bf16 v[30:33], v[130:133], v[210:213], v[30:33]
	v_mfma_f32_16x16x32_bf16 v[26:29], v[138:141], v[210:213], v[26:29]
	v_mfma_f32_16x16x32_bf16 v[14:17], v[130:133], v[218:221], v[14:17]
	v_mfma_f32_16x16x32_bf16 v[10:13], v[138:141], v[218:221], v[10:13]
	v_mfma_f32_16x16x32_bf16 v[62:65], v[134:137], v[178:181], v[62:65]
	v_mfma_f32_16x16x32_bf16 v[58:61], v[142:145], v[178:181], v[58:61]
	v_mfma_f32_16x16x32_bf16 v[46:49], v[134:137], v[206:209], v[46:49]
	v_mfma_f32_16x16x32_bf16 v[42:45], v[142:145], v[206:209], v[42:45]
	v_mfma_f32_16x16x32_bf16 v[30:33], v[134:137], v[214:217], v[30:33]
	v_mfma_f32_16x16x32_bf16 v[26:29], v[142:145], v[214:217], v[26:29]
	v_mfma_f32_16x16x32_bf16 v[14:17], v[134:137], v[222:225], v[14:17]
	v_mfma_f32_16x16x32_bf16 v[10:13], v[142:145], v[222:225], v[10:13]
	s_setprio 0
	s_setprio 1
	v_mfma_f32_16x16x32_bf16 v[54:57], v[146:149], v[174:177], v[54:57]
	v_mfma_f32_16x16x32_bf16 v[50:53], v[166:169], v[174:177], v[50:53]
	v_mfma_f32_16x16x32_bf16 v[38:41], v[146:149], v[190:193], v[38:41]
	v_mfma_f32_16x16x32_bf16 v[34:37], v[166:169], v[190:193], v[34:37]
	v_mfma_f32_16x16x32_bf16 v[22:25], v[146:149], v[210:213], v[22:25]
	v_mfma_f32_16x16x32_bf16 v[18:21], v[166:169], v[210:213], v[18:21]
	v_mfma_f32_16x16x32_bf16 v[6:9], v[146:149], v[218:221], v[6:9]
	v_mfma_f32_16x16x32_bf16 v[2:5], v[166:169], v[218:221], v[2:5]
	v_mfma_f32_16x16x32_bf16 v[54:57], v[150:153], v[178:181], v[54:57]
	v_mfma_f32_16x16x32_bf16 v[50:53], v[170:173], v[178:181], v[50:53]
	v_mfma_f32_16x16x32_bf16 v[38:41], v[150:153], v[206:209], v[38:41]
	v_mfma_f32_16x16x32_bf16 v[34:37], v[170:173], v[206:209], v[34:37]
	v_mfma_f32_16x16x32_bf16 v[22:25], v[150:153], v[214:217], v[22:25]
	v_mfma_f32_16x16x32_bf16 v[18:21], v[170:173], v[214:217], v[18:21]
	v_mfma_f32_16x16x32_bf16 v[6:9], v[150:153], v[222:225], v[6:9]
	v_mfma_f32_16x16x32_bf16 v[2:5], v[170:173], v[222:225], v[2:5]
	s_setprio 0
	s_barrier
	ds_read_b128 v[130:133], v239
	ds_read_b128 v[134:137], v239 offset:1024
	ds_read_b128 v[138:141], v239 offset:2048
	ds_read_b128 v[142:145], v239 offset:3072
	ds_read_b128 v[146:149], v250
	ds_read_b128 v[150:153], v250 offset:1024
	ds_read_b128 v[166:169], v250 offset:2048
	ds_read_b128 v[170:173], v250 offset:3072
	s_add_i32 s26, 0, 0x18000
	s_add_i32 s39, 0, 0x1c000
	s_add_u32 s28, s28, s48
	s_addc_u32 s29, s29, s49
	s_mov_b32 m0, s30
	v_lshl_add_u64 v[246:247], s[28:29], 0, v[158:159]
	ds_read_b128 v[174:177], v189 offset:32768
	ds_read_b128 v[178:181], v189 offset:33792
	ds_read_b128 v[190:193], v189 offset:34816
	ds_read_b128 v[206:209], v189 offset:35840
	ds_read_b128 v[210:213], v189 offset:36864
	ds_read_b128 v[214:217], v189 offset:37888
	ds_read_b128 v[218:221], v189 offset:38912
	ds_read_b128 v[222:225], v189 offset:39936
	global_load_lds_dwordx4 v[246:247], off
	s_mov_b32 m0, s31
	v_lshl_add_u64 v[246:247], s[28:29], 0, v[156:157]
	global_load_lds_dwordx4 v[246:247], off
	s_waitcnt vmcnt(8)
	s_waitcnt lgkmcnt(0)
	s_barrier
; #define PG8_STAGE(bufoff, gbase, voff) do { _Pragma("unroll") for (int _i = 0; _i < 2; ++_i) \
;         __builtin_amdgcn_global_load_lds((const unsigned*)((const char*)(gbase) + (voff)[_i]), (LAS unsigned*)(lds + (bufoff) + ldsw + _i * 8192), 16, 0, 0); } while (0)
; #define PG8_LDA(dst, b, h) do { _Pragma("unroll") for (int m = 0; m < 4; ++m) _Pragma("unroll") for (int k = 0; k < 2; ++k) dst[m][k] = *(const LAS bf16x8*)(lds + PG8_SA(b, h) + aoff + m * 2048 + k * 1024); } while (0)
; #define PG8_MMA(ai, bj, At, Bt) do { __builtin_amdgcn_s_setprio(1); _Pragma("unroll") for (int m = 0; m < 4; ++m) _Pragma("unroll") for (int n = 0; n < 2; ++n) _Pragma("unroll") for (int k = 0; k < 2; ++k) \
;         acc[ai][bj][m][n] = __builtin_amdgcn_mfma_f32_16x16x32_bf16(Bt[n][k], At[m][k], acc[ai][bj][m][n], 0, 0, 0); __builtin_amdgcn_s_setprio(0); } while (0)
; #define PG8_WAIT_V(n) asm volatile("s_waitcnt vmcnt(" #n ")" ::: "memory")
; #define PG8_WAIT_L(n) asm volatile("s_waitcnt lgkmcnt(" #n ")" ::: "memory")
; #define PG8_BAR __builtin_amdgcn_s_barrier()
; #define PG8_SCHED __builtin_amdgcn_sched_barrier(0)
; template <class Epi, class Sched>
; __device__ __forceinline__ void gemm_phase(LAS unsigned char* lds, const Gemm g, const Sched& S, const Epi& E) {
;     ...
;             PG8_WAIT_V(8); PG8_WAIT_L(0); PG8_BAR; PG8_MMA(0, 0, At, B0); PG8_MMA(0, 1, At, B1); PG8_BAR; PG8_SCHED;
;             PG8_LDA(At, 1, 1); PG8_STAGE(PG8_SB(1, 0), b3, voffB); PG8_STAGE(PG8_SB(1, 1), b3 + hstep, voffB); PG8_STAGE(PG8_SA(1, 0), a3, voffA);
;             PG8_WAIT_V(8); PG8_WAIT_L(0); PG8_BAR; PG8_MMA(1, 0, At, B0); PG8_MMA(1, 1, At, B1); PG8_BAR; PG8_SCHED;
;         }
	s_setprio 1
	s_waitcnt lgkmcnt(0)
	v_mfma_f32_16x16x32_bf16 v[126:129], v[130:133], v[174:177], v[126:129]
	v_mfma_f32_16x16x32_bf16 v[122:125], v[138:141], v[174:177], v[122:125]
	v_mfma_f32_16x16x32_bf16 v[110:113], v[130:133], v[190:193], v[110:113]
	v_mfma_f32_16x16x32_bf16 v[106:109], v[138:141], v[190:193], v[106:109]
	v_mfma_f32_16x16x32_bf16 v[94:97], v[130:133], v[210:213], v[94:97]
	v_mfma_f32_16x16x32_bf16 v[90:93], v[138:141], v[210:213], v[90:93]
	v_mfma_f32_16x16x32_bf16 v[78:81], v[130:133], v[218:221], v[78:81]
	v_mfma_f32_16x16x32_bf16 v[74:77], v[138:141], v[218:221], v[74:77]
	v_mfma_f32_16x16x32_bf16 v[126:129], v[134:137], v[178:181], v[126:129]
	v_mfma_f32_16x16x32_bf16 v[122:125], v[142:145], v[178:181], v[122:125]
	v_mfma_f32_16x16x32_bf16 v[110:113], v[134:137], v[206:209], v[110:113]
	v_mfma_f32_16x16x32_bf16 v[106:109], v[142:145], v[206:209], v[106:109]
	v_mfma_f32_16x16x32_bf16 v[94:97], v[134:137], v[214:217], v[94:97]
	v_mfma_f32_16x16x32_bf16 v[90:93], v[142:145], v[214:217], v[90:93]
	v_mfma_f32_16x16x32_bf16 v[78:81], v[134:137], v[222:225], v[78:81]
	v_mfma_f32_16x16x32_bf16 v[74:77], v[142:145], v[222:225], v[74:77]
	s_setprio 0
	s_setprio 1
	v_mfma_f32_16x16x32_bf16 v[118:121], v[146:149], v[174:177], v[118:121]
	v_mfma_f32_16x16x32_bf16 v[114:117], v[166:169], v[174:177], v[114:117]
	v_mfma_f32_16x16x32_bf16 v[102:105], v[146:149], v[190:193], v[102:105]
	v_mfma_f32_16x16x32_bf16 v[98:101], v[166:169], v[190:193], v[98:101]
	v_mfma_f32_16x16x32_bf16 v[86:89], v[146:149], v[210:213], v[86:89]
	v_mfma_f32_16x16x32_bf16 v[82:85], v[166:169], v[210:213], v[82:85]
	v_mfma_f32_16x16x32_bf16 v[70:73], v[146:149], v[218:221], v[70:73]
	v_mfma_f32_16x16x32_bf16 v[66:69], v[166:169], v[218:221], v[66:69]
	v_mfma_f32_16x16x32_bf16 v[118:121], v[150:153], v[178:181], v[118:121]
	v_mfma_f32_16x16x32_bf16 v[114:117], v[170:173], v[178:181], v[114:117]
	v_mfma_f32_16x16x32_bf16 v[102:105], v[150:153], v[206:209], v[102:105]
	v_mfma_f32_16x16x32_bf16 v[98:101], v[170:173], v[206:209], v[98:101]
	v_mfma_f32_16x16x32_bf16 v[86:89], v[150:153], v[214:217], v[86:89]
	v_mfma_f32_16x16x32_bf16 v[82:85], v[170:173], v[214:217], v[82:85]
	v_mfma_f32_16x16x32_bf16 v[70:73], v[150:153], v[222:225], v[70:73]
	v_mfma_f32_16x16x32_bf16 v[66:69], v[170:173], v[222:225], v[66:69]
	s_setprio 0
	s_barrier
	s_add_i32 s26, s26, s12
	v_lshl_add_u64 v[186:187], v[186:187], 0, s[18:19]
	s_mov_b32 m0, s26
	ds_read_b128 v[174:177], v189 offset:49152
	ds_read_b128 v[178:181], v189 offset:50176
	ds_read_b128 v[190:193], v189 offset:51200
	ds_read_b128 v[206:209], v189 offset:52224
	ds_read_b128 v[210:213], v189 offset:53248
	ds_read_b128 v[214:217], v189 offset:54272
	ds_read_b128 v[218:221], v189 offset:55296
	ds_read_b128 v[222:225], v189 offset:56320
	global_load_lds_dwordx4 v[186:187], off
	v_lshl_add_u64 v[186:187], v[226:227], 0, s[18:19]
	s_add_i32 m0, s26, 0x2000
	s_add_i32 s26, s39, s12
	global_load_lds_dwordx4 v[186:187], off
	s_mov_b32 m0, s26
	v_lshl_add_u64 v[186:187], v[228:229], 0, s[18:19]
	global_load_lds_dwordx4 v[186:187], off
	s_add_i32 m0, s26, 0x2000
	v_lshl_add_u64 v[186:187], v[230:231], 0, s[18:19]
	global_load_lds_dwordx4 v[186:187], off
	s_mov_b32 m0, s34
	v_lshl_add_u64 v[186:187], v[232:233], 0, s[18:19]
	global_load_lds_dwordx4 v[186:187], off
	s_mov_b32 m0, s35
	v_lshl_add_u64 v[186:187], v[244:245], 0, s[18:19]
	global_load_lds_dwordx4 v[186:187], off
	s_waitcnt vmcnt(8)
	s_waitcnt lgkmcnt(0)
	s_barrier
	s_setprio 1
	s_waitcnt lgkmcnt(0)
	v_mfma_f32_16x16x32_bf16 v[62:65], v[130:133], v[174:177], v[62:65]
	v_mfma_f32_16x16x32_bf16 v[58:61], v[138:141], v[174:177], v[58:61]
	v_mfma_f32_16x16x32_bf16 v[46:49], v[130:133], v[190:193], v[46:49]
	v_mfma_f32_16x16x32_bf16 v[42:45], v[138:141], v[190:193], v[42:45]
	v_mfma_f32_16x16x32_bf16 v[30:33], v[130:133], v[210:213], v[30:33]
	v_mfma_f32_16x16x32_bf16 v[26:29], v[138:141], v[210:213], v[26:29]
	v_mfma_f32_16x16x32_bf16 v[14:17], v[130:133], v[218:221], v[14:17]
	v_mfma_f32_16x16x32_bf16 v[10:13], v[138:141], v[218:221], v[10:13]
	v_mfma_f32_16x16x32_bf16 v[62:65], v[134:137], v[178:181], v[62:65]
	v_mfma_f32_16x16x32_bf16 v[58:61], v[142:145], v[178:181], v[58:61]
	v_mfma_f32_16x16x32_bf16 v[46:49], v[134:137], v[206:209], v[46:49]
	v_mfma_f32_16x16x32_bf16 v[42:45], v[142:145], v[206:209], v[42:45]
	v_mfma_f32_16x16x32_bf16 v[30:33], v[134:137], v[214:217], v[30:33]
	v_mfma_f32_16x16x32_bf16 v[26:29], v[142:145], v[214:217], v[26:29]
	v_mfma_f32_16x16x32_bf16 v[14:17], v[134:137], v[222:225], v[14:17]
	v_mfma_f32_16x16x32_bf16 v[10:13], v[142:145], v[222:225], v[10:13]
	s_setprio 0
	s_setprio 1
	v_mfma_f32_16x16x32_bf16 v[54:57], v[146:149], v[174:177], v[54:57]
	v_mfma_f32_16x16x32_bf16 v[50:53], v[166:169], v[174:177], v[50:53]
	v_mfma_f32_16x16x32_bf16 v[38:41], v[146:149], v[190:193], v[38:41]
	v_mfma_f32_16x16x32_bf16 v[34:37], v[166:169], v[190:193], v[34:37]
	v_mfma_f32_16x16x32_bf16 v[22:25], v[146:149], v[210:213], v[22:25]
	v_mfma_f32_16x16x32_bf16 v[18:21], v[166:169], v[210:213], v[18:21]
	v_mfma_f32_16x16x32_bf16 v[6:9], v[146:149], v[218:221], v[6:9]
	v_mfma_f32_16x16x32_bf16 v[2:5], v[166:169], v[218:221], v[2:5]
	v_mfma_f32_16x16x32_bf16 v[54:57], v[150:153], v[178:181], v[54:57]
	v_mfma_f32_16x16x32_bf16 v[50:53], v[170:173], v[178:181], v[50:53]
	v_mfma_f32_16x16x32_bf16 v[38:41], v[150:153], v[206:209], v[38:41]
	v_mfma_f32_16x16x32_bf16 v[34:37], v[170:173], v[206:209], v[34:37]
	v_mfma_f32_16x16x32_bf16 v[22:25], v[150:153], v[214:217], v[22:25]
	v_mfma_f32_16x16x32_bf16 v[18:21], v[170:173], v[214:217], v[18:21]
	v_mfma_f32_16x16x32_bf16 v[6:9], v[150:153], v[222:225], v[6:9]
	v_mfma_f32_16x16x32_bf16 v[2:5], v[170:173], v[222:225], v[2:5]
	s_setprio 0
	s_barrier
	s_add_u32 s15, s15, 0x100
	s_addc_u32 s16, s16, 0
	s_add_u32 s0, s0, 0x100
	s_addc_u32 s1, s1, 0
	s_cmp_ge_i32 s38, s80
	s_mov_b32 s28, s38
	s_cbranch_scc0 .LBB0_428

; #define PG8_STAGE(bufoff, gbase, voff) do { _Pragma("unroll") for (int _i = 0; _i < 2; ++_i) \
;         __builtin_amdgcn_global_load_lds((const unsigned*)((const char*)(gbase) + (voff)[_i]), (LAS unsigned*)(lds + (bufoff) + ldsw + _i * 8192), 16, 0, 0); } while (0)
; #define PG8_LDA(dst, b, h) do { _Pragma("unroll") for (int m = 0; m < 4; ++m) _Pragma("unroll") for (int k = 0; k < 2; ++k) dst[m][k] = *(const LAS bf16x8*)(lds + PG8_SA(b, h) + aoff + m * 2048 + k * 1024); } while (0)
; #define PG8_LDB(dst, b, h) do { _Pragma("unroll") for (int n = 0; n < 2; ++n) _Pragma("unroll") for (int k = 0; k < 2; ++k) dst[n][k] = *(const LAS bf16x8*)(lds + PG8_SB(b, h) + boff + n * 2048 + k * 1024); } while (0)
; #define PG8_MMA(ai, bj, At, Bt) do { __builtin_amdgcn_s_setprio(1); _Pragma("unroll") for (int m = 0; m < 4; ++m) _Pragma("unroll") for (int n = 0; n < 2; ++n) _Pragma("unroll") for (int k = 0; k < 2; ++k) \
;         acc[ai][bj][m][n] = __builtin_amdgcn_mfma_f32_16x16x32_bf16(Bt[n][k], At[m][k], acc[ai][bj][m][n], 0, 0, 0); __builtin_amdgcn_s_setprio(0); } while (0)
; #define PG8_WAIT_V(n) asm volatile("s_waitcnt vmcnt(" #n ")" ::: "memory")
; #define PG8_WAIT_L(n) asm volatile("s_waitcnt lgkmcnt(" #n ")" ::: "memory")
; #define PG8_BAR __builtin_amdgcn_s_barrier()
; #define PG8_SCHED __builtin_amdgcn_sched_barrier(0)
; template <class Epi, class Sched>
; __device__ __forceinline__ void gemm_phase(LAS unsigned char* lds, const Gemm g, const Sched& S, const Epi& E) {
;     ...
;             PG8_LDB(B0, 0, 0); PG8_LDB(B1, 0, 1); PG8_SCHED; PG8_LDA(At, 0, 0); PG8_STAGE(PG8_SA(1, 1), a1 + hstep, voffA);
;             PG8_WAIT_V(8); PG8_WAIT_L(0); PG8_BAR; PG8_MMA(0, 0, At, B0); PG8_MMA(0, 1, At, B1); PG8_BAR; PG8_SCHED;
;             PG8_LDA(At, 0, 1); PG8_STAGE(PG8_SB(0, 0), b2, voffB); PG8_STAGE(PG8_SB(0, 1), b2 + hstep, voffB); PG8_STAGE(PG8_SA(0, 0), a2, voffA);
;             PG8_WAIT_V(8); PG8_WAIT_L(0); PG8_BAR; PG8_MMA(1, 0, At, B0); PG8_MMA(1, 1, At, B1); PG8_BAR; PG8_SCHED;
.LBB0_1440:
	ds_read_b128 v[130:133], v235
	ds_read_b128 v[134:137], v235 offset:1024
	ds_read_b128 v[138:141], v235 offset:2048
	ds_read_b128 v[142:145], v235 offset:3072
	ds_read_b128 v[146:149], v238
	ds_read_b128 v[150:153], v238 offset:1024
	ds_read_b128 v[166:169], v238 offset:2048
	ds_read_b128 v[170:173], v238 offset:3072
	ds_read_b128 v[174:177], v187
	ds_read_b128 v[178:181], v187 offset:1024
	ds_read_b128 v[188:191], v187 offset:2048
	ds_read_b128 v[206:209], v187 offset:3072
	ds_read_b128 v[210:213], v187 offset:4096
	ds_read_b128 v[214:217], v187 offset:5120
	ds_read_b128 v[218:221], v187 offset:6144
	ds_read_b128 v[222:225], v187 offset:7168
	s_add_i32 s38, s28, 2
	s_add_u32 s26, s0, 0x80
	s_addc_u32 s29, s1, 0
	s_add_i32 s39, 0, 0x10000
	s_cmp_eq_u32 s84, s28
	s_cselect_b32 s29, s43, s29
	s_cselect_b32 s28, s42, s26
	s_cselect_b32 s47, s41, s16
	s_cselect_b32 s46, s40, s15
	s_add_i32 s26, 0, 0x14000
	s_add_i32 m0, s13, 0xc000
	v_lshl_add_u64 v[182:183], s[0:1], 0, v[164:165]
	global_load_lds_dwordx4 v[182:183], off
	s_add_i32 m0, s13, 0xe000
	v_lshl_add_u64 v[182:183], s[0:1], 0, v[162:163]
	global_load_lds_dwordx4 v[182:183], off
	s_waitcnt vmcnt(8)
	s_waitcnt lgkmcnt(0)
	s_barrier
	s_setprio 1
	s_waitcnt lgkmcnt(0)
	v_mfma_f32_16x16x32_bf16 v[126:129], v[130:133], v[174:177], v[126:129]
	v_mfma_f32_16x16x32_bf16 v[122:125], v[138:141], v[174:177], v[122:125]
	v_mfma_f32_16x16x32_bf16 v[110:113], v[130:133], v[188:191], v[110:113]
	v_mfma_f32_16x16x32_bf16 v[106:109], v[138:141], v[188:191], v[106:109]
	v_mfma_f32_16x16x32_bf16 v[94:97], v[130:133], v[210:213], v[94:97]
	v_mfma_f32_16x16x32_bf16 v[90:93], v[138:141], v[210:213], v[90:93]
	v_mfma_f32_16x16x32_bf16 v[78:81], v[130:133], v[218:221], v[78:81]
	v_mfma_f32_16x16x32_bf16 v[74:77], v[138:141], v[218:221], v[74:77]
	v_mfma_f32_16x16x32_bf16 v[126:129], v[134:137], v[178:181], v[126:129]
	v_mfma_f32_16x16x32_bf16 v[122:125], v[142:145], v[178:181], v[122:125]
	v_mfma_f32_16x16x32_bf16 v[110:113], v[134:137], v[206:209], v[110:113]
	v_mfma_f32_16x16x32_bf16 v[106:109], v[142:145], v[206:209], v[106:109]
	v_mfma_f32_16x16x32_bf16 v[94:97], v[134:137], v[214:217], v[94:97]
	v_mfma_f32_16x16x32_bf16 v[90:93], v[142:145], v[214:217], v[90:93]
	v_mfma_f32_16x16x32_bf16 v[78:81], v[134:137], v[222:225], v[78:81]
	v_mfma_f32_16x16x32_bf16 v[74:77], v[142:145], v[222:225], v[74:77]
	s_setprio 0
	s_setprio 1
	v_mfma_f32_16x16x32_bf16 v[118:121], v[146:149], v[174:177], v[118:121]
	v_mfma_f32_16x16x32_bf16 v[114:117], v[166:169], v[174:177], v[114:117]
	v_mfma_f32_16x16x32_bf16 v[102:105], v[146:149], v[188:191], v[102:105]
	v_mfma_f32_16x16x32_bf16 v[98:101], v[166:169], v[188:191], v[98:101]
	v_mfma_f32_16x16x32_bf16 v[86:89], v[146:149], v[210:213], v[86:89]
	v_mfma_f32_16x16x32_bf16 v[82:85], v[166:169], v[210:213], v[82:85]
	v_mfma_f32_16x16x32_bf16 v[70:73], v[146:149], v[218:221], v[70:73]
	v_mfma_f32_16x16x32_bf16 v[66:69], v[166:169], v[218:221], v[66:69]
	v_mfma_f32_16x16x32_bf16 v[118:121], v[150:153], v[178:181], v[118:121]
	v_mfma_f32_16x16x32_bf16 v[114:117], v[170:173], v[178:181], v[114:117]
	v_mfma_f32_16x16x32_bf16 v[102:105], v[150:153], v[206:209], v[102:105]
	v_mfma_f32_16x16x32_bf16 v[98:101], v[170:173], v[206:209], v[98:101]
	v_mfma_f32_16x16x32_bf16 v[86:89], v[150:153], v[214:217], v[86:89]
	v_mfma_f32_16x16x32_bf16 v[82:85], v[170:173], v[214:217], v[82:85]
	v_mfma_f32_16x16x32_bf16 v[70:73], v[150:153], v[222:225], v[70:73]
	v_mfma_f32_16x16x32_bf16 v[66:69], v[170:173], v[222:225], v[66:69]
	s_setprio 0
	s_barrier
	s_add_i32 s39, s39, s12
	v_lshl_add_u64 v[182:183], s[46:47], 0, v[0:1]
	s_mov_b32 m0, s39
	ds_read_b128 v[174:177], v187 offset:16384
	ds_read_b128 v[178:181], v187 offset:17408
	ds_read_b128 v[188:191], v187 offset:18432
	ds_read_b128 v[206:209], v187 offset:19456
	ds_read_b128 v[210:213], v187 offset:20480
	ds_read_b128 v[214:217], v187 offset:21504
	ds_read_b128 v[218:221], v187 offset:22528
	ds_read_b128 v[222:225], v187 offset:23552
	global_load_lds_dwordx4 v[182:183], off
	s_add_i32 m0, s39, 0x2000
	v_lshl_add_u64 v[192:193], s[46:47], 0, v[154:155]
	s_add_u32 s46, s46, s58
	s_addc_u32 s47, s47, s59
	s_add_i32 s26, s26, s12
	global_load_lds_dwordx4 v[192:193], off
	v_lshl_add_u64 v[226:227], s[46:47], 0, v[0:1]
	s_mov_b32 m0, s26
	v_lshl_add_u64 v[228:229], s[46:47], 0, v[154:155]
	global_load_lds_dwordx4 v[226:227], off
	s_add_i32 m0, s26, 0x2000
	v_lshl_add_u64 v[230:231], s[28:29], 0, v[158:159]
	global_load_lds_dwordx4 v[228:229], off
	s_mov_b32 m0, s13
	v_lshl_add_u64 v[232:233], s[28:29], 0, v[156:157]
	global_load_lds_dwordx4 v[230:231], off
	s_mov_b32 m0, s27
	s_nop 0
	global_load_lds_dwordx4 v[232:233], off
	s_waitcnt vmcnt(8)
	s_waitcnt lgkmcnt(0)
	s_barrier
; #define PG8_STAGE(bufoff, gbase, voff) do { _Pragma("unroll") for (int _i = 0; _i < 2; ++_i) \
;         __builtin_amdgcn_global_load_lds((const unsigned*)((const char*)(gbase) + (voff)[_i]), (LAS unsigned*)(lds + (bufoff) + ldsw + _i * 8192), 16, 0, 0); } while (0)
; #define PG8_LDA(dst, b, h) do { _Pragma("unroll") for (int m = 0; m < 4; ++m) _Pragma("unroll") for (int k = 0; k < 2; ++k) dst[m][k] = *(const LAS bf16x8*)(lds + PG8_SA(b, h) + aoff + m * 2048 + k * 1024); } while (0)
; #define PG8_LDB(dst, b, h) do { _Pragma("unroll") for (int n = 0; n < 2; ++n) _Pragma("unroll") for (int k = 0; k < 2; ++k) dst[n][k] = *(const LAS bf16x8*)(lds + PG8_SB(b, h) + boff + n * 2048 + k * 1024); } while (0)
; #define PG8_MMA(ai, bj, At, Bt) do { __builtin_amdgcn_s_setprio(1); _Pragma("unroll") for (int m = 0; m < 4; ++m) _Pragma("unroll") for (int n = 0; n < 2; ++n) _Pragma("unroll") for (int k = 0; k < 2; ++k) \
;         acc[ai][bj][m][n] = __builtin_amdgcn_mfma_f32_16x16x32_bf16(Bt[n][k], At[m][k], acc[ai][bj][m][n], 0, 0, 0); __builtin_amdgcn_s_setprio(0); } while (0)
; #define PG8_WAIT_V(n) asm volatile("s_waitcnt vmcnt(" #n ")" ::: "memory")
; #define PG8_WAIT_L(n) asm volatile("s_waitcnt lgkmcnt(" #n ")" ::: "memory")
; #define PG8_BAR __builtin_amdgcn_s_barrier()
; #define PG8_SCHED __builtin_amdgcn_sched_barrier(0)
; template <class Epi, class Sched>
; __device__ __forceinline__ void gemm_phase(LAS unsigned char* lds, const Gemm g, const Sched& S, const Epi& E) {
;     ...
;             PG8_WAIT_V(8); PG8_WAIT_L(0); PG8_BAR; PG8_MMA(1, 0, At, B0); PG8_MMA(1, 1, At, B1); PG8_BAR; PG8_SCHED;
;             PG8_LDB(B0, 1, 0); PG8_LDB(B1, 1, 1); PG8_SCHED; PG8_LDA(At, 1, 0); PG8_STAGE(PG8_SA(0, 1), a2 + hstep, voffA);
;             PG8_WAIT_V(8); PG8_WAIT_L(0); PG8_BAR; PG8_MMA(0, 0, At, B0); PG8_MMA(0, 1, At, B1); PG8_BAR; PG8_SCHED;
	s_setprio 1
	s_waitcnt lgkmcnt(0)
	v_mfma_f32_16x16x32_bf16 v[62:65], v[130:133], v[174:177], v[62:65]
	v_mfma_f32_16x16x32_bf16 v[58:61], v[138:141], v[174:177], v[58:61]
	v_mfma_f32_16x16x32_bf16 v[46:49], v[130:133], v[188:191], v[46:49]
	v_mfma_f32_16x16x32_bf16 v[42:45], v[138:141], v[188:191], v[42:45]
	v_mfma_f32_16x16x32_bf16 v[30:33], v[130:133], v[210:213], v[30:33]
	v_mfma_f32_16x16x32_bf16 v[26:29], v[138:141], v[210:213], v[26:29]
	v_mfma_f32_16x16x32_bf16 v[14:17], v[130:133], v[218:221], v[14:17]
	v_mfma_f32_16x16x32_bf16 v[10:13], v[138:141], v[218:221], v[10:13]
	v_mfma_f32_16x16x32_bf16 v[62:65], v[134:137], v[178:181], v[62:65]
	v_mfma_f32_16x16x32_bf16 v[58:61], v[142:145], v[178:181], v[58:61]
	v_mfma_f32_16x16x32_bf16 v[46:49], v[134:137], v[206:209], v[46:49]
	v_mfma_f32_16x16x32_bf16 v[42:45], v[142:145], v[206:209], v[42:45]
	v_mfma_f32_16x16x32_bf16 v[30:33], v[134:137], v[214:217], v[30:33]
	v_mfma_f32_16x16x32_bf16 v[26:29], v[142:145], v[214:217], v[26:29]
	v_mfma_f32_16x16x32_bf16 v[14:17], v[134:137], v[222:225], v[14:17]
	v_mfma_f32_16x16x32_bf16 v[10:13], v[142:145], v[222:225], v[10:13]
	s_setprio 0
	s_setprio 1
	v_mfma_f32_16x16x32_bf16 v[54:57], v[146:149], v[174:177], v[54:57]
	v_mfma_f32_16x16x32_bf16 v[50:53], v[166:169], v[174:177], v[50:53]
	v_mfma_f32_16x16x32_bf16 v[38:41], v[146:149], v[188:191], v[38:41]
	v_mfma_f32_16x16x32_bf16 v[34:37], v[166:169], v[188:191], v[34:37]
	v_mfma_f32_16x16x32_bf16 v[22:25], v[146:149], v[210:213], v[22:25]
	v_mfma_f32_16x16x32_bf16 v[18:21], v[166:169], v[210:213], v[18:21]
	v_mfma_f32_16x16x32_bf16 v[6:9], v[146:149], v[218:221], v[6:9]
	v_mfma_f32_16x16x32_bf16 v[2:5], v[166:169], v[218:221], v[2:5]
	v_mfma_f32_16x16x32_bf16 v[54:57], v[150:153], v[178:181], v[54:57]
	v_mfma_f32_16x16x32_bf16 v[50:53], v[170:173], v[178:181], v[50:53]
	v_mfma_f32_16x16x32_bf16 v[38:41], v[150:153], v[206:209], v[38:41]
	v_mfma_f32_16x16x32_bf16 v[34:37], v[170:173], v[206:209], v[34:37]
	v_mfma_f32_16x16x32_bf16 v[22:25], v[150:153], v[214:217], v[22:25]
	v_mfma_f32_16x16x32_bf16 v[18:21], v[170:173], v[214:217], v[18:21]
	v_mfma_f32_16x16x32_bf16 v[6:9], v[150:153], v[222:225], v[6:9]
	v_mfma_f32_16x16x32_bf16 v[2:5], v[170:173], v[222:225], v[2:5]
	s_setprio 0
	s_barrier
	ds_read_b128 v[130:133], v239
	ds_read_b128 v[134:137], v239 offset:1024
	ds_read_b128 v[138:141], v239 offset:2048
	ds_read_b128 v[142:145], v239 offset:3072
	ds_read_b128 v[146:149], v250
	ds_read_b128 v[150:153], v250 offset:1024
	ds_read_b128 v[166:169], v250 offset:2048
	ds_read_b128 v[170:173], v250 offset:3072
	s_add_i32 s26, 0, 0x18000
	s_add_i32 s39, 0, 0x1c000
	s_add_u32 s28, s28, s58
	s_addc_u32 s29, s29, s59
	s_mov_b32 m0, s30
	v_lshl_add_u64 v[244:245], s[28:29], 0, v[158:159]
	ds_read_b128 v[174:177], v187 offset:32768
	ds_read_b128 v[178:181], v187 offset:33792
	ds_read_b128 v[188:191], v187 offset:34816
	ds_read_b128 v[206:209], v187 offset:35840
	ds_read_b128 v[210:213], v187 offset:36864
	ds_read_b128 v[214:217], v187 offset:37888
	ds_read_b128 v[218:221], v187 offset:38912
	ds_read_b128 v[222:225], v187 offset:39936
	global_load_lds_dwordx4 v[244:245], off
	s_mov_b32 m0, s31
	v_lshl_add_u64 v[244:245], s[28:29], 0, v[156:157]
	global_load_lds_dwordx4 v[244:245], off
	s_waitcnt vmcnt(8)
	s_waitcnt lgkmcnt(0)
	s_barrier
	s_setprio 1
	s_waitcnt lgkmcnt(0)
	v_mfma_f32_16x16x32_bf16 v[126:129], v[130:133], v[174:177], v[126:129]
	v_mfma_f32_16x16x32_bf16 v[122:125], v[138:141], v[174:177], v[122:125]
	v_mfma_f32_16x16x32_bf16 v[110:113], v[130:133], v[188:191], v[110:113]
	v_mfma_f32_16x16x32_bf16 v[106:109], v[138:141], v[188:191], v[106:109]
	v_mfma_f32_16x16x32_bf16 v[94:97], v[130:133], v[210:213], v[94:97]
	v_mfma_f32_16x16x32_bf16 v[90:93], v[138:141], v[210:213], v[90:93]
	v_mfma_f32_16x16x32_bf16 v[78:81], v[130:133], v[218:221], v[78:81]
	v_mfma_f32_16x16x32_bf16 v[74:77], v[138:141], v[218:221], v[74:77]
	v_mfma_f32_16x16x32_bf16 v[126:129], v[134:137], v[178:181], v[126:129]
	v_mfma_f32_16x16x32_bf16 v[122:125], v[142:145], v[178:181], v[122:125]
	v_mfma_f32_16x16x32_bf16 v[110:113], v[134:137], v[206:209], v[110:113]
	v_mfma_f32_16x16x32_bf16 v[106:109], v[142:145], v[206:209], v[106:109]
	v_mfma_f32_16x16x32_bf16 v[94:97], v[134:137], v[214:217], v[94:97]
	v_mfma_f32_16x16x32_bf16 v[90:93], v[142:145], v[214:217], v[90:93]
	v_mfma_f32_16x16x32_bf16 v[78:81], v[134:137], v[222:225], v[78:81]
	v_mfma_f32_16x16x32_bf16 v[74:77], v[142:145], v[222:225], v[74:77]
	s_setprio 0
	s_setprio 1
	v_mfma_f32_16x16x32_bf16 v[118:121], v[146:149], v[174:177], v[118:121]
	v_mfma_f32_16x16x32_bf16 v[114:117], v[166:169], v[174:177], v[114:117]
	v_mfma_f32_16x16x32_bf16 v[102:105], v[146:149], v[188:191], v[102:105]
	v_mfma_f32_16x16x32_bf16 v[98:101], v[166:169], v[188:191], v[98:101]
	v_mfma_f32_16x16x32_bf16 v[86:89], v[146:149], v[210:213], v[86:89]
	v_mfma_f32_16x16x32_bf16 v[82:85], v[166:169], v[210:213], v[82:85]
	v_mfma_f32_16x16x32_bf16 v[70:73], v[146:149], v[218:221], v[70:73]
	v_mfma_f32_16x16x32_bf16 v[66:69], v[166:169], v[218:221], v[66:69]
	v_mfma_f32_16x16x32_bf16 v[118:121], v[150:153], v[178:181], v[118:121]
	v_mfma_f32_16x16x32_bf16 v[114:117], v[170:173], v[178:181], v[114:117]
	v_mfma_f32_16x16x32_bf16 v[102:105], v[150:153], v[206:209], v[102:105]
	v_mfma_f32_16x16x32_bf16 v[98:101], v[170:173], v[206:209], v[98:101]
	v_mfma_f32_16x16x32_bf16 v[86:89], v[150:153], v[214:217], v[86:89]
	v_mfma_f32_16x16x32_bf16 v[82:85], v[170:173], v[214:217], v[82:85]
	v_mfma_f32_16x16x32_bf16 v[70:73], v[150:153], v[222:225], v[70:73]
	v_mfma_f32_16x16x32_bf16 v[66:69], v[170:173], v[222:225], v[66:69]
	s_setprio 0
	s_barrier
; #define PG8_STAGE(bufoff, gbase, voff) do { _Pragma("unroll") for (int _i = 0; _i < 2; ++_i) \
;         __builtin_amdgcn_global_load_lds((const unsigned*)((const char*)(gbase) + (voff)[_i]), (LAS unsigned*)(lds + (bufoff) + ldsw + _i * 8192), 16, 0, 0); } while (0)
; #define PG8_LDA(dst, b, h) do { _Pragma("unroll") for (int m = 0; m < 4; ++m) _Pragma("unroll") for (int k = 0; k < 2; ++k) dst[m][k] = *(const LAS bf16x8*)(lds + PG8_SA(b, h) + aoff + m * 2048 + k * 1024); } while (0)
; #define PG8_MMA(ai, bj, At, Bt) do { __builtin_amdgcn_s_setprio(1); _Pragma("unroll") for (int m = 0; m < 4; ++m) _Pragma("unroll") for (int n = 0; n < 2; ++n) _Pragma("unroll") for (int k = 0; k < 2; ++k) \
;         acc[ai][bj][m][n] = __builtin_amdgcn_mfma_f32_16x16x32_bf16(Bt[n][k], At[m][k], acc[ai][bj][m][n], 0, 0, 0); __builtin_amdgcn_s_setprio(0); } while (0)
; #define PG8_WAIT_V(n) asm volatile("s_waitcnt vmcnt(" #n ")" ::: "memory")
; #define PG8_WAIT_L(n) asm volatile("s_waitcnt lgkmcnt(" #n ")" ::: "memory")
; #define PG8_BAR __builtin_amdgcn_s_barrier()
; #define PG8_SCHED __builtin_amdgcn_sched_barrier(0)
; template <class Epi, class Sched>
; __device__ __forceinline__ void gemm_phase(LAS unsigned char* lds, const Gemm g, const Sched& S, const Epi& E) {
;     ...
;             PG8_LDA(At, 1, 1); PG8_STAGE(PG8_SB(1, 0), b3, voffB); PG8_STAGE(PG8_SB(1, 1), b3 + hstep, voffB); PG8_STAGE(PG8_SA(1, 0), a3, voffA);
;             PG8_WAIT_V(8); PG8_WAIT_L(0); PG8_BAR; PG8_MMA(1, 0, At, B0); PG8_MMA(1, 1, At, B1); PG8_BAR; PG8_SCHED;
;         }
	s_add_i32 s26, s26, s12
	v_lshl_add_u64 v[182:183], v[182:183], 0, s[18:19]
	s_mov_b32 m0, s26
	ds_read_b128 v[174:177], v187 offset:49152
	ds_read_b128 v[178:181], v187 offset:50176
	ds_read_b128 v[188:191], v187 offset:51200
	ds_read_b128 v[206:209], v187 offset:52224
	ds_read_b128 v[210:213], v187 offset:53248
	ds_read_b128 v[214:217], v187 offset:54272
	ds_read_b128 v[218:221], v187 offset:55296
	ds_read_b128 v[222:225], v187 offset:56320
	global_load_lds_dwordx4 v[182:183], off
	v_lshl_add_u64 v[182:183], v[192:193], 0, s[18:19]
	s_add_i32 m0, s26, 0x2000
	s_add_i32 s26, s39, s12
	global_load_lds_dwordx4 v[182:183], off
	s_mov_b32 m0, s26
	v_lshl_add_u64 v[182:183], v[226:227], 0, s[18:19]
	global_load_lds_dwordx4 v[182:183], off
	s_add_i32 m0, s26, 0x2000
	v_lshl_add_u64 v[182:183], v[228:229], 0, s[18:19]
	global_load_lds_dwordx4 v[182:183], off
	s_mov_b32 m0, s34
	v_lshl_add_u64 v[182:183], v[230:231], 0, s[18:19]
	global_load_lds_dwordx4 v[182:183], off
	s_mov_b32 m0, s35
	v_lshl_add_u64 v[182:183], v[232:233], 0, s[18:19]
	global_load_lds_dwordx4 v[182:183], off
	s_waitcnt vmcnt(8)
	s_waitcnt lgkmcnt(0)
	s_barrier
	s_setprio 1
	s_waitcnt lgkmcnt(0)
	v_mfma_f32_16x16x32_bf16 v[62:65], v[130:133], v[174:177], v[62:65]
	v_mfma_f32_16x16x32_bf16 v[58:61], v[138:141], v[174:177], v[58:61]
	v_mfma_f32_16x16x32_bf16 v[46:49], v[130:133], v[188:191], v[46:49]
	v_mfma_f32_16x16x32_bf16 v[42:45], v[138:141], v[188:191], v[42:45]
	v_mfma_f32_16x16x32_bf16 v[30:33], v[130:133], v[210:213], v[30:33]
	v_mfma_f32_16x16x32_bf16 v[26:29], v[138:141], v[210:213], v[26:29]
	v_mfma_f32_16x16x32_bf16 v[14:17], v[130:133], v[218:221], v[14:17]
	v_mfma_f32_16x16x32_bf16 v[10:13], v[138:141], v[218:221], v[10:13]
	v_mfma_f32_16x16x32_bf16 v[62:65], v[134:137], v[178:181], v[62:65]
	v_mfma_f32_16x16x32_bf16 v[58:61], v[142:145], v[178:181], v[58:61]
	v_mfma_f32_16x16x32_bf16 v[46:49], v[134:137], v[206:209], v[46:49]
	v_mfma_f32_16x16x32_bf16 v[42:45], v[142:145], v[206:209], v[42:45]
	v_mfma_f32_16x16x32_bf16 v[30:33], v[134:137], v[214:217], v[30:33]
	v_mfma_f32_16x16x32_bf16 v[26:29], v[142:145], v[214:217], v[26:29]
	v_mfma_f32_16x16x32_bf16 v[14:17], v[134:137], v[222:225], v[14:17]
	v_mfma_f32_16x16x32_bf16 v[10:13], v[142:145], v[222:225], v[10:13]
	s_setprio 0
	s_setprio 1
	v_mfma_f32_16x16x32_bf16 v[54:57], v[146:149], v[174:177], v[54:57]
	v_mfma_f32_16x16x32_bf16 v[50:53], v[166:169], v[174:177], v[50:53]
	v_mfma_f32_16x16x32_bf16 v[38:41], v[146:149], v[188:191], v[38:41]
	v_mfma_f32_16x16x32_bf16 v[34:37], v[166:169], v[188:191], v[34:37]
	v_mfma_f32_16x16x32_bf16 v[22:25], v[146:149], v[210:213], v[22:25]
	v_mfma_f32_16x16x32_bf16 v[18:21], v[166:169], v[210:213], v[18:21]
	v_mfma_f32_16x16x32_bf16 v[6:9], v[146:149], v[218:221], v[6:9]
	v_mfma_f32_16x16x32_bf16 v[2:5], v[166:169], v[218:221], v[2:5]
	v_mfma_f32_16x16x32_bf16 v[54:57], v[150:153], v[178:181], v[54:57]
	v_mfma_f32_16x16x32_bf16 v[50:53], v[170:173], v[178:181], v[50:53]
	v_mfma_f32_16x16x32_bf16 v[38:41], v[150:153], v[206:209], v[38:41]
	v_mfma_f32_16x16x32_bf16 v[34:37], v[170:173], v[206:209], v[34:37]
	v_mfma_f32_16x16x32_bf16 v[22:25], v[150:153], v[214:217], v[22:25]
	v_mfma_f32_16x16x32_bf16 v[18:21], v[170:173], v[214:217], v[18:21]
	v_mfma_f32_16x16x32_bf16 v[6:9], v[150:153], v[222:225], v[6:9]
	v_mfma_f32_16x16x32_bf16 v[2:5], v[170:173], v[222:225], v[2:5]
	s_setprio 0
	s_barrier
	s_add_u32 s15, s15, 0x100
	s_addc_u32 s16, s16, 0
	s_add_u32 s0, s0, 0x100
	s_addc_u32 s1, s1, 0
	s_cmp_ge_i32 s38, s80
	s_mov_b32 s28, s38
	s_cbranch_scc0 .LBB0_1440

; #define PG8_STAGE(bufoff, gbase, voff) do { _Pragma("unroll") for (int _i = 0; _i < 2; ++_i) \
;         __builtin_amdgcn_global_load_lds((const unsigned*)((const char*)(gbase) + (voff)[_i]), (LAS unsigned*)(lds + (bufoff) + ldsw + _i * 8192), 16, 0, 0); } while (0)
; #define PG8_LDA(dst, b, h) do { _Pragma("unroll") for (int m = 0; m < 4; ++m) _Pragma("unroll") for (int k = 0; k < 2; ++k) dst[m][k] = *(const LAS bf16x8*)(lds + PG8_SA(b, h) + aoff + m * 2048 + k * 1024); } while (0)
; #define PG8_LDB(dst, b, h) do { _Pragma("unroll") for (int n = 0; n < 2; ++n) _Pragma("unroll") for (int k = 0; k < 2; ++k) dst[n][k] = *(const LAS bf16x8*)(lds + PG8_SB(b, h) + boff + n * 2048 + k * 1024); } while (0)
; #define PG8_MMA(ai, bj, At, Bt) do { __builtin_amdgcn_s_setprio(1); _Pragma("unroll") for (int m = 0; m < 4; ++m) _Pragma("unroll") for (int n = 0; n < 2; ++n) _Pragma("unroll") for (int k = 0; k < 2; ++k) \
;         acc[ai][bj][m][n] = __builtin_amdgcn_mfma_f32_16x16x32_bf16(Bt[n][k], At[m][k], acc[ai][bj][m][n], 0, 0, 0); __builtin_amdgcn_s_setprio(0); } while (0)
; #define PG8_WAIT_V(n) asm volatile("s_waitcnt vmcnt(" #n ")" ::: "memory")
; #define PG8_WAIT_L(n) asm volatile("s_waitcnt lgkmcnt(" #n ")" ::: "memory")
; #define PG8_BAR __builtin_amdgcn_s_barrier()
; #define PG8_SCHED __builtin_amdgcn_sched_barrier(0)
; template <class Epi, class Sched>
; __device__ __forceinline__ void gemm_phase(LAS unsigned char* lds, const Gemm g, const Sched& S, const Epi& E) {
;     ...
;             PG8_LDB(B0, 0, 0); PG8_LDB(B1, 0, 1); PG8_SCHED; PG8_LDA(At, 0, 0); PG8_STAGE(PG8_SA(1, 1), a1 + hstep, voffA);
;             PG8_WAIT_V(8); PG8_WAIT_L(0); PG8_BAR; PG8_MMA(0, 0, At, B0); PG8_MMA(0, 1, At, B1); PG8_BAR; PG8_SCHED;
;             PG8_LDA(At, 0, 1); PG8_STAGE(PG8_SB(0, 0), b2, voffB); PG8_STAGE(PG8_SB(0, 1), b2 + hstep, voffB); PG8_STAGE(PG8_SA(0, 0), a2, voffA);
;             PG8_WAIT_V(8); PG8_WAIT_L(0); PG8_BAR; PG8_MMA(1, 0, At, B0); PG8_MMA(1, 1, At, B1); PG8_BAR; PG8_SCHED;
.LBB0_1556:
	s_add_i32 s38, s28, 2
	s_add_u32 s26, s0, 0x80
	s_addc_u32 s29, s1, 0
	s_add_i32 s39, 0, 0x10000
	s_cmp_eq_u32 s84, s28
	s_cselect_b32 s29, s65, s29
	s_cselect_b32 s28, s64, s26
	v_add_u32_e32 v0, s39, v244
	s_cselect_b32 s47, s67, s16
	s_cselect_b32 s46, s66, s15
	s_add_i32 s26, 0, 0x14000
	ds_read_b128 v[130:133], v0
	ds_read_b128 v[134:137], v0 offset:1024
	ds_read_b128 v[138:141], v0 offset:2048
	ds_read_b128 v[142:145], v0 offset:3072
	v_add_u32_e32 v0, s26, v244
	ds_read_b128 v[146:149], v0
	ds_read_b128 v[150:153], v0 offset:1024
	ds_read_b128 v[154:157], v0 offset:2048
	ds_read_b128 v[158:161], v0 offset:3072
	v_lshl_add_u64 v[218:219], s[0:1], 0, v[216:217]
	s_add_i32 m0, s13, 0xc000
	ds_read_b128 v[162:165], v246
	ds_read_b128 v[166:169], v246 offset:1024
	ds_read_b128 v[170:173], v246 offset:2048
	ds_read_b128 v[174:177], v246 offset:3072
	ds_read_b128 v[178:181], v246 offset:4096
	ds_read_b128 v[182:185], v246 offset:5120
	ds_read_b128 v[186:189], v246 offset:6144
	ds_read_b128 v[190:193], v246 offset:7168
	global_load_lds_dwordx4 v[218:219], off
	s_add_i32 m0, s13, 0xe000
	v_lshl_add_u64 v[218:219], s[0:1], 0, v[214:215]
	global_load_lds_dwordx4 v[218:219], off
	s_waitcnt vmcnt(8)
	s_waitcnt lgkmcnt(0)
	s_barrier
	s_setprio 1
	s_waitcnt lgkmcnt(0)
	v_mfma_f32_16x16x32_bf16 v[126:129], v[130:133], v[162:165], v[126:129]
	v_mfma_f32_16x16x32_bf16 v[122:125], v[138:141], v[162:165], v[122:125]
	v_mfma_f32_16x16x32_bf16 v[110:113], v[130:133], v[170:173], v[110:113]
	v_mfma_f32_16x16x32_bf16 v[106:109], v[138:141], v[170:173], v[106:109]
	v_mfma_f32_16x16x32_bf16 v[102:105], v[130:133], v[178:181], v[102:105]
	v_mfma_f32_16x16x32_bf16 v[98:101], v[138:141], v[178:181], v[98:101]
	v_mfma_f32_16x16x32_bf16 v[94:97], v[130:133], v[186:189], v[94:97]
	v_mfma_f32_16x16x32_bf16 v[90:93], v[138:141], v[186:189], v[90:93]
	v_mfma_f32_16x16x32_bf16 v[126:129], v[134:137], v[166:169], v[126:129]
	v_mfma_f32_16x16x32_bf16 v[122:125], v[142:145], v[166:169], v[122:125]
	v_mfma_f32_16x16x32_bf16 v[110:113], v[134:137], v[174:177], v[110:113]
	v_mfma_f32_16x16x32_bf16 v[106:109], v[142:145], v[174:177], v[106:109]
	v_mfma_f32_16x16x32_bf16 v[102:105], v[134:137], v[182:185], v[102:105]
	v_mfma_f32_16x16x32_bf16 v[98:101], v[142:145], v[182:185], v[98:101]
	v_mfma_f32_16x16x32_bf16 v[94:97], v[134:137], v[190:193], v[94:97]
	v_mfma_f32_16x16x32_bf16 v[90:93], v[142:145], v[190:193], v[90:93]
	s_setprio 0
	s_setprio 1
	v_mfma_f32_16x16x32_bf16 v[118:121], v[146:149], v[162:165], v[118:121]
	v_mfma_f32_16x16x32_bf16 v[114:117], v[154:157], v[162:165], v[114:117]
	v_mfma_f32_16x16x32_bf16 v[86:89], v[146:149], v[170:173], v[86:89]
	v_mfma_f32_16x16x32_bf16 v[82:85], v[154:157], v[170:173], v[82:85]
	v_mfma_f32_16x16x32_bf16 v[78:81], v[146:149], v[178:181], v[78:81]
	v_mfma_f32_16x16x32_bf16 v[74:77], v[154:157], v[178:181], v[74:77]
	v_mfma_f32_16x16x32_bf16 v[70:73], v[146:149], v[186:189], v[70:73]
	v_mfma_f32_16x16x32_bf16 v[66:69], v[154:157], v[186:189], v[66:69]
	v_mfma_f32_16x16x32_bf16 v[118:121], v[150:153], v[166:169], v[118:121]
	v_mfma_f32_16x16x32_bf16 v[114:117], v[158:161], v[166:169], v[114:117]
	v_mfma_f32_16x16x32_bf16 v[86:89], v[150:153], v[174:177], v[86:89]
	v_mfma_f32_16x16x32_bf16 v[82:85], v[158:161], v[174:177], v[82:85]
	v_mfma_f32_16x16x32_bf16 v[78:81], v[150:153], v[182:185], v[78:81]
	v_mfma_f32_16x16x32_bf16 v[74:77], v[158:161], v[182:185], v[74:77]
	v_mfma_f32_16x16x32_bf16 v[70:73], v[150:153], v[190:193], v[70:73]
	v_mfma_f32_16x16x32_bf16 v[66:69], v[158:161], v[190:193], v[66:69]
	s_setprio 0
	s_barrier
	s_add_i32 s39, s39, s12
	v_lshl_add_u64 v[218:219], s[46:47], 0, v[210:211]
	s_mov_b32 m0, s39
	ds_read_b128 v[162:165], v246 offset:16384
	ds_read_b128 v[166:169], v246 offset:17408
	ds_read_b128 v[170:173], v246 offset:18432
	ds_read_b128 v[174:177], v246 offset:19456
	ds_read_b128 v[178:181], v246 offset:20480
	ds_read_b128 v[182:185], v246 offset:21504
	ds_read_b128 v[186:189], v246 offset:22528
	ds_read_b128 v[190:193], v246 offset:23552
	global_load_lds_dwordx4 v[218:219], off
	s_add_i32 m0, s39, 0x2000
	v_lshl_add_u64 v[220:221], s[46:47], 0, v[206:207]
	s_add_u32 s46, s46, s48
	s_addc_u32 s47, s47, s49
	s_add_i32 s26, s26, s12
	global_load_lds_dwordx4 v[220:221], off
	v_lshl_add_u64 v[222:223], s[46:47], 0, v[210:211]
	s_mov_b32 m0, s26
	v_lshl_add_u64 v[224:225], s[46:47], 0, v[206:207]
	global_load_lds_dwordx4 v[222:223], off
	s_add_i32 m0, s26, 0x2000
	v_lshl_add_u64 v[226:227], s[28:29], 0, v[212:213]
	global_load_lds_dwordx4 v[224:225], off
	s_mov_b32 m0, s13
	v_lshl_add_u64 v[228:229], s[28:29], 0, v[208:209]
	global_load_lds_dwordx4 v[226:227], off
	s_mov_b32 m0, s27
	s_nop 0
	global_load_lds_dwordx4 v[228:229], off
	s_waitcnt vmcnt(8)
	s_waitcnt lgkmcnt(0)
	s_barrier
; #define PG8_STAGE(bufoff, gbase, voff) do { _Pragma("unroll") for (int _i = 0; _i < 2; ++_i) \
;         __builtin_amdgcn_global_load_lds((const unsigned*)((const char*)(gbase) + (voff)[_i]), (LAS unsigned*)(lds + (bufoff) + ldsw + _i * 8192), 16, 0, 0); } while (0)
; #define PG8_LDA(dst, b, h) do { _Pragma("unroll") for (int m = 0; m < 4; ++m) _Pragma("unroll") for (int k = 0; k < 2; ++k) dst[m][k] = *(const LAS bf16x8*)(lds + PG8_SA(b, h) + aoff + m * 2048 + k * 1024); } while (0)
; #define PG8_LDB(dst, b, h) do { _Pragma("unroll") for (int n = 0; n < 2; ++n) _Pragma("unroll") for (int k = 0; k < 2; ++k) dst[n][k] = *(const LAS bf16x8*)(lds + PG8_SB(b, h) + boff + n * 2048 + k * 1024); } while (0)
; #define PG8_MMA(ai, bj, At, Bt) do { __builtin_amdgcn_s_setprio(1); _Pragma("unroll") for (int m = 0; m < 4; ++m) _Pragma("unroll") for (int n = 0; n < 2; ++n) _Pragma("unroll") for (int k = 0; k < 2; ++k) \
;         acc[ai][bj][m][n] = __builtin_amdgcn_mfma_f32_16x16x32_bf16(Bt[n][k], At[m][k], acc[ai][bj][m][n], 0, 0, 0); __builtin_amdgcn_s_setprio(0); } while (0)
; #define PG8_WAIT_V(n) asm volatile("s_waitcnt vmcnt(" #n ")" ::: "memory")
; #define PG8_WAIT_L(n) asm volatile("s_waitcnt lgkmcnt(" #n ")" ::: "memory")
; #define PG8_BAR __builtin_amdgcn_s_barrier()
; #define PG8_SCHED __builtin_amdgcn_sched_barrier(0)
; template <class Epi, class Sched>
; __device__ __forceinline__ void gemm_phase(LAS unsigned char* lds, const Gemm g, const Sched& S, const Epi& E) {
;     ...
;             PG8_WAIT_V(8); PG8_WAIT_L(0); PG8_BAR; PG8_MMA(1, 0, At, B0); PG8_MMA(1, 1, At, B1); PG8_BAR; PG8_SCHED;
;             PG8_LDB(B0, 1, 0); PG8_LDB(B1, 1, 1); PG8_SCHED; PG8_LDA(At, 1, 0); PG8_STAGE(PG8_SA(0, 1), a2 + hstep, voffA);
;             PG8_WAIT_V(8); PG8_WAIT_L(0); PG8_BAR; PG8_MMA(0, 0, At, B0); PG8_MMA(0, 1, At, B1); PG8_BAR; PG8_SCHED;
	s_setprio 1
	s_waitcnt lgkmcnt(0)
	v_mfma_f32_16x16x32_bf16 v[62:65], v[130:133], v[162:165], v[62:65]
	v_mfma_f32_16x16x32_bf16 v[58:61], v[138:141], v[162:165], v[58:61]
	v_mfma_f32_16x16x32_bf16 v[46:49], v[130:133], v[170:173], v[46:49]
	v_mfma_f32_16x16x32_bf16 v[42:45], v[138:141], v[170:173], v[42:45]
	v_mfma_f32_16x16x32_bf16 v[30:33], v[130:133], v[178:181], v[30:33]
	v_mfma_f32_16x16x32_bf16 v[26:29], v[138:141], v[178:181], v[26:29]
	v_mfma_f32_16x16x32_bf16 v[14:17], v[130:133], v[186:189], v[14:17]
	v_mfma_f32_16x16x32_bf16 v[10:13], v[138:141], v[186:189], v[10:13]
	v_mfma_f32_16x16x32_bf16 v[62:65], v[134:137], v[166:169], v[62:65]
	v_mfma_f32_16x16x32_bf16 v[58:61], v[142:145], v[166:169], v[58:61]
	v_mfma_f32_16x16x32_bf16 v[46:49], v[134:137], v[174:177], v[46:49]
	v_mfma_f32_16x16x32_bf16 v[42:45], v[142:145], v[174:177], v[42:45]
	v_mfma_f32_16x16x32_bf16 v[30:33], v[134:137], v[182:185], v[30:33]
	v_mfma_f32_16x16x32_bf16 v[26:29], v[142:145], v[182:185], v[26:29]
	v_mfma_f32_16x16x32_bf16 v[14:17], v[134:137], v[190:193], v[14:17]
	v_mfma_f32_16x16x32_bf16 v[10:13], v[142:145], v[190:193], v[10:13]
	s_setprio 0
	s_setprio 1
	v_mfma_f32_16x16x32_bf16 v[54:57], v[146:149], v[162:165], v[54:57]
	v_mfma_f32_16x16x32_bf16 v[50:53], v[154:157], v[162:165], v[50:53]
	v_mfma_f32_16x16x32_bf16 v[38:41], v[146:149], v[170:173], v[38:41]
	v_mfma_f32_16x16x32_bf16 v[34:37], v[154:157], v[170:173], v[34:37]
	v_mfma_f32_16x16x32_bf16 v[22:25], v[146:149], v[178:181], v[22:25]
	v_mfma_f32_16x16x32_bf16 v[18:21], v[154:157], v[178:181], v[18:21]
	v_mfma_f32_16x16x32_bf16 v[6:9], v[146:149], v[186:189], v[6:9]
	v_mfma_f32_16x16x32_bf16 v[2:5], v[154:157], v[186:189], v[2:5]
	v_mfma_f32_16x16x32_bf16 v[54:57], v[150:153], v[166:169], v[54:57]
	v_mfma_f32_16x16x32_bf16 v[50:53], v[158:161], v[166:169], v[50:53]
	v_mfma_f32_16x16x32_bf16 v[38:41], v[150:153], v[174:177], v[38:41]
	v_mfma_f32_16x16x32_bf16 v[34:37], v[158:161], v[174:177], v[34:37]
	v_mfma_f32_16x16x32_bf16 v[22:25], v[150:153], v[182:185], v[22:25]
	v_mfma_f32_16x16x32_bf16 v[18:21], v[158:161], v[182:185], v[18:21]
	v_mfma_f32_16x16x32_bf16 v[6:9], v[150:153], v[190:193], v[6:9]
	v_mfma_f32_16x16x32_bf16 v[2:5], v[158:161], v[190:193], v[2:5]
	s_setprio 0
	s_barrier
	s_add_i32 s26, 0, 0x18000
	v_add_u32_e32 v0, s26, v244
	s_add_i32 s39, 0, 0x1c000
	ds_read_b128 v[130:133], v0
	ds_read_b128 v[134:137], v0 offset:1024
	ds_read_b128 v[138:141], v0 offset:2048
	ds_read_b128 v[142:145], v0 offset:3072
	v_add_u32_e32 v0, s39, v244
	ds_read_b128 v[146:149], v0
	ds_read_b128 v[150:153], v0 offset:1024
	ds_read_b128 v[154:157], v0 offset:2048
	ds_read_b128 v[158:161], v0 offset:3072
	s_add_u32 s28, s28, s48
	s_addc_u32 s29, s29, s49
	s_mov_b32 m0, s34
	v_lshl_add_u64 v[230:231], s[28:29], 0, v[212:213]
	ds_read_b128 v[162:165], v246 offset:32768
	ds_read_b128 v[166:169], v246 offset:33792
	ds_read_b128 v[170:173], v246 offset:34816
	ds_read_b128 v[174:177], v246 offset:35840
	ds_read_b128 v[178:181], v246 offset:36864
	ds_read_b128 v[182:185], v246 offset:37888
	ds_read_b128 v[186:189], v246 offset:38912
	ds_read_b128 v[190:193], v246 offset:39936
	global_load_lds_dwordx4 v[230:231], off
	s_mov_b32 m0, s35
	v_lshl_add_u64 v[230:231], s[28:29], 0, v[208:209]
	global_load_lds_dwordx4 v[230:231], off
	s_waitcnt vmcnt(8)
	s_waitcnt lgkmcnt(0)
	s_barrier
	s_setprio 1
	s_waitcnt lgkmcnt(0)
	v_mfma_f32_16x16x32_bf16 v[126:129], v[130:133], v[162:165], v[126:129]
	v_mfma_f32_16x16x32_bf16 v[122:125], v[138:141], v[162:165], v[122:125]
	v_mfma_f32_16x16x32_bf16 v[110:113], v[130:133], v[170:173], v[110:113]
	v_mfma_f32_16x16x32_bf16 v[106:109], v[138:141], v[170:173], v[106:109]
	v_mfma_f32_16x16x32_bf16 v[102:105], v[130:133], v[178:181], v[102:105]
	v_mfma_f32_16x16x32_bf16 v[98:101], v[138:141], v[178:181], v[98:101]
	v_mfma_f32_16x16x32_bf16 v[94:97], v[130:133], v[186:189], v[94:97]
	v_mfma_f32_16x16x32_bf16 v[90:93], v[138:141], v[186:189], v[90:93]
	v_mfma_f32_16x16x32_bf16 v[126:129], v[134:137], v[166:169], v[126:129]
	v_mfma_f32_16x16x32_bf16 v[122:125], v[142:145], v[166:169], v[122:125]
	v_mfma_f32_16x16x32_bf16 v[110:113], v[134:137], v[174:177], v[110:113]
	v_mfma_f32_16x16x32_bf16 v[106:109], v[142:145], v[174:177], v[106:109]
	v_mfma_f32_16x16x32_bf16 v[102:105], v[134:137], v[182:185], v[102:105]
	v_mfma_f32_16x16x32_bf16 v[98:101], v[142:145], v[182:185], v[98:101]
	v_mfma_f32_16x16x32_bf16 v[94:97], v[134:137], v[190:193], v[94:97]
	v_mfma_f32_16x16x32_bf16 v[90:93], v[142:145], v[190:193], v[90:93]
	s_setprio 0
	s_setprio 1
	v_mfma_f32_16x16x32_bf16 v[118:121], v[146:149], v[162:165], v[118:121]
	v_mfma_f32_16x16x32_bf16 v[114:117], v[154:157], v[162:165], v[114:117]
	v_mfma_f32_16x16x32_bf16 v[86:89], v[146:149], v[170:173], v[86:89]
	v_mfma_f32_16x16x32_bf16 v[82:85], v[154:157], v[170:173], v[82:85]
	v_mfma_f32_16x16x32_bf16 v[78:81], v[146:149], v[178:181], v[78:81]
	v_mfma_f32_16x16x32_bf16 v[74:77], v[154:157], v[178:181], v[74:77]
	v_mfma_f32_16x16x32_bf16 v[70:73], v[146:149], v[186:189], v[70:73]
	v_mfma_f32_16x16x32_bf16 v[66:69], v[154:157], v[186:189], v[66:69]
	v_mfma_f32_16x16x32_bf16 v[118:121], v[150:153], v[166:169], v[118:121]
	v_mfma_f32_16x16x32_bf16 v[114:117], v[158:161], v[166:169], v[114:117]
	v_mfma_f32_16x16x32_bf16 v[86:89], v[150:153], v[174:177], v[86:89]
	v_mfma_f32_16x16x32_bf16 v[82:85], v[158:161], v[174:177], v[82:85]
	v_mfma_f32_16x16x32_bf16 v[78:81], v[150:153], v[182:185], v[78:81]
	v_mfma_f32_16x16x32_bf16 v[74:77], v[158:161], v[182:185], v[74:77]
	v_mfma_f32_16x16x32_bf16 v[70:73], v[150:153], v[190:193], v[70:73]
	v_mfma_f32_16x16x32_bf16 v[66:69], v[158:161], v[190:193], v[66:69]
	s_setprio 0
	s_barrier
; #define PG8_STAGE(bufoff, gbase, voff) do { _Pragma("unroll") for (int _i = 0; _i < 2; ++_i) \
;         __builtin_amdgcn_global_load_lds((const unsigned*)((const char*)(gbase) + (voff)[_i]), (LAS unsigned*)(lds + (bufoff) + ldsw + _i * 8192), 16, 0, 0); } while (0)
; #define PG8_LDA(dst, b, h) do { _Pragma("unroll") for (int m = 0; m < 4; ++m) _Pragma("unroll") for (int k = 0; k < 2; ++k) dst[m][k] = *(const LAS bf16x8*)(lds + PG8_SA(b, h) + aoff + m * 2048 + k * 1024); } while (0)
; #define PG8_MMA(ai, bj, At, Bt) do { __builtin_amdgcn_s_setprio(1); _Pragma("unroll") for (int m = 0; m < 4; ++m) _Pragma("unroll") for (int n = 0; n < 2; ++n) _Pragma("unroll") for (int k = 0; k < 2; ++k) \
;         acc[ai][bj][m][n] = __builtin_amdgcn_mfma_f32_16x16x32_bf16(Bt[n][k], At[m][k], acc[ai][bj][m][n], 0, 0, 0); __builtin_amdgcn_s_setprio(0); } while (0)
; #define PG8_WAIT_V(n) asm volatile("s_waitcnt vmcnt(" #n ")" ::: "memory")
; #define PG8_WAIT_L(n) asm volatile("s_waitcnt lgkmcnt(" #n ")" ::: "memory")
; #define PG8_BAR __builtin_amdgcn_s_barrier()
; #define PG8_SCHED __builtin_amdgcn_sched_barrier(0)
; template <class Epi, class Sched>
; __device__ __forceinline__ void gemm_phase(LAS unsigned char* lds, const Gemm g, const Sched& S, const Epi& E) {
;     ...
;             PG8_LDA(At, 1, 1); PG8_STAGE(PG8_SB(1, 0), b3, voffB); PG8_STAGE(PG8_SB(1, 1), b3 + hstep, voffB); PG8_STAGE(PG8_SA(1, 0), a3, voffA);
;             PG8_WAIT_V(8); PG8_WAIT_L(0); PG8_BAR; PG8_MMA(1, 0, At, B0); PG8_MMA(1, 1, At, B1); PG8_BAR; PG8_SCHED;
;         }
	s_add_i32 s26, s26, s12
	v_lshl_add_u64 v[218:219], v[218:219], 0, s[18:19]
	s_mov_b32 m0, s26
	ds_read_b128 v[162:165], v246 offset:49152
	ds_read_b128 v[166:169], v246 offset:50176
	ds_read_b128 v[170:173], v246 offset:51200
	ds_read_b128 v[174:177], v246 offset:52224
	ds_read_b128 v[178:181], v246 offset:53248
	ds_read_b128 v[182:185], v246 offset:54272
	ds_read_b128 v[186:189], v246 offset:55296
	ds_read_b128 v[190:193], v246 offset:56320
	global_load_lds_dwordx4 v[218:219], off
	v_lshl_add_u64 v[218:219], v[220:221], 0, s[18:19]
	s_add_i32 m0, s26, 0x2000
	s_add_i32 s26, s39, s12
	global_load_lds_dwordx4 v[218:219], off
	s_mov_b32 m0, s26
	v_lshl_add_u64 v[218:219], v[222:223], 0, s[18:19]
	global_load_lds_dwordx4 v[218:219], off
	s_add_i32 m0, s26, 0x2000
	v_lshl_add_u64 v[218:219], v[224:225], 0, s[18:19]
	global_load_lds_dwordx4 v[218:219], off
	s_mov_b32 m0, s31
	v_lshl_add_u64 v[218:219], v[226:227], 0, s[18:19]
	global_load_lds_dwordx4 v[218:219], off
	s_mov_b32 m0, s80
	v_lshl_add_u64 v[218:219], v[228:229], 0, s[18:19]
	global_load_lds_dwordx4 v[218:219], off
	s_waitcnt vmcnt(8)
	s_waitcnt lgkmcnt(0)
	s_barrier
	s_setprio 1
	s_waitcnt lgkmcnt(0)
	v_mfma_f32_16x16x32_bf16 v[62:65], v[130:133], v[162:165], v[62:65]
	v_mfma_f32_16x16x32_bf16 v[58:61], v[138:141], v[162:165], v[58:61]
	v_mfma_f32_16x16x32_bf16 v[46:49], v[130:133], v[170:173], v[46:49]
	v_mfma_f32_16x16x32_bf16 v[42:45], v[138:141], v[170:173], v[42:45]
	v_mfma_f32_16x16x32_bf16 v[30:33], v[130:133], v[178:181], v[30:33]
	v_mfma_f32_16x16x32_bf16 v[26:29], v[138:141], v[178:181], v[26:29]
	v_mfma_f32_16x16x32_bf16 v[14:17], v[130:133], v[186:189], v[14:17]
	v_mfma_f32_16x16x32_bf16 v[10:13], v[138:141], v[186:189], v[10:13]
	v_mfma_f32_16x16x32_bf16 v[62:65], v[134:137], v[166:169], v[62:65]
	v_mfma_f32_16x16x32_bf16 v[58:61], v[142:145], v[166:169], v[58:61]
	v_mfma_f32_16x16x32_bf16 v[46:49], v[134:137], v[174:177], v[46:49]
	v_mfma_f32_16x16x32_bf16 v[42:45], v[142:145], v[174:177], v[42:45]
	v_mfma_f32_16x16x32_bf16 v[30:33], v[134:137], v[182:185], v[30:33]
	v_mfma_f32_16x16x32_bf16 v[26:29], v[142:145], v[182:185], v[26:29]
	v_mfma_f32_16x16x32_bf16 v[14:17], v[134:137], v[190:193], v[14:17]
	v_mfma_f32_16x16x32_bf16 v[10:13], v[142:145], v[190:193], v[10:13]
	s_setprio 0
	s_setprio 1
	v_mfma_f32_16x16x32_bf16 v[54:57], v[146:149], v[162:165], v[54:57]
	v_mfma_f32_16x16x32_bf16 v[50:53], v[154:157], v[162:165], v[50:53]
	v_mfma_f32_16x16x32_bf16 v[38:41], v[146:149], v[170:173], v[38:41]
	v_mfma_f32_16x16x32_bf16 v[34:37], v[154:157], v[170:173], v[34:37]
	v_mfma_f32_16x16x32_bf16 v[22:25], v[146:149], v[178:181], v[22:25]
	v_mfma_f32_16x16x32_bf16 v[18:21], v[154:157], v[178:181], v[18:21]
	v_mfma_f32_16x16x32_bf16 v[6:9], v[146:149], v[186:189], v[6:9]
	v_mfma_f32_16x16x32_bf16 v[2:5], v[154:157], v[186:189], v[2:5]
	v_mfma_f32_16x16x32_bf16 v[54:57], v[150:153], v[166:169], v[54:57]
	v_mfma_f32_16x16x32_bf16 v[50:53], v[158:161], v[166:169], v[50:53]
	v_mfma_f32_16x16x32_bf16 v[38:41], v[150:153], v[174:177], v[38:41]
	v_mfma_f32_16x16x32_bf16 v[34:37], v[158:161], v[174:177], v[34:37]
	v_mfma_f32_16x16x32_bf16 v[22:25], v[150:153], v[182:185], v[22:25]
	v_mfma_f32_16x16x32_bf16 v[18:21], v[158:161], v[182:185], v[18:21]
	v_mfma_f32_16x16x32_bf16 v[6:9], v[150:153], v[190:193], v[6:9]
	v_mfma_f32_16x16x32_bf16 v[2:5], v[158:161], v[190:193], v[2:5]
	s_setprio 0
	s_barrier
	s_add_u32 s15, s15, 0x100
	s_addc_u32 s16, s16, 0
	s_add_u32 s0, s0, 0x100
	s_addc_u32 s1, s1, 0
	s_cmp_ge_i32 s38, s30
	s_mov_b32 s28, s38
	s_cbranch_scc0 .LBB0_1556

; #define PG8_STAGE(bufoff, gbase, voff) do { _Pragma("unroll") for (int _i = 0; _i < 2; ++_i) \
;         __builtin_amdgcn_global_load_lds((const unsigned*)((const char*)(gbase) + (voff)[_i]), (LAS unsigned*)(lds + (bufoff) + ldsw + _i * 8192), 16, 0, 0); } while (0)
; #define PG8_LDA(dst, b, h) do { _Pragma("unroll") for (int m = 0; m < 4; ++m) _Pragma("unroll") for (int k = 0; k < 2; ++k) dst[m][k] = *(const LAS bf16x8*)(lds + PG8_SA(b, h) + aoff + m * 2048 + k * 1024); } while (0)
; #define PG8_LDB(dst, b, h) do { _Pragma("unroll") for (int n = 0; n < 2; ++n) _Pragma("unroll") for (int k = 0; k < 2; ++k) dst[n][k] = *(const LAS bf16x8*)(lds + PG8_SB(b, h) + boff + n * 2048 + k * 1024); } while (0)
; #define PG8_MMA(ai, bj, At, Bt) do { __builtin_amdgcn_s_setprio(1); _Pragma("unroll") for (int m = 0; m < 4; ++m) _Pragma("unroll") for (int n = 0; n < 2; ++n) _Pragma("unroll") for (int k = 0; k < 2; ++k) \
;         acc[ai][bj][m][n] = __builtin_amdgcn_mfma_f32_16x16x32_bf16(Bt[n][k], At[m][k], acc[ai][bj][m][n], 0, 0, 0); __builtin_amdgcn_s_setprio(0); } while (0)
; #define PG8_WAIT_V(n) asm volatile("s_waitcnt vmcnt(" #n ")" ::: "memory")
; #define PG8_WAIT_L(n) asm volatile("s_waitcnt lgkmcnt(" #n ")" ::: "memory")
; #define PG8_BAR __builtin_amdgcn_s_barrier()
; #define PG8_SCHED __builtin_amdgcn_sched_barrier(0)
; template <class Epi, class Sched>
; __device__ __forceinline__ void gemm_phase(LAS unsigned char* lds, const Gemm g, const Sched& S, const Epi& E) {
;     ...
;             PG8_LDB(B0, 0, 0); PG8_LDB(B1, 0, 1); PG8_SCHED; PG8_LDA(At, 0, 0); PG8_STAGE(PG8_SA(1, 1), a1 + hstep, voffA);
;             PG8_WAIT_V(8); PG8_WAIT_L(0); PG8_BAR; PG8_MMA(0, 0, At, B0); PG8_MMA(0, 1, At, B1); PG8_BAR; PG8_SCHED;
;             PG8_LDA(At, 0, 1); PG8_STAGE(PG8_SB(0, 0), b2, voffB); PG8_STAGE(PG8_SB(0, 1), b2 + hstep, voffB); PG8_STAGE(PG8_SA(0, 0), a2, voffA);
;             PG8_WAIT_V(8); PG8_WAIT_L(0); PG8_BAR; PG8_MMA(1, 0, At, B0); PG8_MMA(1, 1, At, B1); PG8_BAR; PG8_SCHED;
.LBB0_1776:
	ds_read_b128 v[130:133], v235
	ds_read_b128 v[134:137], v235 offset:1024
	ds_read_b128 v[138:141], v235 offset:2048
	ds_read_b128 v[142:145], v235 offset:3072
	ds_read_b128 v[146:149], v238
	ds_read_b128 v[150:153], v238 offset:1024
	ds_read_b128 v[154:157], v238 offset:2048
	ds_read_b128 v[158:161], v238 offset:3072
	ds_read_b128 v[162:165], v219
	ds_read_b128 v[166:169], v219 offset:1024
	ds_read_b128 v[170:173], v219 offset:2048
	ds_read_b128 v[174:177], v219 offset:3072
	ds_read_b128 v[178:181], v219 offset:4096
	ds_read_b128 v[182:185], v219 offset:5120
	ds_read_b128 v[186:189], v219 offset:6144
	ds_read_b128 v[212:215], v219 offset:7168
	s_add_i32 s38, s28, 2
	s_add_u32 s26, s0, 0x80
	s_addc_u32 s29, s1, 0
	s_add_i32 s39, 0, 0x10000
	s_cmp_eq_u32 s88, s28
	s_cselect_b32 s29, s49, s29
	s_cselect_b32 s28, s48, s26
	s_cselect_b32 s93, s67, s16
	s_cselect_b32 s92, s66, s15
	s_add_i32 s26, 0, 0x14000
	s_add_i32 m0, s13, 0xc000
	v_lshl_add_u64 v[202:203], s[0:1], 0, v[210:211]
	global_load_lds_dwordx4 v[202:203], off
	s_add_i32 m0, s13, 0xe000
	v_lshl_add_u64 v[202:203], s[0:1], 0, v[208:209]
	global_load_lds_dwordx4 v[202:203], off
	s_waitcnt vmcnt(8)
	s_waitcnt lgkmcnt(0)
	s_barrier
	s_setprio 1
	s_waitcnt lgkmcnt(0)
	v_mfma_f32_16x16x32_bf16 v[122:125], v[130:133], v[162:165], v[122:125]
	v_mfma_f32_16x16x32_bf16 v[126:129], v[138:141], v[162:165], v[126:129]
	v_mfma_f32_16x16x32_bf16 v[110:113], v[130:133], v[170:173], v[110:113]
	v_mfma_f32_16x16x32_bf16 v[106:109], v[138:141], v[170:173], v[106:109]
	v_mfma_f32_16x16x32_bf16 v[94:97], v[130:133], v[178:181], v[94:97]
	v_mfma_f32_16x16x32_bf16 v[90:93], v[138:141], v[178:181], v[90:93]
	v_mfma_f32_16x16x32_bf16 v[78:81], v[130:133], v[186:189], v[78:81]
	v_mfma_f32_16x16x32_bf16 v[74:77], v[138:141], v[186:189], v[74:77]
	v_mfma_f32_16x16x32_bf16 v[122:125], v[134:137], v[166:169], v[122:125]
	v_mfma_f32_16x16x32_bf16 v[126:129], v[142:145], v[166:169], v[126:129]
	v_mfma_f32_16x16x32_bf16 v[110:113], v[134:137], v[174:177], v[110:113]
	v_mfma_f32_16x16x32_bf16 v[106:109], v[142:145], v[174:177], v[106:109]
	v_mfma_f32_16x16x32_bf16 v[94:97], v[134:137], v[182:185], v[94:97]
	v_mfma_f32_16x16x32_bf16 v[90:93], v[142:145], v[182:185], v[90:93]
	v_mfma_f32_16x16x32_bf16 v[78:81], v[134:137], v[212:215], v[78:81]
	v_mfma_f32_16x16x32_bf16 v[74:77], v[142:145], v[212:215], v[74:77]
	s_setprio 0
	s_setprio 1
	v_mfma_f32_16x16x32_bf16 v[118:121], v[146:149], v[162:165], v[118:121]
	v_mfma_f32_16x16x32_bf16 v[114:117], v[154:157], v[162:165], v[114:117]
	v_mfma_f32_16x16x32_bf16 v[102:105], v[146:149], v[170:173], v[102:105]
	v_mfma_f32_16x16x32_bf16 v[98:101], v[154:157], v[170:173], v[98:101]
	v_mfma_f32_16x16x32_bf16 v[86:89], v[146:149], v[178:181], v[86:89]
	v_mfma_f32_16x16x32_bf16 v[82:85], v[154:157], v[178:181], v[82:85]
	v_mfma_f32_16x16x32_bf16 v[70:73], v[146:149], v[186:189], v[70:73]
	v_mfma_f32_16x16x32_bf16 v[66:69], v[154:157], v[186:189], v[66:69]
	v_mfma_f32_16x16x32_bf16 v[118:121], v[150:153], v[166:169], v[118:121]
	v_mfma_f32_16x16x32_bf16 v[114:117], v[158:161], v[166:169], v[114:117]
	v_mfma_f32_16x16x32_bf16 v[102:105], v[150:153], v[174:177], v[102:105]
	v_mfma_f32_16x16x32_bf16 v[98:101], v[158:161], v[174:177], v[98:101]
	v_mfma_f32_16x16x32_bf16 v[86:89], v[150:153], v[182:185], v[86:89]
	v_mfma_f32_16x16x32_bf16 v[82:85], v[158:161], v[182:185], v[82:85]
	v_mfma_f32_16x16x32_bf16 v[70:73], v[150:153], v[212:215], v[70:73]
	v_mfma_f32_16x16x32_bf16 v[66:69], v[158:161], v[212:215], v[66:69]
	s_setprio 0
	s_barrier
	s_add_i32 s39, s39, s12
	v_lshl_add_u64 v[202:203], s[92:93], 0, v[0:1]
	s_mov_b32 m0, s39
	ds_read_b128 v[162:165], v219 offset:16384
	ds_read_b128 v[166:169], v219 offset:17408
	ds_read_b128 v[170:173], v219 offset:18432
	ds_read_b128 v[174:177], v219 offset:19456
	ds_read_b128 v[178:181], v219 offset:20480
	ds_read_b128 v[182:185], v219 offset:21504
	ds_read_b128 v[186:189], v219 offset:22528
	ds_read_b128 v[212:215], v219 offset:23552
	global_load_lds_dwordx4 v[202:203], off
	s_add_i32 m0, s39, 0x2000
	v_lshl_add_u64 v[220:221], s[92:93], 0, v[190:191]
	s_add_u32 s92, s92, s56
	s_addc_u32 s93, s93, s57
	s_add_i32 s26, s26, s12
	global_load_lds_dwordx4 v[220:221], off
	v_lshl_add_u64 v[222:223], s[92:93], 0, v[0:1]
	s_mov_b32 m0, s26
	v_lshl_add_u64 v[224:225], s[92:93], 0, v[190:191]
	global_load_lds_dwordx4 v[222:223], off
	s_add_i32 m0, s26, 0x2000
	v_lshl_add_u64 v[226:227], s[28:29], 0, v[206:207]
	global_load_lds_dwordx4 v[224:225], off
	s_mov_b32 m0, s13
	v_lshl_add_u64 v[228:229], s[28:29], 0, v[192:193]
	global_load_lds_dwordx4 v[226:227], off
	s_mov_b32 m0, s27
	s_nop 0
	global_load_lds_dwordx4 v[228:229], off
	s_waitcnt vmcnt(8)
	s_waitcnt lgkmcnt(0)
	s_barrier
; #define PG8_STAGE(bufoff, gbase, voff) do { _Pragma("unroll") for (int _i = 0; _i < 2; ++_i) \
;         __builtin_amdgcn_global_load_lds((const unsigned*)((const char*)(gbase) + (voff)[_i]), (LAS unsigned*)(lds + (bufoff) + ldsw + _i * 8192), 16, 0, 0); } while (0)
; #define PG8_LDA(dst, b, h) do { _Pragma("unroll") for (int m = 0; m < 4; ++m) _Pragma("unroll") for (int k = 0; k < 2; ++k) dst[m][k] = *(const LAS bf16x8*)(lds + PG8_SA(b, h) + aoff + m * 2048 + k * 1024); } while (0)
; #define PG8_LDB(dst, b, h) do { _Pragma("unroll") for (int n = 0; n < 2; ++n) _Pragma("unroll") for (int k = 0; k < 2; ++k) dst[n][k] = *(const LAS bf16x8*)(lds + PG8_SB(b, h) + boff + n * 2048 + k * 1024); } while (0)
; #define PG8_MMA(ai, bj, At, Bt) do { __builtin_amdgcn_s_setprio(1); _Pragma("unroll") for (int m = 0; m < 4; ++m) _Pragma("unroll") for (int n = 0; n < 2; ++n) _Pragma("unroll") for (int k = 0; k < 2; ++k) \
;         acc[ai][bj][m][n] = __builtin_amdgcn_mfma_f32_16x16x32_bf16(Bt[n][k], At[m][k], acc[ai][bj][m][n], 0, 0, 0); __builtin_amdgcn_s_setprio(0); } while (0)
; #define PG8_WAIT_V(n) asm volatile("s_waitcnt vmcnt(" #n ")" ::: "memory")
; #define PG8_WAIT_L(n) asm volatile("s_waitcnt lgkmcnt(" #n ")" ::: "memory")
; #define PG8_BAR __builtin_amdgcn_s_barrier()
; #define PG8_SCHED __builtin_amdgcn_sched_barrier(0)
; template <class Epi, class Sched>
; __device__ __forceinline__ void gemm_phase(LAS unsigned char* lds, const Gemm g, const Sched& S, const Epi& E) {
;     ...
;             PG8_WAIT_V(8); PG8_WAIT_L(0); PG8_BAR; PG8_MMA(1, 0, At, B0); PG8_MMA(1, 1, At, B1); PG8_BAR; PG8_SCHED;
;             PG8_LDB(B0, 1, 0); PG8_LDB(B1, 1, 1); PG8_SCHED; PG8_LDA(At, 1, 0); PG8_STAGE(PG8_SA(0, 1), a2 + hstep, voffA);
;             PG8_WAIT_V(8); PG8_WAIT_L(0); PG8_BAR; PG8_MMA(0, 0, At, B0); PG8_MMA(0, 1, At, B1); PG8_BAR; PG8_SCHED;
	s_setprio 1
	s_waitcnt lgkmcnt(0)
	v_mfma_f32_16x16x32_bf16 v[62:65], v[130:133], v[162:165], v[62:65]
	v_mfma_f32_16x16x32_bf16 v[58:61], v[138:141], v[162:165], v[58:61]
	v_mfma_f32_16x16x32_bf16 v[46:49], v[130:133], v[170:173], v[46:49]
	v_mfma_f32_16x16x32_bf16 v[42:45], v[138:141], v[170:173], v[42:45]
	v_mfma_f32_16x16x32_bf16 v[30:33], v[130:133], v[178:181], v[30:33]
	v_mfma_f32_16x16x32_bf16 v[26:29], v[138:141], v[178:181], v[26:29]
	v_mfma_f32_16x16x32_bf16 v[14:17], v[130:133], v[186:189], v[14:17]
	v_mfma_f32_16x16x32_bf16 v[10:13], v[138:141], v[186:189], v[10:13]
	v_mfma_f32_16x16x32_bf16 v[62:65], v[134:137], v[166:169], v[62:65]
	v_mfma_f32_16x16x32_bf16 v[58:61], v[142:145], v[166:169], v[58:61]
	v_mfma_f32_16x16x32_bf16 v[46:49], v[134:137], v[174:177], v[46:49]
	v_mfma_f32_16x16x32_bf16 v[42:45], v[142:145], v[174:177], v[42:45]
	v_mfma_f32_16x16x32_bf16 v[30:33], v[134:137], v[182:185], v[30:33]
	v_mfma_f32_16x16x32_bf16 v[26:29], v[142:145], v[182:185], v[26:29]
	v_mfma_f32_16x16x32_bf16 v[14:17], v[134:137], v[212:215], v[14:17]
	v_mfma_f32_16x16x32_bf16 v[10:13], v[142:145], v[212:215], v[10:13]
	s_setprio 0
	s_setprio 1
	v_mfma_f32_16x16x32_bf16 v[54:57], v[146:149], v[162:165], v[54:57]
	v_mfma_f32_16x16x32_bf16 v[50:53], v[154:157], v[162:165], v[50:53]
	v_mfma_f32_16x16x32_bf16 v[38:41], v[146:149], v[170:173], v[38:41]
	v_mfma_f32_16x16x32_bf16 v[34:37], v[154:157], v[170:173], v[34:37]
	v_mfma_f32_16x16x32_bf16 v[22:25], v[146:149], v[178:181], v[22:25]
	v_mfma_f32_16x16x32_bf16 v[18:21], v[154:157], v[178:181], v[18:21]
	v_mfma_f32_16x16x32_bf16 v[6:9], v[146:149], v[186:189], v[6:9]
	v_mfma_f32_16x16x32_bf16 v[2:5], v[154:157], v[186:189], v[2:5]
	v_mfma_f32_16x16x32_bf16 v[54:57], v[150:153], v[166:169], v[54:57]
	v_mfma_f32_16x16x32_bf16 v[50:53], v[158:161], v[166:169], v[50:53]
	v_mfma_f32_16x16x32_bf16 v[38:41], v[150:153], v[174:177], v[38:41]
	v_mfma_f32_16x16x32_bf16 v[34:37], v[158:161], v[174:177], v[34:37]
	v_mfma_f32_16x16x32_bf16 v[22:25], v[150:153], v[182:185], v[22:25]
	v_mfma_f32_16x16x32_bf16 v[18:21], v[158:161], v[182:185], v[18:21]
	v_mfma_f32_16x16x32_bf16 v[6:9], v[150:153], v[212:215], v[6:9]
	v_mfma_f32_16x16x32_bf16 v[2:5], v[158:161], v[212:215], v[2:5]
	s_setprio 0
	s_barrier
	ds_read_b128 v[130:133], v239
	ds_read_b128 v[134:137], v239 offset:1024
	ds_read_b128 v[138:141], v239 offset:2048
	ds_read_b128 v[142:145], v239 offset:3072
	ds_read_b128 v[146:149], v250
	ds_read_b128 v[150:153], v250 offset:1024
	ds_read_b128 v[154:157], v250 offset:2048
	ds_read_b128 v[158:161], v250 offset:3072
	s_add_i32 s26, 0, 0x18000
	s_add_i32 s39, 0, 0x1c000
	s_add_u32 s28, s28, s56
	s_addc_u32 s29, s29, s57
	s_mov_b32 m0, s34
	v_lshl_add_u64 v[230:231], s[28:29], 0, v[206:207]
	ds_read_b128 v[162:165], v219 offset:32768
	ds_read_b128 v[166:169], v219 offset:33792
	ds_read_b128 v[170:173], v219 offset:34816
	ds_read_b128 v[174:177], v219 offset:35840
	ds_read_b128 v[178:181], v219 offset:36864
	ds_read_b128 v[182:185], v219 offset:37888
	ds_read_b128 v[186:189], v219 offset:38912
	ds_read_b128 v[212:215], v219 offset:39936
	global_load_lds_dwordx4 v[230:231], off
	s_mov_b32 m0, s35
	v_lshl_add_u64 v[230:231], s[28:29], 0, v[192:193]
	global_load_lds_dwordx4 v[230:231], off
	s_waitcnt vmcnt(8)
	s_waitcnt lgkmcnt(0)
	s_barrier
	s_setprio 1
	s_waitcnt lgkmcnt(0)
	v_mfma_f32_16x16x32_bf16 v[122:125], v[130:133], v[162:165], v[122:125]
	v_mfma_f32_16x16x32_bf16 v[126:129], v[138:141], v[162:165], v[126:129]
	v_mfma_f32_16x16x32_bf16 v[110:113], v[130:133], v[170:173], v[110:113]
	v_mfma_f32_16x16x32_bf16 v[106:109], v[138:141], v[170:173], v[106:109]
	v_mfma_f32_16x16x32_bf16 v[94:97], v[130:133], v[178:181], v[94:97]
	v_mfma_f32_16x16x32_bf16 v[90:93], v[138:141], v[178:181], v[90:93]
	v_mfma_f32_16x16x32_bf16 v[78:81], v[130:133], v[186:189], v[78:81]
	v_mfma_f32_16x16x32_bf16 v[74:77], v[138:141], v[186:189], v[74:77]
	v_mfma_f32_16x16x32_bf16 v[122:125], v[134:137], v[166:169], v[122:125]
	v_mfma_f32_16x16x32_bf16 v[126:129], v[142:145], v[166:169], v[126:129]
	v_mfma_f32_16x16x32_bf16 v[110:113], v[134:137], v[174:177], v[110:113]
	v_mfma_f32_16x16x32_bf16 v[106:109], v[142:145], v[174:177], v[106:109]
	v_mfma_f32_16x16x32_bf16 v[94:97], v[134:137], v[182:185], v[94:97]
	v_mfma_f32_16x16x32_bf16 v[90:93], v[142:145], v[182:185], v[90:93]
	v_mfma_f32_16x16x32_bf16 v[78:81], v[134:137], v[212:215], v[78:81]
	v_mfma_f32_16x16x32_bf16 v[74:77], v[142:145], v[212:215], v[74:77]
	s_setprio 0
	s_setprio 1
	v_mfma_f32_16x16x32_bf16 v[118:121], v[146:149], v[162:165], v[118:121]
	v_mfma_f32_16x16x32_bf16 v[114:117], v[154:157], v[162:165], v[114:117]
	v_mfma_f32_16x16x32_bf16 v[102:105], v[146:149], v[170:173], v[102:105]
	v_mfma_f32_16x16x32_bf16 v[98:101], v[154:157], v[170:173], v[98:101]
	v_mfma_f32_16x16x32_bf16 v[86:89], v[146:149], v[178:181], v[86:89]
	v_mfma_f32_16x16x32_bf16 v[82:85], v[154:157], v[178:181], v[82:85]
	v_mfma_f32_16x16x32_bf16 v[70:73], v[146:149], v[186:189], v[70:73]
	v_mfma_f32_16x16x32_bf16 v[66:69], v[154:157], v[186:189], v[66:69]
	v_mfma_f32_16x16x32_bf16 v[118:121], v[150:153], v[166:169], v[118:121]
	v_mfma_f32_16x16x32_bf16 v[114:117], v[158:161], v[166:169], v[114:117]
	v_mfma_f32_16x16x32_bf16 v[102:105], v[150:153], v[174:177], v[102:105]
	v_mfma_f32_16x16x32_bf16 v[98:101], v[158:161], v[174:177], v[98:101]
	v_mfma_f32_16x16x32_bf16 v[86:89], v[150:153], v[182:185], v[86:89]
	v_mfma_f32_16x16x32_bf16 v[82:85], v[158:161], v[182:185], v[82:85]
	v_mfma_f32_16x16x32_bf16 v[70:73], v[150:153], v[212:215], v[70:73]
	v_mfma_f32_16x16x32_bf16 v[66:69], v[158:161], v[212:215], v[66:69]
	s_setprio 0
	s_barrier
; #define PG8_STAGE(bufoff, gbase, voff) do { _Pragma("unroll") for (int _i = 0; _i < 2; ++_i) \
;         __builtin_amdgcn_global_load_lds((const unsigned*)((const char*)(gbase) + (voff)[_i]), (LAS unsigned*)(lds + (bufoff) + ldsw + _i * 8192), 16, 0, 0); } while (0)
; #define PG8_LDA(dst, b, h) do { _Pragma("unroll") for (int m = 0; m < 4; ++m) _Pragma("unroll") for (int k = 0; k < 2; ++k) dst[m][k] = *(const LAS bf16x8*)(lds + PG8_SA(b, h) + aoff + m * 2048 + k * 1024); } while (0)
; #define PG8_MMA(ai, bj, At, Bt) do { __builtin_amdgcn_s_setprio(1); _Pragma("unroll") for (int m = 0; m < 4; ++m) _Pragma("unroll") for (int n = 0; n < 2; ++n) _Pragma("unroll") for (int k = 0; k < 2; ++k) \
;         acc[ai][bj][m][n] = __builtin_amdgcn_mfma_f32_16x16x32_bf16(Bt[n][k], At[m][k], acc[ai][bj][m][n], 0, 0, 0); __builtin_amdgcn_s_setprio(0); } while (0)
; #define PG8_WAIT_V(n) asm volatile("s_waitcnt vmcnt(" #n ")" ::: "memory")
; #define PG8_WAIT_L(n) asm volatile("s_waitcnt lgkmcnt(" #n ")" ::: "memory")
; #define PG8_BAR __builtin_amdgcn_s_barrier()
; #define PG8_SCHED __builtin_amdgcn_sched_barrier(0)
; template <class Epi, class Sched>
; __device__ __forceinline__ void gemm_phase(LAS unsigned char* lds, const Gemm g, const Sched& S, const Epi& E) {
;     ...
;             PG8_LDA(At, 1, 1); PG8_STAGE(PG8_SB(1, 0), b3, voffB); PG8_STAGE(PG8_SB(1, 1), b3 + hstep, voffB); PG8_STAGE(PG8_SA(1, 0), a3, voffA);
;             PG8_WAIT_V(8); PG8_WAIT_L(0); PG8_BAR; PG8_MMA(1, 0, At, B0); PG8_MMA(1, 1, At, B1); PG8_BAR; PG8_SCHED;
;         }
	s_add_i32 s26, s26, s12
	v_lshl_add_u64 v[202:203], v[202:203], 0, s[18:19]
	s_mov_b32 m0, s26
	ds_read_b128 v[162:165], v219 offset:49152
	ds_read_b128 v[166:169], v219 offset:50176
	ds_read_b128 v[170:173], v219 offset:51200
	ds_read_b128 v[174:177], v219 offset:52224
	ds_read_b128 v[178:181], v219 offset:53248
	ds_read_b128 v[182:185], v219 offset:54272
	ds_read_b128 v[186:189], v219 offset:55296
	ds_read_b128 v[212:215], v219 offset:56320
	global_load_lds_dwordx4 v[202:203], off
	v_lshl_add_u64 v[202:203], v[220:221], 0, s[18:19]
	s_add_i32 m0, s26, 0x2000
	s_add_i32 s26, s39, s12
	global_load_lds_dwordx4 v[202:203], off
	s_mov_b32 m0, s26
	v_lshl_add_u64 v[202:203], v[222:223], 0, s[18:19]
	global_load_lds_dwordx4 v[202:203], off
	s_add_i32 m0, s26, 0x2000
	v_lshl_add_u64 v[202:203], v[224:225], 0, s[18:19]
	global_load_lds_dwordx4 v[202:203], off
	s_mov_b32 m0, s84
	v_lshl_add_u64 v[202:203], v[226:227], 0, s[18:19]
	global_load_lds_dwordx4 v[202:203], off
	s_mov_b32 m0, s85
	v_lshl_add_u64 v[202:203], v[228:229], 0, s[18:19]
	global_load_lds_dwordx4 v[202:203], off
	s_waitcnt vmcnt(8)
	s_waitcnt lgkmcnt(0)
	s_barrier
	s_setprio 1
	s_waitcnt lgkmcnt(0)
	v_mfma_f32_16x16x32_bf16 v[62:65], v[130:133], v[162:165], v[62:65]
	v_mfma_f32_16x16x32_bf16 v[58:61], v[138:141], v[162:165], v[58:61]
	v_mfma_f32_16x16x32_bf16 v[46:49], v[130:133], v[170:173], v[46:49]
	v_mfma_f32_16x16x32_bf16 v[42:45], v[138:141], v[170:173], v[42:45]
	v_mfma_f32_16x16x32_bf16 v[30:33], v[130:133], v[178:181], v[30:33]
	v_mfma_f32_16x16x32_bf16 v[26:29], v[138:141], v[178:181], v[26:29]
	v_mfma_f32_16x16x32_bf16 v[14:17], v[130:133], v[186:189], v[14:17]
	v_mfma_f32_16x16x32_bf16 v[10:13], v[138:141], v[186:189], v[10:13]
	v_mfma_f32_16x16x32_bf16 v[62:65], v[134:137], v[166:169], v[62:65]
	v_mfma_f32_16x16x32_bf16 v[58:61], v[142:145], v[166:169], v[58:61]
	v_mfma_f32_16x16x32_bf16 v[46:49], v[134:137], v[174:177], v[46:49]
	v_mfma_f32_16x16x32_bf16 v[42:45], v[142:145], v[174:177], v[42:45]
	v_mfma_f32_16x16x32_bf16 v[30:33], v[134:137], v[182:185], v[30:33]
	v_mfma_f32_16x16x32_bf16 v[26:29], v[142:145], v[182:185], v[26:29]
	v_mfma_f32_16x16x32_bf16 v[14:17], v[134:137], v[212:215], v[14:17]
	v_mfma_f32_16x16x32_bf16 v[10:13], v[142:145], v[212:215], v[10:13]
	s_setprio 0
	s_setprio 1
	v_mfma_f32_16x16x32_bf16 v[54:57], v[146:149], v[162:165], v[54:57]
	v_mfma_f32_16x16x32_bf16 v[50:53], v[154:157], v[162:165], v[50:53]
	v_mfma_f32_16x16x32_bf16 v[38:41], v[146:149], v[170:173], v[38:41]
	v_mfma_f32_16x16x32_bf16 v[34:37], v[154:157], v[170:173], v[34:37]
	v_mfma_f32_16x16x32_bf16 v[22:25], v[146:149], v[178:181], v[22:25]
	v_mfma_f32_16x16x32_bf16 v[18:21], v[154:157], v[178:181], v[18:21]
	v_mfma_f32_16x16x32_bf16 v[6:9], v[146:149], v[186:189], v[6:9]
	v_mfma_f32_16x16x32_bf16 v[2:5], v[154:157], v[186:189], v[2:5]
	v_mfma_f32_16x16x32_bf16 v[54:57], v[150:153], v[166:169], v[54:57]
	v_mfma_f32_16x16x32_bf16 v[50:53], v[158:161], v[166:169], v[50:53]
	v_mfma_f32_16x16x32_bf16 v[38:41], v[150:153], v[174:177], v[38:41]
	v_mfma_f32_16x16x32_bf16 v[34:37], v[158:161], v[174:177], v[34:37]
	v_mfma_f32_16x16x32_bf16 v[22:25], v[150:153], v[182:185], v[22:25]
	v_mfma_f32_16x16x32_bf16 v[18:21], v[158:161], v[182:185], v[18:21]
	v_mfma_f32_16x16x32_bf16 v[6:9], v[150:153], v[212:215], v[6:9]
	v_mfma_f32_16x16x32_bf16 v[2:5], v[158:161], v[212:215], v[2:5]
	s_setprio 0
	s_barrier
	s_add_u32 s15, s15, 0x100
	s_addc_u32 s16, s16, 0
	s_add_u32 s0, s0, 0x100
	s_addc_u32 s1, s1, 0
	s_cmp_ge_i32 s38, s31
	s_mov_b32 s28, s38
	s_cbranch_scc0 .LBB0_1776
	v_readlane_b32 s92, v255, 40
	v_readlane_b32 s93, v255, 41

; #define PG8_STAGE(bufoff, gbase, voff) do { _Pragma("unroll") for (int _i = 0; _i < 2; ++_i) \
;         __builtin_amdgcn_global_load_lds((const unsigned*)((const char*)(gbase) + (voff)[_i]), (LAS unsigned*)(lds + (bufoff) + ldsw + _i * 8192), 16, 0, 0); } while (0)
; #define PG8_LDA(dst, b, h) do { _Pragma("unroll") for (int m = 0; m < 4; ++m) _Pragma("unroll") for (int k = 0; k < 2; ++k) dst[m][k] = *(const LAS bf16x8*)(lds + PG8_SA(b, h) + aoff + m * 2048 + k * 1024); } while (0)
; #define PG8_LDB(dst, b, h) do { _Pragma("unroll") for (int n = 0; n < 2; ++n) _Pragma("unroll") for (int k = 0; k < 2; ++k) dst[n][k] = *(const LAS bf16x8*)(lds + PG8_SB(b, h) + boff + n * 2048 + k * 1024); } while (0)
; #define PG8_MMA(ai, bj, At, Bt) do { __builtin_amdgcn_s_setprio(1); _Pragma("unroll") for (int m = 0; m < 4; ++m) _Pragma("unroll") for (int n = 0; n < 2; ++n) _Pragma("unroll") for (int k = 0; k < 2; ++k) \
;         acc[ai][bj][m][n] = __builtin_amdgcn_mfma_f32_16x16x32_bf16(Bt[n][k], At[m][k], acc[ai][bj][m][n], 0, 0, 0); __builtin_amdgcn_s_setprio(0); } while (0)
; #define PG8_WAIT_V(n) asm volatile("s_waitcnt vmcnt(" #n ")" ::: "memory")
; #define PG8_WAIT_L(n) asm volatile("s_waitcnt lgkmcnt(" #n ")" ::: "memory")
; #define PG8_BAR __builtin_amdgcn_s_barrier()
; #define PG8_SCHED __builtin_amdgcn_sched_barrier(0)
; template <class Epi, class Sched>
; __device__ __forceinline__ void gemm_phase(LAS unsigned char* lds, const Gemm g, const Sched& S, const Epi& E) {
;     ...
;         for (int t = 0; t < nt; t += 2) {
;             const bool last = (t == nt - 2);
;             const char* a1 = cA + (size_t)(t + 1) * kstep;
;             const char* a2 = last ? nA : cA + (size_t)(t + 2) * kstep; const char* b2 = last ? nB : cB + (size_t)(t + 2) * kstep;
;             const char* a3 = a2 + kstep; const char* b3 = b2 + kstep;
;             PG8_LDB(B0, 0, 0); PG8_LDB(B1, 0, 1); PG8_SCHED; PG8_LDA(At, 0, 0); PG8_STAGE(PG8_SA(1, 1), a1 + hstep, voffA);
;             PG8_WAIT_V(8); PG8_WAIT_L(0); PG8_BAR; PG8_MMA(0, 0, At, B0); PG8_MMA(0, 1, At, B1); PG8_BAR; PG8_SCHED;
;             PG8_LDA(At, 0, 1); PG8_STAGE(PG8_SB(0, 0), b2, voffB); PG8_STAGE(PG8_SB(0, 1), b2 + hstep, voffB); PG8_STAGE(PG8_SA(0, 0), a2, voffA);
.LBB0_1908:
	ds_read_b128 v[130:133], v235
	ds_read_b128 v[134:137], v235 offset:1024
	ds_read_b128 v[138:141], v235 offset:2048
	ds_read_b128 v[142:145], v235 offset:3072
	ds_read_b128 v[146:149], v238
	ds_read_b128 v[150:153], v238 offset:1024
	ds_read_b128 v[166:169], v238 offset:2048
	ds_read_b128 v[170:173], v238 offset:3072
	ds_read_b128 v[174:177], v187
	ds_read_b128 v[178:181], v187 offset:1024
	ds_read_b128 v[188:191], v187 offset:2048
	ds_read_b128 v[206:209], v187 offset:3072
	ds_read_b128 v[210:213], v187 offset:4096
	ds_read_b128 v[214:217], v187 offset:5120
	ds_read_b128 v[218:221], v187 offset:6144
	ds_read_b128 v[222:225], v187 offset:7168
	s_add_i32 s38, s28, 2
	s_add_u32 s26, s0, 0x80
	s_addc_u32 s29, s1, 0
	s_add_i32 s39, 0, 0x10000
	s_cmp_eq_u32 s84, s28
	s_cselect_b32 s29, s65, s29
	s_cselect_b32 s28, s64, s26
	s_cselect_b32 s45, s67, s16
	s_cselect_b32 s44, s66, s15
	s_add_i32 s26, 0, 0x14000
	s_add_i32 m0, s13, 0xc000
	v_lshl_add_u64 v[182:183], s[0:1], 0, v[164:165]
	global_load_lds_dwordx4 v[182:183], off
	s_add_i32 m0, s13, 0xe000
	v_lshl_add_u64 v[182:183], s[0:1], 0, v[162:163]
	global_load_lds_dwordx4 v[182:183], off
	s_waitcnt vmcnt(8)
	s_waitcnt lgkmcnt(0)
	s_barrier
	s_setprio 1
	s_waitcnt lgkmcnt(0)
	v_mfma_f32_16x16x32_bf16 v[122:125], v[130:133], v[174:177], v[122:125]
	v_mfma_f32_16x16x32_bf16 v[114:117], v[138:141], v[174:177], v[114:117]
	v_mfma_f32_16x16x32_bf16 v[106:109], v[130:133], v[188:191], v[106:109]
	v_mfma_f32_16x16x32_bf16 v[98:101], v[138:141], v[188:191], v[98:101]
	v_mfma_f32_16x16x32_bf16 v[90:93], v[130:133], v[210:213], v[90:93]
	v_mfma_f32_16x16x32_bf16 v[82:85], v[138:141], v[210:213], v[82:85]
	v_mfma_f32_16x16x32_bf16 v[74:77], v[130:133], v[218:221], v[74:77]
	v_mfma_f32_16x16x32_bf16 v[66:69], v[138:141], v[218:221], v[66:69]
	v_mfma_f32_16x16x32_bf16 v[122:125], v[134:137], v[178:181], v[122:125]
	v_mfma_f32_16x16x32_bf16 v[114:117], v[142:145], v[178:181], v[114:117]
	v_mfma_f32_16x16x32_bf16 v[106:109], v[134:137], v[206:209], v[106:109]
	v_mfma_f32_16x16x32_bf16 v[98:101], v[142:145], v[206:209], v[98:101]
	v_mfma_f32_16x16x32_bf16 v[90:93], v[134:137], v[214:217], v[90:93]
	v_mfma_f32_16x16x32_bf16 v[82:85], v[142:145], v[214:217], v[82:85]
	v_mfma_f32_16x16x32_bf16 v[74:77], v[134:137], v[222:225], v[74:77]
	v_mfma_f32_16x16x32_bf16 v[66:69], v[142:145], v[222:225], v[66:69]
	s_setprio 0
	s_setprio 1
	v_mfma_f32_16x16x32_bf16 v[126:129], v[146:149], v[174:177], v[126:129]
	v_mfma_f32_16x16x32_bf16 v[118:121], v[166:169], v[174:177], v[118:121]
	v_mfma_f32_16x16x32_bf16 v[110:113], v[146:149], v[188:191], v[110:113]
	v_mfma_f32_16x16x32_bf16 v[102:105], v[166:169], v[188:191], v[102:105]
	v_mfma_f32_16x16x32_bf16 v[94:97], v[146:149], v[210:213], v[94:97]
	v_mfma_f32_16x16x32_bf16 v[86:89], v[166:169], v[210:213], v[86:89]
	v_mfma_f32_16x16x32_bf16 v[78:81], v[146:149], v[218:221], v[78:81]
	v_mfma_f32_16x16x32_bf16 v[70:73], v[166:169], v[218:221], v[70:73]
	v_mfma_f32_16x16x32_bf16 v[126:129], v[150:153], v[178:181], v[126:129]
	v_mfma_f32_16x16x32_bf16 v[118:121], v[170:173], v[178:181], v[118:121]
	v_mfma_f32_16x16x32_bf16 v[110:113], v[150:153], v[206:209], v[110:113]
	v_mfma_f32_16x16x32_bf16 v[102:105], v[170:173], v[206:209], v[102:105]
	v_mfma_f32_16x16x32_bf16 v[94:97], v[150:153], v[214:217], v[94:97]
	v_mfma_f32_16x16x32_bf16 v[86:89], v[170:173], v[214:217], v[86:89]
	v_mfma_f32_16x16x32_bf16 v[78:81], v[150:153], v[222:225], v[78:81]
	v_mfma_f32_16x16x32_bf16 v[70:73], v[170:173], v[222:225], v[70:73]
	s_setprio 0
	s_barrier
	s_add_i32 s39, s39, s12
	v_lshl_add_u64 v[182:183], s[44:45], 0, v[0:1]
	s_mov_b32 m0, s39
	ds_read_b128 v[174:177], v187 offset:16384
	ds_read_b128 v[178:181], v187 offset:17408
	ds_read_b128 v[188:191], v187 offset:18432
	ds_read_b128 v[206:209], v187 offset:19456
	ds_read_b128 v[210:213], v187 offset:20480
	ds_read_b128 v[214:217], v187 offset:21504
	ds_read_b128 v[218:221], v187 offset:22528
	ds_read_b128 v[222:225], v187 offset:23552
	global_load_lds_dwordx4 v[182:183], off
	s_add_i32 m0, s39, 0x2000
	v_lshl_add_u64 v[192:193], s[44:45], 0, v[154:155]
	s_add_u32 s44, s44, s56
	s_addc_u32 s45, s45, s57
	s_add_i32 s26, s26, s12
	global_load_lds_dwordx4 v[192:193], off
	v_lshl_add_u64 v[202:203], s[44:45], 0, v[0:1]
	s_mov_b32 m0, s26
	v_lshl_add_u64 v[226:227], s[44:45], 0, v[154:155]
	global_load_lds_dwordx4 v[202:203], off
	s_add_i32 m0, s26, 0x2000
	v_lshl_add_u64 v[228:229], s[28:29], 0, v[158:159]
	global_load_lds_dwordx4 v[226:227], off
	s_mov_b32 m0, s13
	v_lshl_add_u64 v[230:231], s[28:29], 0, v[156:157]
	global_load_lds_dwordx4 v[228:229], off
	s_mov_b32 m0, s27
	s_nop 0
	global_load_lds_dwordx4 v[230:231], off
	s_waitcnt vmcnt(8)
	s_waitcnt lgkmcnt(0)
	s_barrier
; #define PG8_STAGE(bufoff, gbase, voff) do { _Pragma("unroll") for (int _i = 0; _i < 2; ++_i) \
;         __builtin_amdgcn_global_load_lds((const unsigned*)((const char*)(gbase) + (voff)[_i]), (LAS unsigned*)(lds + (bufoff) + ldsw + _i * 8192), 16, 0, 0); } while (0)
; #define PG8_LDA(dst, b, h) do { _Pragma("unroll") for (int m = 0; m < 4; ++m) _Pragma("unroll") for (int k = 0; k < 2; ++k) dst[m][k] = *(const LAS bf16x8*)(lds + PG8_SA(b, h) + aoff + m * 2048 + k * 1024); } while (0)
; #define PG8_LDB(dst, b, h) do { _Pragma("unroll") for (int n = 0; n < 2; ++n) _Pragma("unroll") for (int k = 0; k < 2; ++k) dst[n][k] = *(const LAS bf16x8*)(lds + PG8_SB(b, h) + boff + n * 2048 + k * 1024); } while (0)
; #define PG8_MMA(ai, bj, At, Bt) do { __builtin_amdgcn_s_setprio(1); _Pragma("unroll") for (int m = 0; m < 4; ++m) _Pragma("unroll") for (int n = 0; n < 2; ++n) _Pragma("unroll") for (int k = 0; k < 2; ++k) \
;         acc[ai][bj][m][n] = __builtin_amdgcn_mfma_f32_16x16x32_bf16(Bt[n][k], At[m][k], acc[ai][bj][m][n], 0, 0, 0); __builtin_amdgcn_s_setprio(0); } while (0)
; #define PG8_WAIT_V(n) asm volatile("s_waitcnt vmcnt(" #n ")" ::: "memory")
; #define PG8_WAIT_L(n) asm volatile("s_waitcnt lgkmcnt(" #n ")" ::: "memory")
; #define PG8_BAR __builtin_amdgcn_s_barrier()
; #define PG8_SCHED __builtin_amdgcn_sched_barrier(0)
; template <class Epi, class Sched>
; __device__ __forceinline__ void gemm_phase(LAS unsigned char* lds, const Gemm g, const Sched& S, const Epi& E) {
;     ...
;             PG8_WAIT_V(8); PG8_WAIT_L(0); PG8_BAR; PG8_MMA(1, 0, At, B0); PG8_MMA(1, 1, At, B1); PG8_BAR; PG8_SCHED;
;             PG8_LDB(B0, 1, 0); PG8_LDB(B1, 1, 1); PG8_SCHED; PG8_LDA(At, 1, 0); PG8_STAGE(PG8_SA(0, 1), a2 + hstep, voffA);
;             PG8_WAIT_V(8); PG8_WAIT_L(0); PG8_BAR; PG8_MMA(0, 0, At, B0); PG8_MMA(0, 1, At, B1); PG8_BAR; PG8_SCHED;
	s_setprio 1
	s_waitcnt lgkmcnt(0)
	v_mfma_f32_16x16x32_bf16 v[58:61], v[130:133], v[174:177], v[58:61]
	v_mfma_f32_16x16x32_bf16 v[50:53], v[138:141], v[174:177], v[50:53]
	v_mfma_f32_16x16x32_bf16 v[42:45], v[130:133], v[188:191], v[42:45]
	v_mfma_f32_16x16x32_bf16 v[34:37], v[138:141], v[188:191], v[34:37]
	v_mfma_f32_16x16x32_bf16 v[26:29], v[130:133], v[210:213], v[26:29]
	v_mfma_f32_16x16x32_bf16 v[18:21], v[138:141], v[210:213], v[18:21]
	v_mfma_f32_16x16x32_bf16 v[10:13], v[130:133], v[218:221], v[10:13]
	v_mfma_f32_16x16x32_bf16 v[2:5], v[138:141], v[218:221], v[2:5]
	v_mfma_f32_16x16x32_bf16 v[58:61], v[134:137], v[178:181], v[58:61]
	v_mfma_f32_16x16x32_bf16 v[50:53], v[142:145], v[178:181], v[50:53]
	v_mfma_f32_16x16x32_bf16 v[42:45], v[134:137], v[206:209], v[42:45]
	v_mfma_f32_16x16x32_bf16 v[34:37], v[142:145], v[206:209], v[34:37]
	v_mfma_f32_16x16x32_bf16 v[26:29], v[134:137], v[214:217], v[26:29]
	v_mfma_f32_16x16x32_bf16 v[18:21], v[142:145], v[214:217], v[18:21]
	v_mfma_f32_16x16x32_bf16 v[10:13], v[134:137], v[222:225], v[10:13]
	v_mfma_f32_16x16x32_bf16 v[2:5], v[142:145], v[222:225], v[2:5]
	s_setprio 0
	s_setprio 1
	v_mfma_f32_16x16x32_bf16 v[62:65], v[146:149], v[174:177], v[62:65]
	v_mfma_f32_16x16x32_bf16 v[54:57], v[166:169], v[174:177], v[54:57]
	v_mfma_f32_16x16x32_bf16 v[46:49], v[146:149], v[188:191], v[46:49]
	v_mfma_f32_16x16x32_bf16 v[38:41], v[166:169], v[188:191], v[38:41]
	v_mfma_f32_16x16x32_bf16 v[30:33], v[146:149], v[210:213], v[30:33]
	v_mfma_f32_16x16x32_bf16 v[22:25], v[166:169], v[210:213], v[22:25]
	v_mfma_f32_16x16x32_bf16 v[14:17], v[146:149], v[218:221], v[14:17]
	v_mfma_f32_16x16x32_bf16 v[6:9], v[166:169], v[218:221], v[6:9]
	v_mfma_f32_16x16x32_bf16 v[62:65], v[150:153], v[178:181], v[62:65]
	v_mfma_f32_16x16x32_bf16 v[54:57], v[170:173], v[178:181], v[54:57]
	v_mfma_f32_16x16x32_bf16 v[46:49], v[150:153], v[206:209], v[46:49]
	v_mfma_f32_16x16x32_bf16 v[38:41], v[170:173], v[206:209], v[38:41]
	v_mfma_f32_16x16x32_bf16 v[30:33], v[150:153], v[214:217], v[30:33]
	v_mfma_f32_16x16x32_bf16 v[22:25], v[170:173], v[214:217], v[22:25]
	v_mfma_f32_16x16x32_bf16 v[14:17], v[150:153], v[222:225], v[14:17]
	v_mfma_f32_16x16x32_bf16 v[6:9], v[170:173], v[222:225], v[6:9]
	s_setprio 0
	s_barrier
	ds_read_b128 v[130:133], v239
	ds_read_b128 v[134:137], v239 offset:1024
	ds_read_b128 v[138:141], v239 offset:2048
	ds_read_b128 v[142:145], v239 offset:3072
	ds_read_b128 v[146:149], v250
	ds_read_b128 v[150:153], v250 offset:1024
	ds_read_b128 v[166:169], v250 offset:2048
	ds_read_b128 v[170:173], v250 offset:3072
	s_add_i32 s26, 0, 0x18000
	s_add_i32 s39, 0, 0x1c000
	s_add_u32 s28, s28, s56
	s_addc_u32 s29, s29, s57
	s_mov_b32 m0, s30
	v_lshl_add_u64 v[232:233], s[28:29], 0, v[158:159]
	ds_read_b128 v[174:177], v187 offset:32768
	ds_read_b128 v[178:181], v187 offset:33792
	ds_read_b128 v[188:191], v187 offset:34816
	ds_read_b128 v[206:209], v187 offset:35840
	ds_read_b128 v[210:213], v187 offset:36864
	ds_read_b128 v[214:217], v187 offset:37888
	ds_read_b128 v[218:221], v187 offset:38912
	ds_read_b128 v[222:225], v187 offset:39936
	global_load_lds_dwordx4 v[232:233], off
	s_mov_b32 m0, s31
	v_lshl_add_u64 v[232:233], s[28:29], 0, v[156:157]
	global_load_lds_dwordx4 v[232:233], off
	s_waitcnt vmcnt(8)
	s_waitcnt lgkmcnt(0)
	s_barrier
	s_setprio 1
	s_waitcnt lgkmcnt(0)
	v_mfma_f32_16x16x32_bf16 v[122:125], v[130:133], v[174:177], v[122:125]
	v_mfma_f32_16x16x32_bf16 v[114:117], v[138:141], v[174:177], v[114:117]
	v_mfma_f32_16x16x32_bf16 v[106:109], v[130:133], v[188:191], v[106:109]
	v_mfma_f32_16x16x32_bf16 v[98:101], v[138:141], v[188:191], v[98:101]
	v_mfma_f32_16x16x32_bf16 v[90:93], v[130:133], v[210:213], v[90:93]
	v_mfma_f32_16x16x32_bf16 v[82:85], v[138:141], v[210:213], v[82:85]
	v_mfma_f32_16x16x32_bf16 v[74:77], v[130:133], v[218:221], v[74:77]
	v_mfma_f32_16x16x32_bf16 v[66:69], v[138:141], v[218:221], v[66:69]
	v_mfma_f32_16x16x32_bf16 v[122:125], v[134:137], v[178:181], v[122:125]
	v_mfma_f32_16x16x32_bf16 v[114:117], v[142:145], v[178:181], v[114:117]
	v_mfma_f32_16x16x32_bf16 v[106:109], v[134:137], v[206:209], v[106:109]
	v_mfma_f32_16x16x32_bf16 v[98:101], v[142:145], v[206:209], v[98:101]
	v_mfma_f32_16x16x32_bf16 v[90:93], v[134:137], v[214:217], v[90:93]
	v_mfma_f32_16x16x32_bf16 v[82:85], v[142:145], v[214:217], v[82:85]
	v_mfma_f32_16x16x32_bf16 v[74:77], v[134:137], v[222:225], v[74:77]
	v_mfma_f32_16x16x32_bf16 v[66:69], v[142:145], v[222:225], v[66:69]
	s_setprio 0
	s_setprio 1
	v_mfma_f32_16x16x32_bf16 v[126:129], v[146:149], v[174:177], v[126:129]
	v_mfma_f32_16x16x32_bf16 v[118:121], v[166:169], v[174:177], v[118:121]
	v_mfma_f32_16x16x32_bf16 v[110:113], v[146:149], v[188:191], v[110:113]
	v_mfma_f32_16x16x32_bf16 v[102:105], v[166:169], v[188:191], v[102:105]
	v_mfma_f32_16x16x32_bf16 v[94:97], v[146:149], v[210:213], v[94:97]
	v_mfma_f32_16x16x32_bf16 v[86:89], v[166:169], v[210:213], v[86:89]
	v_mfma_f32_16x16x32_bf16 v[78:81], v[146:149], v[218:221], v[78:81]
	v_mfma_f32_16x16x32_bf16 v[70:73], v[166:169], v[218:221], v[70:73]
	v_mfma_f32_16x16x32_bf16 v[126:129], v[150:153], v[178:181], v[126:129]
	v_mfma_f32_16x16x32_bf16 v[118:121], v[170:173], v[178:181], v[118:121]
	v_mfma_f32_16x16x32_bf16 v[110:113], v[150:153], v[206:209], v[110:113]
	v_mfma_f32_16x16x32_bf16 v[102:105], v[170:173], v[206:209], v[102:105]
	v_mfma_f32_16x16x32_bf16 v[94:97], v[150:153], v[214:217], v[94:97]
	v_mfma_f32_16x16x32_bf16 v[86:89], v[170:173], v[214:217], v[86:89]
	v_mfma_f32_16x16x32_bf16 v[78:81], v[150:153], v[222:225], v[78:81]
	v_mfma_f32_16x16x32_bf16 v[70:73], v[170:173], v[222:225], v[70:73]
	s_setprio 0
	s_barrier
; #define PG8_STAGE(bufoff, gbase, voff) do { _Pragma("unroll") for (int _i = 0; _i < 2; ++_i) \
;         __builtin_amdgcn_global_load_lds((const unsigned*)((const char*)(gbase) + (voff)[_i]), (LAS unsigned*)(lds + (bufoff) + ldsw + _i * 8192), 16, 0, 0); } while (0)
; #define PG8_LDA(dst, b, h) do { _Pragma("unroll") for (int m = 0; m < 4; ++m) _Pragma("unroll") for (int k = 0; k < 2; ++k) dst[m][k] = *(const LAS bf16x8*)(lds + PG8_SA(b, h) + aoff + m * 2048 + k * 1024); } while (0)
; #define PG8_MMA(ai, bj, At, Bt) do { __builtin_amdgcn_s_setprio(1); _Pragma("unroll") for (int m = 0; m < 4; ++m) _Pragma("unroll") for (int n = 0; n < 2; ++n) _Pragma("unroll") for (int k = 0; k < 2; ++k) \
;         acc[ai][bj][m][n] = __builtin_amdgcn_mfma_f32_16x16x32_bf16(Bt[n][k], At[m][k], acc[ai][bj][m][n], 0, 0, 0); __builtin_amdgcn_s_setprio(0); } while (0)
; #define PG8_WAIT_V(n) asm volatile("s_waitcnt vmcnt(" #n ")" ::: "memory")
; #define PG8_WAIT_L(n) asm volatile("s_waitcnt lgkmcnt(" #n ")" ::: "memory")
; #define PG8_BAR __builtin_amdgcn_s_barrier()
; #define PG8_SCHED __builtin_amdgcn_sched_barrier(0)
; template <class Epi, class Sched>
; __device__ __forceinline__ void gemm_phase(LAS unsigned char* lds, const Gemm g, const Sched& S, const Epi& E) {
;     ...
;             PG8_LDA(At, 1, 1); PG8_STAGE(PG8_SB(1, 0), b3, voffB); PG8_STAGE(PG8_SB(1, 1), b3 + hstep, voffB); PG8_STAGE(PG8_SA(1, 0), a3, voffA);
;             PG8_WAIT_V(8); PG8_WAIT_L(0); PG8_BAR; PG8_MMA(1, 0, At, B0); PG8_MMA(1, 1, At, B1); PG8_BAR; PG8_SCHED;
;         }
	s_add_i32 s26, s26, s12
	v_lshl_add_u64 v[182:183], v[182:183], 0, s[18:19]
	s_mov_b32 m0, s26
	ds_read_b128 v[174:177], v187 offset:49152
	ds_read_b128 v[178:181], v187 offset:50176
	ds_read_b128 v[188:191], v187 offset:51200
	ds_read_b128 v[206:209], v187 offset:52224
	ds_read_b128 v[210:213], v187 offset:53248
	ds_read_b128 v[214:217], v187 offset:54272
	ds_read_b128 v[218:221], v187 offset:55296
	ds_read_b128 v[222:225], v187 offset:56320
	global_load_lds_dwordx4 v[182:183], off
	v_lshl_add_u64 v[182:183], v[192:193], 0, s[18:19]
	s_add_i32 m0, s26, 0x2000
	s_add_i32 s26, s39, s12
	global_load_lds_dwordx4 v[182:183], off
	s_mov_b32 m0, s26
	v_lshl_add_u64 v[182:183], v[202:203], 0, s[18:19]
	global_load_lds_dwordx4 v[182:183], off
	s_add_i32 m0, s26, 0x2000
	v_lshl_add_u64 v[182:183], v[226:227], 0, s[18:19]
	global_load_lds_dwordx4 v[182:183], off
	s_mov_b32 m0, s34
	v_lshl_add_u64 v[182:183], v[228:229], 0, s[18:19]
	global_load_lds_dwordx4 v[182:183], off
	s_mov_b32 m0, s35
	v_lshl_add_u64 v[182:183], v[230:231], 0, s[18:19]
	global_load_lds_dwordx4 v[182:183], off
	s_waitcnt vmcnt(8)
	s_waitcnt lgkmcnt(0)
	s_barrier
	s_setprio 1
	s_waitcnt lgkmcnt(0)
	v_mfma_f32_16x16x32_bf16 v[58:61], v[130:133], v[174:177], v[58:61]
	v_mfma_f32_16x16x32_bf16 v[50:53], v[138:141], v[174:177], v[50:53]
	v_mfma_f32_16x16x32_bf16 v[42:45], v[130:133], v[188:191], v[42:45]
	v_mfma_f32_16x16x32_bf16 v[34:37], v[138:141], v[188:191], v[34:37]
	v_mfma_f32_16x16x32_bf16 v[26:29], v[130:133], v[210:213], v[26:29]
	v_mfma_f32_16x16x32_bf16 v[18:21], v[138:141], v[210:213], v[18:21]
	v_mfma_f32_16x16x32_bf16 v[10:13], v[130:133], v[218:221], v[10:13]
	v_mfma_f32_16x16x32_bf16 v[2:5], v[138:141], v[218:221], v[2:5]
	v_mfma_f32_16x16x32_bf16 v[58:61], v[134:137], v[178:181], v[58:61]
	v_mfma_f32_16x16x32_bf16 v[50:53], v[142:145], v[178:181], v[50:53]
	v_mfma_f32_16x16x32_bf16 v[42:45], v[134:137], v[206:209], v[42:45]
	v_mfma_f32_16x16x32_bf16 v[34:37], v[142:145], v[206:209], v[34:37]
	v_mfma_f32_16x16x32_bf16 v[26:29], v[134:137], v[214:217], v[26:29]
	v_mfma_f32_16x16x32_bf16 v[18:21], v[142:145], v[214:217], v[18:21]
	v_mfma_f32_16x16x32_bf16 v[10:13], v[134:137], v[222:225], v[10:13]
	v_mfma_f32_16x16x32_bf16 v[2:5], v[142:145], v[222:225], v[2:5]
	s_setprio 0
	s_setprio 1
	v_mfma_f32_16x16x32_bf16 v[62:65], v[146:149], v[174:177], v[62:65]
	v_mfma_f32_16x16x32_bf16 v[54:57], v[166:169], v[174:177], v[54:57]
	v_mfma_f32_16x16x32_bf16 v[46:49], v[146:149], v[188:191], v[46:49]
	v_mfma_f32_16x16x32_bf16 v[38:41], v[166:169], v[188:191], v[38:41]
	v_mfma_f32_16x16x32_bf16 v[30:33], v[146:149], v[210:213], v[30:33]
	v_mfma_f32_16x16x32_bf16 v[22:25], v[166:169], v[210:213], v[22:25]
	v_mfma_f32_16x16x32_bf16 v[14:17], v[146:149], v[218:221], v[14:17]
	v_mfma_f32_16x16x32_bf16 v[6:9], v[166:169], v[218:221], v[6:9]
	v_mfma_f32_16x16x32_bf16 v[62:65], v[150:153], v[178:181], v[62:65]
	v_mfma_f32_16x16x32_bf16 v[54:57], v[170:173], v[178:181], v[54:57]
	v_mfma_f32_16x16x32_bf16 v[46:49], v[150:153], v[206:209], v[46:49]
	v_mfma_f32_16x16x32_bf16 v[38:41], v[170:173], v[206:209], v[38:41]
	v_mfma_f32_16x16x32_bf16 v[30:33], v[150:153], v[214:217], v[30:33]
	v_mfma_f32_16x16x32_bf16 v[22:25], v[170:173], v[214:217], v[22:25]
	v_mfma_f32_16x16x32_bf16 v[14:17], v[150:153], v[222:225], v[14:17]
	v_mfma_f32_16x16x32_bf16 v[6:9], v[170:173], v[222:225], v[6:9]
	s_setprio 0
	s_barrier
	s_add_u32 s15, s15, 0x100
	s_addc_u32 s16, s16, 0
	s_add_u32 s0, s0, 0x100
	s_addc_u32 s1, s1, 0
	s_cmp_ge_i32 s38, s80
	s_mov_b32 s28, s38
	s_cbranch_scc0 .LBB0_1908

; #define PG8_STAGE(bufoff, gbase, voff) do { _Pragma("unroll") for (int _i = 0; _i < 2; ++_i) \
;         __builtin_amdgcn_global_load_lds((const unsigned*)((const char*)(gbase) + (voff)[_i]), (LAS unsigned*)(lds + (bufoff) + ldsw + _i * 8192), 16, 0, 0); } while (0)
; #define PG8_LDA(dst, b, h) do { _Pragma("unroll") for (int m = 0; m < 4; ++m) _Pragma("unroll") for (int k = 0; k < 2; ++k) dst[m][k] = *(const LAS bf16x8*)(lds + PG8_SA(b, h) + aoff + m * 2048 + k * 1024); } while (0)
; #define PG8_LDB(dst, b, h) do { _Pragma("unroll") for (int n = 0; n < 2; ++n) _Pragma("unroll") for (int k = 0; k < 2; ++k) dst[n][k] = *(const LAS bf16x8*)(lds + PG8_SB(b, h) + boff + n * 2048 + k * 1024); } while (0)
; #define PG8_MMA(ai, bj, At, Bt) do { __builtin_amdgcn_s_setprio(1); _Pragma("unroll") for (int m = 0; m < 4; ++m) _Pragma("unroll") for (int n = 0; n < 2; ++n) _Pragma("unroll") for (int k = 0; k < 2; ++k) \
;         acc[ai][bj][m][n] = __builtin_amdgcn_mfma_f32_16x16x32_bf16(Bt[n][k], At[m][k], acc[ai][bj][m][n], 0, 0, 0); __builtin_amdgcn_s_setprio(0); } while (0)
; #define PG8_WAIT_V(n) asm volatile("s_waitcnt vmcnt(" #n ")" ::: "memory")
; #define PG8_WAIT_L(n) asm volatile("s_waitcnt lgkmcnt(" #n ")" ::: "memory")
; #define PG8_BAR __builtin_amdgcn_s_barrier()
; template <class Epi, class Sched>
; __device__ __forceinline__ void gemm_phase(LAS unsigned char* lds, const Gemm g, const Sched& S, const Epi& E) {
;     ...
;         for (int t = 0; t < nt; t += 2) {
;             const bool last = (t == nt - 2);
;             const char* a1 = cA + (size_t)(t + 1) * kstep;
;             const char* a2 = last ? nA : cA + (size_t)(t + 2) * kstep; const char* b2 = last ? nB : cB + (size_t)(t + 2) * kstep;
;             const char* a3 = a2 + kstep; const char* b3 = b2 + kstep;
;             PG8_LDB(B0, 0, 0); PG8_LDB(B1, 0, 1); PG8_SCHED; PG8_LDA(At, 0, 0); PG8_STAGE(PG8_SA(1, 1), a1 + hstep, voffA);
;             PG8_WAIT_V(8); PG8_WAIT_L(0); PG8_BAR; PG8_MMA(0, 0, At, B0); PG8_MMA(0, 1, At, B1); PG8_BAR; PG8_SCHED;
;     ...
; #pragma unroll
;         for (int a = 0; a < 2; ++a)
; #pragma unroll
;             for (int b = 0; b < 2; ++b)
; #pragma unroll
;                 for (int m = 0; m < 4; ++m)
; #pragma unroll
;                     for (int n = 0; n < 2; ++n) acc[a][b][m][n] = (f32x4){0.f, 0.f, 0.f, 0.f};
;         cur = nxt; cA = nA; cB = nB; ++ui;
.Lunit7_k:
	s_add_u32 s15, s0, 0x100
	s_addc_u32 s16, s1, 0
	s_add_u32 s0, s64, 0x80
	v_mov_b64_e32 v[2:3], 0
	v_mov_b64_e32 v[4:5], 0
	v_mov_b64_e32 v[6:7], 0
	v_mov_b64_e32 v[8:9], 0
	v_mov_b64_e32 v[10:11], 0
	v_mov_b64_e32 v[12:13], 0
	v_mov_b64_e32 v[14:15], 0
	v_mov_b64_e32 v[16:17], 0
	v_mov_b64_e32 v[18:19], 0
	v_mov_b64_e32 v[20:21], 0
	v_mov_b64_e32 v[22:23], 0
	v_mov_b64_e32 v[24:25], 0
	v_mov_b64_e32 v[26:27], 0
	v_mov_b64_e32 v[28:29], 0
	v_mov_b64_e32 v[30:31], 0
	v_mov_b64_e32 v[32:33], 0
	v_mov_b64_e32 v[34:35], 0
	v_mov_b64_e32 v[36:37], 0
	v_mov_b64_e32 v[38:39], 0
	v_mov_b64_e32 v[40:41], 0
	v_mov_b64_e32 v[42:43], 0
	v_mov_b64_e32 v[44:45], 0
	v_mov_b64_e32 v[46:47], 0
	v_mov_b64_e32 v[48:49], 0
	v_mov_b64_e32 v[50:51], 0
	v_mov_b64_e32 v[52:53], 0
	v_mov_b64_e32 v[54:55], 0
	v_mov_b64_e32 v[56:57], 0
	v_mov_b64_e32 v[58:59], 0
	v_mov_b64_e32 v[60:61], 0
	v_mov_b64_e32 v[62:63], 0
	v_mov_b64_e32 v[64:65], 0
	v_mov_b64_e32 v[66:67], 0
	v_mov_b64_e32 v[68:69], 0
	v_mov_b64_e32 v[70:71], 0
	v_mov_b64_e32 v[72:73], 0
	v_mov_b64_e32 v[74:75], 0
	v_mov_b64_e32 v[76:77], 0
	v_mov_b64_e32 v[78:79], 0
	v_mov_b64_e32 v[80:81], 0
	v_mov_b64_e32 v[82:83], 0
	v_mov_b64_e32 v[84:85], 0
	v_mov_b64_e32 v[86:87], 0
	v_mov_b64_e32 v[88:89], 0
	v_mov_b64_e32 v[90:91], 0
	v_mov_b64_e32 v[92:93], 0
	v_mov_b64_e32 v[94:95], 0
	v_mov_b64_e32 v[96:97], 0
	v_mov_b64_e32 v[98:99], 0
	v_mov_b64_e32 v[100:101], 0
	v_mov_b64_e32 v[102:103], 0
	v_mov_b64_e32 v[104:105], 0
	v_mov_b64_e32 v[106:107], 0
	v_mov_b64_e32 v[108:109], 0
	v_mov_b64_e32 v[110:111], 0
	v_mov_b64_e32 v[112:113], 0
	v_mov_b64_e32 v[114:115], 0
	v_mov_b64_e32 v[116:117], 0
	v_mov_b64_e32 v[118:119], 0
	v_mov_b64_e32 v[120:121], 0
	v_mov_b64_e32 v[122:123], 0
	v_mov_b64_e32 v[124:125], 0
	v_mov_b64_e32 v[126:127], 0
	v_mov_b64_e32 v[128:129], 0
	s_addc_u32 s1, s65, 0
	s_mov_b32 s28, 0
	v_add_u32_e32 v235, 0x10000, v217
	v_add_u32_e32 v238, 0x14000, v217
	v_add_u32_e32 v239, 0x18000, v217
	v_add_u32_e32 v250, 0x1c000, v217
.LBB0_2026:
	ds_read_b128 v[140:143], v235
	ds_read_b128 v[144:147], v235 offset:1024
	ds_read_b128 v[148:151], v235 offset:2048
	ds_read_b128 v[152:155], v235 offset:3072
	ds_read_b128 v[156:159], v238
	ds_read_b128 v[160:163], v238 offset:1024
	ds_read_b128 v[164:167], v238 offset:2048
	ds_read_b128 v[168:171], v238 offset:3072
	ds_read_b128 v[172:175], v219
	ds_read_b128 v[176:179], v219 offset:1024
	ds_read_b128 v[180:183], v219 offset:2048
	ds_read_b128 v[184:187], v219 offset:3072
	ds_read_b128 v[188:191], v219 offset:4096
	ds_read_b128 v[206:209], v219 offset:5120
	ds_read_b128 v[210:213], v219 offset:6144
	ds_read_b128 v[220:223], v219 offset:7168
	s_add_i32 s64, s28, 2
	s_add_u32 s26, s0, 0x80
	s_addc_u32 s29, s1, 0
	s_add_i32 s65, 0, 0x10000
	s_cmp_eq_u32 s84, s28
	s_cselect_b32 s29, s45, s29
	s_cselect_b32 s28, s44, s26
	s_cselect_b32 s91, s63, s16
	s_cselect_b32 s90, s62, s15
	s_add_i32 s26, 0, 0x14000
	s_add_i32 m0, s13, 0xc000
	v_lshl_add_u64 v[192:193], s[0:1], 0, v[138:139]
	global_load_lds_dwordx4 v[192:193], off
	s_add_i32 m0, s13, 0xe000
	v_lshl_add_u64 v[192:193], s[0:1], 0, v[136:137]
	global_load_lds_dwordx4 v[192:193], off
	s_waitcnt vmcnt(8)
	s_waitcnt lgkmcnt(0)
	s_barrier
	s_setprio 1
	s_waitcnt lgkmcnt(0)
	v_mfma_f32_16x16x32_bf16 v[126:129], v[140:143], v[172:175], v[126:129]
	v_mfma_f32_16x16x32_bf16 v[122:125], v[148:151], v[172:175], v[122:125]
	v_mfma_f32_16x16x32_bf16 v[118:121], v[140:143], v[180:183], v[118:121]
	v_mfma_f32_16x16x32_bf16 v[114:117], v[148:151], v[180:183], v[114:117]
	v_mfma_f32_16x16x32_bf16 v[106:109], v[140:143], v[188:191], v[106:109]
	v_mfma_f32_16x16x32_bf16 v[98:101], v[148:151], v[188:191], v[98:101]
	v_mfma_f32_16x16x32_bf16 v[90:93], v[140:143], v[210:213], v[90:93]
	v_mfma_f32_16x16x32_bf16 v[82:85], v[148:151], v[210:213], v[82:85]
	v_mfma_f32_16x16x32_bf16 v[126:129], v[144:147], v[176:179], v[126:129]
	v_mfma_f32_16x16x32_bf16 v[122:125], v[152:155], v[176:179], v[122:125]
	v_mfma_f32_16x16x32_bf16 v[118:121], v[144:147], v[184:187], v[118:121]
	v_mfma_f32_16x16x32_bf16 v[114:117], v[152:155], v[184:187], v[114:117]
	v_mfma_f32_16x16x32_bf16 v[106:109], v[144:147], v[206:209], v[106:109]
	v_mfma_f32_16x16x32_bf16 v[98:101], v[152:155], v[206:209], v[98:101]
	v_mfma_f32_16x16x32_bf16 v[90:93], v[144:147], v[220:223], v[90:93]
	v_mfma_f32_16x16x32_bf16 v[82:85], v[152:155], v[220:223], v[82:85]
	s_setprio 0
	s_setprio 1
	v_mfma_f32_16x16x32_bf16 v[110:113], v[156:159], v[172:175], v[110:113]
	v_mfma_f32_16x16x32_bf16 v[102:105], v[164:167], v[172:175], v[102:105]
	v_mfma_f32_16x16x32_bf16 v[94:97], v[156:159], v[180:183], v[94:97]
	v_mfma_f32_16x16x32_bf16 v[86:89], v[164:167], v[180:183], v[86:89]
	v_mfma_f32_16x16x32_bf16 v[78:81], v[156:159], v[188:191], v[78:81]
	v_mfma_f32_16x16x32_bf16 v[74:77], v[164:167], v[188:191], v[74:77]
	v_mfma_f32_16x16x32_bf16 v[70:73], v[156:159], v[210:213], v[70:73]
	v_mfma_f32_16x16x32_bf16 v[66:69], v[164:167], v[210:213], v[66:69]
	v_mfma_f32_16x16x32_bf16 v[110:113], v[160:163], v[176:179], v[110:113]
	v_mfma_f32_16x16x32_bf16 v[102:105], v[168:171], v[176:179], v[102:105]
	v_mfma_f32_16x16x32_bf16 v[94:97], v[160:163], v[184:187], v[94:97]
	v_mfma_f32_16x16x32_bf16 v[86:89], v[168:171], v[184:187], v[86:89]
	v_mfma_f32_16x16x32_bf16 v[78:81], v[160:163], v[206:209], v[78:81]
	v_mfma_f32_16x16x32_bf16 v[74:77], v[168:171], v[206:209], v[74:77]
	v_mfma_f32_16x16x32_bf16 v[70:73], v[160:163], v[220:223], v[70:73]
	v_mfma_f32_16x16x32_bf16 v[66:69], v[168:171], v[220:223], v[66:69]
	s_setprio 0
	s_barrier
; #define PG8_STAGE(bufoff, gbase, voff) do { _Pragma("unroll") for (int _i = 0; _i < 2; ++_i) \
;         __builtin_amdgcn_global_load_lds((const unsigned*)((const char*)(gbase) + (voff)[_i]), (LAS unsigned*)(lds + (bufoff) + ldsw + _i * 8192), 16, 0, 0); } while (0)
; #define PG8_LDA(dst, b, h) do { _Pragma("unroll") for (int m = 0; m < 4; ++m) _Pragma("unroll") for (int k = 0; k < 2; ++k) dst[m][k] = *(const LAS bf16x8*)(lds + PG8_SA(b, h) + aoff + m * 2048 + k * 1024); } while (0)
; #define PG8_LDB(dst, b, h) do { _Pragma("unroll") for (int n = 0; n < 2; ++n) _Pragma("unroll") for (int k = 0; k < 2; ++k) dst[n][k] = *(const LAS bf16x8*)(lds + PG8_SB(b, h) + boff + n * 2048 + k * 1024); } while (0)
; #define PG8_MMA(ai, bj, At, Bt) do { __builtin_amdgcn_s_setprio(1); _Pragma("unroll") for (int m = 0; m < 4; ++m) _Pragma("unroll") for (int n = 0; n < 2; ++n) _Pragma("unroll") for (int k = 0; k < 2; ++k) \
;         acc[ai][bj][m][n] = __builtin_amdgcn_mfma_f32_16x16x32_bf16(Bt[n][k], At[m][k], acc[ai][bj][m][n], 0, 0, 0); __builtin_amdgcn_s_setprio(0); } while (0)
; #define PG8_WAIT_V(n) asm volatile("s_waitcnt vmcnt(" #n ")" ::: "memory")
; #define PG8_WAIT_L(n) asm volatile("s_waitcnt lgkmcnt(" #n ")" ::: "memory")
; #define PG8_BAR __builtin_amdgcn_s_barrier()
; #define PG8_SCHED __builtin_amdgcn_sched_barrier(0)
; template <class Epi, class Sched>
; __device__ __forceinline__ void gemm_phase(LAS unsigned char* lds, const Gemm g, const Sched& S, const Epi& E) {
;     ...
;             PG8_LDA(At, 0, 1); PG8_STAGE(PG8_SB(0, 0), b2, voffB); PG8_STAGE(PG8_SB(0, 1), b2 + hstep, voffB); PG8_STAGE(PG8_SA(0, 0), a2, voffA);
;             PG8_WAIT_V(8); PG8_WAIT_L(0); PG8_BAR; PG8_MMA(1, 0, At, B0); PG8_MMA(1, 1, At, B1); PG8_BAR; PG8_SCHED;
;             PG8_LDB(B0, 1, 0); PG8_LDB(B1, 1, 1); PG8_SCHED; PG8_LDA(At, 1, 0); PG8_STAGE(PG8_SA(0, 1), a2 + hstep, voffA);
;             PG8_WAIT_V(8); PG8_WAIT_L(0); PG8_BAR; PG8_MMA(0, 0, At, B0); PG8_MMA(0, 1, At, B1); PG8_BAR; PG8_SCHED;
	s_add_i32 s65, s65, s12
	v_lshl_add_u64 v[192:193], s[90:91], 0, v[0:1]
	s_mov_b32 m0, s65
	ds_read_b128 v[172:175], v219 offset:16384
	ds_read_b128 v[176:179], v219 offset:17408
	ds_read_b128 v[180:183], v219 offset:18432
	ds_read_b128 v[184:187], v219 offset:19456
	ds_read_b128 v[188:191], v219 offset:20480
	ds_read_b128 v[206:209], v219 offset:21504
	ds_read_b128 v[210:213], v219 offset:22528
	ds_read_b128 v[220:223], v219 offset:23552
	global_load_lds_dwordx4 v[192:193], off
	s_add_i32 m0, s65, 0x2000
	v_lshl_add_u64 v[202:203], s[90:91], 0, v[130:131]
	s_add_u32 s90, s90, s48
	s_addc_u32 s91, s91, s49
	s_add_i32 s26, s26, s12
	global_load_lds_dwordx4 v[202:203], off
	v_lshl_add_u64 v[214:215], s[90:91], 0, v[0:1]
	s_mov_b32 m0, s26
	v_lshl_add_u64 v[224:225], s[90:91], 0, v[130:131]
	global_load_lds_dwordx4 v[214:215], off
	s_add_i32 m0, s26, 0x2000
	v_lshl_add_u64 v[226:227], s[28:29], 0, v[134:135]
	global_load_lds_dwordx4 v[224:225], off
	s_mov_b32 m0, s13
	v_lshl_add_u64 v[228:229], s[28:29], 0, v[132:133]
	global_load_lds_dwordx4 v[226:227], off
	s_mov_b32 m0, s27
	s_nop 0
	global_load_lds_dwordx4 v[228:229], off
	s_waitcnt vmcnt(8)
	s_waitcnt lgkmcnt(0)
	s_barrier
	s_setprio 1
	s_waitcnt lgkmcnt(0)
	v_mfma_f32_16x16x32_bf16 v[62:65], v[140:143], v[172:175], v[62:65]
	v_mfma_f32_16x16x32_bf16 v[58:61], v[148:151], v[172:175], v[58:61]
	v_mfma_f32_16x16x32_bf16 v[54:57], v[140:143], v[180:183], v[54:57]
	v_mfma_f32_16x16x32_bf16 v[50:53], v[148:151], v[180:183], v[50:53]
	v_mfma_f32_16x16x32_bf16 v[42:45], v[140:143], v[188:191], v[42:45]
	v_mfma_f32_16x16x32_bf16 v[34:37], v[148:151], v[188:191], v[34:37]
	v_mfma_f32_16x16x32_bf16 v[26:29], v[140:143], v[210:213], v[26:29]
	v_mfma_f32_16x16x32_bf16 v[18:21], v[148:151], v[210:213], v[18:21]
	v_mfma_f32_16x16x32_bf16 v[62:65], v[144:147], v[176:179], v[62:65]
	v_mfma_f32_16x16x32_bf16 v[58:61], v[152:155], v[176:179], v[58:61]
	v_mfma_f32_16x16x32_bf16 v[54:57], v[144:147], v[184:187], v[54:57]
	v_mfma_f32_16x16x32_bf16 v[50:53], v[152:155], v[184:187], v[50:53]
	v_mfma_f32_16x16x32_bf16 v[42:45], v[144:147], v[206:209], v[42:45]
	v_mfma_f32_16x16x32_bf16 v[34:37], v[152:155], v[206:209], v[34:37]
	v_mfma_f32_16x16x32_bf16 v[26:29], v[144:147], v[220:223], v[26:29]
	v_mfma_f32_16x16x32_bf16 v[18:21], v[152:155], v[220:223], v[18:21]
	s_setprio 0
	s_setprio 1
	v_mfma_f32_16x16x32_bf16 v[46:49], v[156:159], v[172:175], v[46:49]
	v_mfma_f32_16x16x32_bf16 v[38:41], v[164:167], v[172:175], v[38:41]
	v_mfma_f32_16x16x32_bf16 v[30:33], v[156:159], v[180:183], v[30:33]
	v_mfma_f32_16x16x32_bf16 v[22:25], v[164:167], v[180:183], v[22:25]
	v_mfma_f32_16x16x32_bf16 v[14:17], v[156:159], v[188:191], v[14:17]
	v_mfma_f32_16x16x32_bf16 v[10:13], v[164:167], v[188:191], v[10:13]
	v_mfma_f32_16x16x32_bf16 v[6:9], v[156:159], v[210:213], v[6:9]
	v_mfma_f32_16x16x32_bf16 v[2:5], v[164:167], v[210:213], v[2:5]
	v_mfma_f32_16x16x32_bf16 v[46:49], v[160:163], v[176:179], v[46:49]
	v_mfma_f32_16x16x32_bf16 v[38:41], v[168:171], v[176:179], v[38:41]
	v_mfma_f32_16x16x32_bf16 v[30:33], v[160:163], v[184:187], v[30:33]
	v_mfma_f32_16x16x32_bf16 v[22:25], v[168:171], v[184:187], v[22:25]
	v_mfma_f32_16x16x32_bf16 v[14:17], v[160:163], v[206:209], v[14:17]
	v_mfma_f32_16x16x32_bf16 v[10:13], v[168:171], v[206:209], v[10:13]
	v_mfma_f32_16x16x32_bf16 v[6:9], v[160:163], v[220:223], v[6:9]
	v_mfma_f32_16x16x32_bf16 v[2:5], v[168:171], v[220:223], v[2:5]
	s_setprio 0
	s_barrier
	ds_read_b128 v[140:143], v239
	ds_read_b128 v[144:147], v239 offset:1024
	ds_read_b128 v[148:151], v239 offset:2048
	ds_read_b128 v[152:155], v239 offset:3072
	ds_read_b128 v[156:159], v250
	ds_read_b128 v[160:163], v250 offset:1024
	ds_read_b128 v[164:167], v250 offset:2048
	ds_read_b128 v[168:171], v250 offset:3072
	s_add_i32 s26, 0, 0x18000
	s_add_i32 s65, 0, 0x1c000
	s_add_u32 s28, s28, s48
	s_addc_u32 s29, s29, s49
	s_mov_b32 m0, s34
	v_lshl_add_u64 v[230:231], s[28:29], 0, v[134:135]
	ds_read_b128 v[172:175], v219 offset:32768
	ds_read_b128 v[176:179], v219 offset:33792
	ds_read_b128 v[180:183], v219 offset:34816
	ds_read_b128 v[184:187], v219 offset:35840
	ds_read_b128 v[188:191], v219 offset:36864
	ds_read_b128 v[206:209], v219 offset:37888
	ds_read_b128 v[210:213], v219 offset:38912
	ds_read_b128 v[220:223], v219 offset:39936
	global_load_lds_dwordx4 v[230:231], off
	s_mov_b32 m0, s35
	v_lshl_add_u64 v[230:231], s[28:29], 0, v[132:133]
	global_load_lds_dwordx4 v[230:231], off
	s_waitcnt vmcnt(8)
	s_waitcnt lgkmcnt(0)
	s_barrier
; #define PG8_STAGE(bufoff, gbase, voff) do { _Pragma("unroll") for (int _i = 0; _i < 2; ++_i) \
;         __builtin_amdgcn_global_load_lds((const unsigned*)((const char*)(gbase) + (voff)[_i]), (LAS unsigned*)(lds + (bufoff) + ldsw + _i * 8192), 16, 0, 0); } while (0)
; #define PG8_LDA(dst, b, h) do { _Pragma("unroll") for (int m = 0; m < 4; ++m) _Pragma("unroll") for (int k = 0; k < 2; ++k) dst[m][k] = *(const LAS bf16x8*)(lds + PG8_SA(b, h) + aoff + m * 2048 + k * 1024); } while (0)
; #define PG8_MMA(ai, bj, At, Bt) do { __builtin_amdgcn_s_setprio(1); _Pragma("unroll") for (int m = 0; m < 4; ++m) _Pragma("unroll") for (int n = 0; n < 2; ++n) _Pragma("unroll") for (int k = 0; k < 2; ++k) \
;         acc[ai][bj][m][n] = __builtin_amdgcn_mfma_f32_16x16x32_bf16(Bt[n][k], At[m][k], acc[ai][bj][m][n], 0, 0, 0); __builtin_amdgcn_s_setprio(0); } while (0)
; #define PG8_WAIT_V(n) asm volatile("s_waitcnt vmcnt(" #n ")" ::: "memory")
; #define PG8_WAIT_L(n) asm volatile("s_waitcnt lgkmcnt(" #n ")" ::: "memory")
; #define PG8_BAR __builtin_amdgcn_s_barrier()
; #define PG8_SCHED __builtin_amdgcn_sched_barrier(0)
; template <class Epi, class Sched>
; __device__ __forceinline__ void gemm_phase(LAS unsigned char* lds, const Gemm g, const Sched& S, const Epi& E) {
;     ...
;             PG8_WAIT_V(8); PG8_WAIT_L(0); PG8_BAR; PG8_MMA(0, 0, At, B0); PG8_MMA(0, 1, At, B1); PG8_BAR; PG8_SCHED;
;             PG8_LDA(At, 1, 1); PG8_STAGE(PG8_SB(1, 0), b3, voffB); PG8_STAGE(PG8_SB(1, 1), b3 + hstep, voffB); PG8_STAGE(PG8_SA(1, 0), a3, voffA);
;             PG8_WAIT_V(8); PG8_WAIT_L(0); PG8_BAR; PG8_MMA(1, 0, At, B0); PG8_MMA(1, 1, At, B1); PG8_BAR; PG8_SCHED;
;         }
	s_setprio 1
	s_waitcnt lgkmcnt(0)
	v_mfma_f32_16x16x32_bf16 v[126:129], v[140:143], v[172:175], v[126:129]
	v_mfma_f32_16x16x32_bf16 v[122:125], v[148:151], v[172:175], v[122:125]
	v_mfma_f32_16x16x32_bf16 v[118:121], v[140:143], v[180:183], v[118:121]
	v_mfma_f32_16x16x32_bf16 v[114:117], v[148:151], v[180:183], v[114:117]
	v_mfma_f32_16x16x32_bf16 v[106:109], v[140:143], v[188:191], v[106:109]
	v_mfma_f32_16x16x32_bf16 v[98:101], v[148:151], v[188:191], v[98:101]
	v_mfma_f32_16x16x32_bf16 v[90:93], v[140:143], v[210:213], v[90:93]
	v_mfma_f32_16x16x32_bf16 v[82:85], v[148:151], v[210:213], v[82:85]
	v_mfma_f32_16x16x32_bf16 v[126:129], v[144:147], v[176:179], v[126:129]
	v_mfma_f32_16x16x32_bf16 v[122:125], v[152:155], v[176:179], v[122:125]
	v_mfma_f32_16x16x32_bf16 v[118:121], v[144:147], v[184:187], v[118:121]
	v_mfma_f32_16x16x32_bf16 v[114:117], v[152:155], v[184:187], v[114:117]
	v_mfma_f32_16x16x32_bf16 v[106:109], v[144:147], v[206:209], v[106:109]
	v_mfma_f32_16x16x32_bf16 v[98:101], v[152:155], v[206:209], v[98:101]
	v_mfma_f32_16x16x32_bf16 v[90:93], v[144:147], v[220:223], v[90:93]
	v_mfma_f32_16x16x32_bf16 v[82:85], v[152:155], v[220:223], v[82:85]
	s_setprio 0
	s_setprio 1
	v_mfma_f32_16x16x32_bf16 v[110:113], v[156:159], v[172:175], v[110:113]
	v_mfma_f32_16x16x32_bf16 v[102:105], v[164:167], v[172:175], v[102:105]
	v_mfma_f32_16x16x32_bf16 v[94:97], v[156:159], v[180:183], v[94:97]
	v_mfma_f32_16x16x32_bf16 v[86:89], v[164:167], v[180:183], v[86:89]
	v_mfma_f32_16x16x32_bf16 v[78:81], v[156:159], v[188:191], v[78:81]
	v_mfma_f32_16x16x32_bf16 v[74:77], v[164:167], v[188:191], v[74:77]
	v_mfma_f32_16x16x32_bf16 v[70:73], v[156:159], v[210:213], v[70:73]
	v_mfma_f32_16x16x32_bf16 v[66:69], v[164:167], v[210:213], v[66:69]
	v_mfma_f32_16x16x32_bf16 v[110:113], v[160:163], v[176:179], v[110:113]
	v_mfma_f32_16x16x32_bf16 v[102:105], v[168:171], v[176:179], v[102:105]
	v_mfma_f32_16x16x32_bf16 v[94:97], v[160:163], v[184:187], v[94:97]
	v_mfma_f32_16x16x32_bf16 v[86:89], v[168:171], v[184:187], v[86:89]
	v_mfma_f32_16x16x32_bf16 v[78:81], v[160:163], v[206:209], v[78:81]
	v_mfma_f32_16x16x32_bf16 v[74:77], v[168:171], v[206:209], v[74:77]
	v_mfma_f32_16x16x32_bf16 v[70:73], v[160:163], v[220:223], v[70:73]
	v_mfma_f32_16x16x32_bf16 v[66:69], v[168:171], v[220:223], v[66:69]
	s_setprio 0
	s_barrier
	s_add_i32 s26, s26, s12
	v_lshl_add_u64 v[192:193], v[192:193], 0, s[18:19]
	s_mov_b32 m0, s26
	ds_read_b128 v[172:175], v219 offset:49152
	ds_read_b128 v[176:179], v219 offset:50176
	ds_read_b128 v[180:183], v219 offset:51200
	ds_read_b128 v[184:187], v219 offset:52224
	ds_read_b128 v[188:191], v219 offset:53248
	ds_read_b128 v[206:209], v219 offset:54272
	ds_read_b128 v[210:213], v219 offset:55296
	ds_read_b128 v[220:223], v219 offset:56320
	global_load_lds_dwordx4 v[192:193], off
	v_lshl_add_u64 v[192:193], v[202:203], 0, s[18:19]
	s_add_i32 m0, s26, 0x2000
	s_add_i32 s26, s65, s12
	global_load_lds_dwordx4 v[192:193], off
	s_mov_b32 m0, s26
	v_lshl_add_u64 v[192:193], v[214:215], 0, s[18:19]
	global_load_lds_dwordx4 v[192:193], off
	s_add_i32 m0, s26, 0x2000
	v_lshl_add_u64 v[192:193], v[224:225], 0, s[18:19]
	global_load_lds_dwordx4 v[192:193], off
	s_mov_b32 m0, s66
	v_lshl_add_u64 v[192:193], v[226:227], 0, s[18:19]
	global_load_lds_dwordx4 v[192:193], off
	s_mov_b32 m0, s67
	v_lshl_add_u64 v[192:193], v[228:229], 0, s[18:19]
	global_load_lds_dwordx4 v[192:193], off
	s_waitcnt vmcnt(8)
	s_waitcnt lgkmcnt(0)
	s_barrier
	s_setprio 1
	s_waitcnt lgkmcnt(0)
	v_mfma_f32_16x16x32_bf16 v[62:65], v[140:143], v[172:175], v[62:65]
	v_mfma_f32_16x16x32_bf16 v[58:61], v[148:151], v[172:175], v[58:61]
	v_mfma_f32_16x16x32_bf16 v[54:57], v[140:143], v[180:183], v[54:57]
	v_mfma_f32_16x16x32_bf16 v[50:53], v[148:151], v[180:183], v[50:53]
	v_mfma_f32_16x16x32_bf16 v[42:45], v[140:143], v[188:191], v[42:45]
	v_mfma_f32_16x16x32_bf16 v[34:37], v[148:151], v[188:191], v[34:37]
	v_mfma_f32_16x16x32_bf16 v[26:29], v[140:143], v[210:213], v[26:29]
	v_mfma_f32_16x16x32_bf16 v[18:21], v[148:151], v[210:213], v[18:21]
	v_mfma_f32_16x16x32_bf16 v[62:65], v[144:147], v[176:179], v[62:65]
	v_mfma_f32_16x16x32_bf16 v[58:61], v[152:155], v[176:179], v[58:61]
	v_mfma_f32_16x16x32_bf16 v[54:57], v[144:147], v[184:187], v[54:57]
	v_mfma_f32_16x16x32_bf16 v[50:53], v[152:155], v[184:187], v[50:53]
	v_mfma_f32_16x16x32_bf16 v[42:45], v[144:147], v[206:209], v[42:45]
	v_mfma_f32_16x16x32_bf16 v[34:37], v[152:155], v[206:209], v[34:37]
	v_mfma_f32_16x16x32_bf16 v[26:29], v[144:147], v[220:223], v[26:29]
	v_mfma_f32_16x16x32_bf16 v[18:21], v[152:155], v[220:223], v[18:21]
	s_setprio 0
	s_setprio 1
	v_mfma_f32_16x16x32_bf16 v[46:49], v[156:159], v[172:175], v[46:49]
	v_mfma_f32_16x16x32_bf16 v[38:41], v[164:167], v[172:175], v[38:41]
	v_mfma_f32_16x16x32_bf16 v[30:33], v[156:159], v[180:183], v[30:33]
	v_mfma_f32_16x16x32_bf16 v[22:25], v[164:167], v[180:183], v[22:25]
	v_mfma_f32_16x16x32_bf16 v[14:17], v[156:159], v[188:191], v[14:17]
	v_mfma_f32_16x16x32_bf16 v[10:13], v[164:167], v[188:191], v[10:13]
	v_mfma_f32_16x16x32_bf16 v[6:9], v[156:159], v[210:213], v[6:9]
	v_mfma_f32_16x16x32_bf16 v[2:5], v[164:167], v[210:213], v[2:5]
	v_mfma_f32_16x16x32_bf16 v[46:49], v[160:163], v[176:179], v[46:49]
	v_mfma_f32_16x16x32_bf16 v[38:41], v[168:171], v[176:179], v[38:41]
	v_mfma_f32_16x16x32_bf16 v[30:33], v[160:163], v[184:187], v[30:33]
	v_mfma_f32_16x16x32_bf16 v[22:25], v[168:171], v[184:187], v[22:25]
	v_mfma_f32_16x16x32_bf16 v[14:17], v[160:163], v[206:209], v[14:17]
	v_mfma_f32_16x16x32_bf16 v[10:13], v[168:171], v[206:209], v[10:13]
	v_mfma_f32_16x16x32_bf16 v[6:9], v[160:163], v[220:223], v[6:9]
	v_mfma_f32_16x16x32_bf16 v[2:5], v[168:171], v[220:223], v[2:5]
	s_setprio 0
	s_barrier
; #define PG8_MMA(ai, bj, At, Bt) do { __builtin_amdgcn_s_setprio(1); _Pragma("unroll") for (int m = 0; m < 4; ++m) _Pragma("unroll") for (int n = 0; n < 2; ++n) _Pragma("unroll") for (int k = 0; k < 2; ++k) \
;         acc[ai][bj][m][n] = __builtin_amdgcn_mfma_f32_16x16x32_bf16(Bt[n][k], At[m][k], acc[ai][bj][m][n], 0, 0, 0); __builtin_amdgcn_s_setprio(0); } while (0)
; #define PG8_WAIT_V(n) asm volatile("s_waitcnt vmcnt(" #n ")" ::: "memory")
; #define PG8_WAIT_L(n) asm volatile("s_waitcnt lgkmcnt(" #n ")" ::: "memory")
; #define PG8_BAR __builtin_amdgcn_s_barrier()
; #define PG8_SCHED __builtin_amdgcn_sched_barrier(0)
; template <class Epi, class Sched>
; __device__ __forceinline__ void gemm_phase(LAS unsigned char* lds, const Gemm g, const Sched& S, const Epi& E) {
;     ...
;             PG8_WAIT_V(8); PG8_WAIT_L(0); PG8_BAR; PG8_MMA(1, 0, At, B0); PG8_MMA(1, 1, At, B1); PG8_BAR; PG8_SCHED;
;         }
;         if (wr == 0) PG8_BAR;
;         E(acc, cur, wr, wc, fr, fq);
;     __device__ __forceinline__ void operator()(const AccT& acc, const Unit& u, int wr, int wc, int fr, int fq) const {
;     ...
;                     v0 = v0 + acc[ai][bj][m][0] * c; v1 = v1 + acc[ai][bj][m][1] * c;
	s_add_u32 s15, s15, 0x100
	s_addc_u32 s16, s16, 0
	s_add_u32 s0, s0, 0x100
	s_addc_u32 s1, s1, 0
	s_cmp_ge_i32 s64, s31
	s_mov_b32 s28, s64
	s_cbranch_scc0 .LBB0_2026
	v_readlane_b32 s90, v255, 43
	v_pk_mul_f32 v[208:209], v[128:129], 0.5 op_sel_hi:[1,0]
	v_pk_mul_f32 v[210:211], v[126:127], 0.5 op_sel_hi:[1,0]
	v_pk_mul_f32 v[212:213], v[124:125], 0.5 op_sel_hi:[1,0]
	v_pk_mul_f32 v[214:215], v[122:123], 0.5 op_sel_hi:[1,0]
	v_pk_mul_f32 v[192:193], v[112:113], 0.5 op_sel_hi:[1,0]
	v_pk_mul_f32 v[190:191], v[110:111], 0.5 op_sel_hi:[1,0]
	v_pk_mul_f32 v[188:189], v[104:105], 0.5 op_sel_hi:[1,0]
	v_pk_mul_f32 v[186:187], v[102:103], 0.5 op_sel_hi:[1,0]
	v_pk_mul_f32 v[184:185], v[120:121], 0.5 op_sel_hi:[1,0]
	v_pk_mul_f32 v[182:183], v[118:119], 0.5 op_sel_hi:[1,0]
	v_pk_mul_f32 v[180:181], v[116:117], 0.5 op_sel_hi:[1,0]
	v_pk_mul_f32 v[178:179], v[114:115], 0.5 op_sel_hi:[1,0]
	v_pk_mul_f32 v[176:177], v[96:97], 0.5 op_sel_hi:[1,0]
	v_pk_mul_f32 v[174:175], v[94:95], 0.5 op_sel_hi:[1,0]
	v_pk_mul_f32 v[172:173], v[88:89], 0.5 op_sel_hi:[1,0]
	v_pk_mul_f32 v[170:171], v[86:87], 0.5 op_sel_hi:[1,0]
	v_pk_mul_f32 v[168:169], v[108:109], 0.5 op_sel_hi:[1,0]
	v_pk_mul_f32 v[166:167], v[106:107], 0.5 op_sel_hi:[1,0]
	v_pk_mul_f32 v[164:165], v[100:101], 0.5 op_sel_hi:[1,0]
	v_pk_mul_f32 v[162:163], v[98:99], 0.5 op_sel_hi:[1,0]
	v_pk_mul_f32 v[160:161], v[80:81], 0.5 op_sel_hi:[1,0]
	v_pk_mul_f32 v[158:159], v[78:79], 0.5 op_sel_hi:[1,0]
	v_pk_mul_f32 v[156:157], v[76:77], 0.5 op_sel_hi:[1,0]
	v_pk_mul_f32 v[154:155], v[74:75], 0.5 op_sel_hi:[1,0]
	v_pk_mul_f32 v[150:151], v[92:93], 0.5 op_sel_hi:[1,0]
	v_pk_mul_f32 v[148:149], v[90:91], 0.5 op_sel_hi:[1,0]
	v_pk_mul_f32 v[146:147], v[84:85], 0.5 op_sel_hi:[1,0]
	v_pk_mul_f32 v[144:145], v[82:83], 0.5 op_sel_hi:[1,0]
	v_pk_mul_f32 v[142:143], v[72:73], 0.5 op_sel_hi:[1,0]
	v_pk_mul_f32 v[140:141], v[70:71], 0.5 op_sel_hi:[1,0]
	v_pk_mul_f32 v[128:129], v[68:69], 0.5 op_sel_hi:[1,0]
	v_pk_mul_f32 v[126:127], v[66:67], 0.5 op_sel_hi:[1,0]
	v_pk_mul_f32 v[124:125], v[64:65], 0.5 op_sel_hi:[1,0]
	v_pk_mul_f32 v[122:123], v[62:63], 0.5 op_sel_hi:[1,0]
	v_pk_mul_f32 v[120:121], v[60:61], 0.5 op_sel_hi:[1,0]
	v_pk_mul_f32 v[118:119], v[58:59], 0.5 op_sel_hi:[1,0]
	v_pk_mul_f32 v[116:117], v[48:49], 0.5 op_sel_hi:[1,0]
	v_pk_mul_f32 v[114:115], v[46:47], 0.5 op_sel_hi:[1,0]
	v_pk_mul_f32 v[112:113], v[40:41], 0.5 op_sel_hi:[1,0]
	v_pk_mul_f32 v[110:111], v[38:39], 0.5 op_sel_hi:[1,0]
	v_pk_mul_f32 v[108:109], v[56:57], 0.5 op_sel_hi:[1,0]
	v_pk_mul_f32 v[106:107], v[54:55], 0.5 op_sel_hi:[1,0]
	v_pk_mul_f32 v[104:105], v[52:53], 0.5 op_sel_hi:[1,0]
	v_pk_mul_f32 v[102:103], v[50:51], 0.5 op_sel_hi:[1,0]
	v_pk_mul_f32 v[100:101], v[32:33], 0.5 op_sel_hi:[1,0]
	v_pk_mul_f32 v[98:99], v[30:31], 0.5 op_sel_hi:[1,0]
	v_pk_mul_f32 v[96:97], v[24:25], 0.5 op_sel_hi:[1,0]
	v_pk_mul_f32 v[94:95], v[22:23], 0.5 op_sel_hi:[1,0]
	v_pk_mul_f32 v[92:93], v[44:45], 0.5 op_sel_hi:[1,0]
	v_pk_mul_f32 v[90:91], v[42:43], 0.5 op_sel_hi:[1,0]
	v_pk_mul_f32 v[88:89], v[36:37], 0.5 op_sel_hi:[1,0]
	v_pk_mul_f32 v[86:87], v[34:35], 0.5 op_sel_hi:[1,0]
	v_pk_mul_f32 v[84:85], v[16:17], 0.5 op_sel_hi:[1,0]
	v_pk_mul_f32 v[82:83], v[14:15], 0.5 op_sel_hi:[1,0]
	v_pk_mul_f32 v[80:81], v[12:13], 0.5 op_sel_hi:[1,0]
	v_pk_mul_f32 v[78:79], v[10:11], 0.5 op_sel_hi:[1,0]
	v_pk_mul_f32 v[76:77], v[28:29], 0.5 op_sel_hi:[1,0]
	v_pk_mul_f32 v[74:75], v[26:27], 0.5 op_sel_hi:[1,0]
	v_pk_mul_f32 v[72:73], v[20:21], 0.5 op_sel_hi:[1,0]
	v_pk_mul_f32 v[70:71], v[18:19], 0.5 op_sel_hi:[1,0]
	v_pk_mul_f32 v[68:69], v[8:9], 0.5 op_sel_hi:[1,0]
	v_pk_mul_f32 v[66:67], v[6:7], 0.5 op_sel_hi:[1,0]
	v_pk_mul_f32 v[64:65], v[4:5], 0.5 op_sel_hi:[1,0]
	v_pk_mul_f32 v[62:63], v[2:3], 0.5 op_sel_hi:[1,0]
	v_readlane_b32 s91, v255, 44
